# replaced hipcc bit-trick f32-to-bf16 rounding with v_cvt_pk_bf16_f32 in remaining compiler code, counted vmcnt at gu tile starts
# speedup vs baseline: 1.1929x; 1.0038x over previous
.Ltrp_0:
	s_or_b64 exec, exec, s[24:25]
	v_lshlrev_b32_e32 v1, 2, v1
	v_mul_lo_u32 v10, v9, s28
	v_add_u32_e32 v10, v1, v10
	s_waitcnt vmcnt(0)
	ds_write2_b32 v10, v168, v169 offset1:1
	ds_write2_b32 v10, v170, v171 offset0:2 offset1:3
	v_add_u32_e32 v4, 0x1040, v10
	ds_write2_b32 v4, v172, v173 offset1:1
	v_add_u32_e32 v0, 0x1048, v10
	ds_write2_b32 v0, v174, v175 offset1:1
	v_add_u32_e32 v1, 0x2080, v10
	ds_write2_b32 v1, v176, v177 offset1:1
	v_add_u32_e32 v2, 0x2088, v10
	ds_write2_b32 v2, v178, v179 offset1:1
	v_add_u32_e32 v3, 0x30c0, v10
	ds_write2_b32 v3, v180, v181 offset1:1
	v_add_u32_e32 v5, 0x30c8, v10
	ds_write2_b32 v5, v182, v183 offset1:1
	v_lshlrev_b32_e32 v0, 4, v8
	v_ashrrev_i32_e32 v12, 2, v8
	v_and_b32_e32 v22, 48, v0
	v_and_b32_e32 v0, -4, v8
	v_mad_u32_u24 v14, v22, s28, v0
	v_add_u32_e32 v12, s27, v12
	s_waitcnt lgkmcnt(0)
	s_barrier
	ds_read2_b32 v[0:1], v14 offset1:65
	ds_read2_b32 v[2:3], v14 offset0:130 offset1:195
	v_ashrrev_i32_e32 v20, 31, v12
	v_mul_lo_u32 v23, s22, v20
	v_mul_lo_u32 v24, s23, v12
	v_mad_u64_u32 v[20:21], s[22:23], s22, v12, 0
	v_add3_u32 v21, v21, v23, v24
	v_add_u32_e32 v6, 0x400, v14
	v_lshl_add_u64 v[20:21], v[20:21], 1, s[20:21]
	s_lshl_b32 s0, s26, 1
	ds_read2_b32 v[4:5], v6 offset0:4 offset1:69
	ds_read2_b32 v[6:7], v6 offset0:134 offset1:199
	v_lshl_add_u64 v[20:21], v[20:21], 0, s[0:1]
	v_lshlrev_b32_e32 v12, 1, v22
	v_lshl_add_u64 v[20:21], v[20:21], 0, v[12:13]
	s_waitcnt lgkmcnt(2)
	v_cvt_pk_bf16_f32 v2, v2, v2
	v_cvt_pk_bf16_f32 v0, v0, v0
	v_and_b32_sdwa v22, v1, v18 dst_sel:DWORD dst_unused:UNUSED_PAD src0_sel:WORD_1 src1_sel:DWORD
	v_cvt_pk_bf16_f32 v3, v3, v3
	v_cvt_pk_bf16_f32 v1, v1, v1
	v_and_b32_e32 v3, 0xffff0000, v3
	v_add_u32_e32 v10, 0x800, v14
	v_and_b32_e32 v12, 0xffff0000, v1
	v_or_b32_sdwa v1, v3, v2 dst_sel:DWORD dst_unused:UNUSED_PAD src0_sel:DWORD src1_sel:WORD_1
	s_waitcnt lgkmcnt(0)
	ds_read2_b32 v[8:9], v10 offset0:8 offset1:73
	ds_read2_b32 v[10:11], v10 offset0:138 offset1:203
	v_cvt_pk_bf16_f32 v4, v4, v4
	v_cvt_pk_bf16_f32 v2, v6, v6
	v_and_b32_sdwa v6, v5, v18 dst_sel:DWORD dst_unused:UNUSED_PAD src0_sel:WORD_1 src1_sel:DWORD
	v_cvt_pk_bf16_f32 v3, v7, v7
	v_cvt_pk_bf16_f32 v5, v5, v5
	v_and_b32_e32 v3, 0xffff0000, v3
	v_and_b32_e32 v5, 0xffff0000, v5
	v_add_u32_e32 v16, 0xc00, v14
	v_or_b32_sdwa v0, v12, v0 dst_sel:DWORD dst_unused:UNUSED_PAD src0_sel:DWORD src1_sel:WORD_1
	v_or_b32_sdwa v3, v3, v2 dst_sel:DWORD dst_unused:UNUSED_PAD src0_sel:DWORD src1_sel:WORD_1
	v_or_b32_sdwa v2, v5, v4 dst_sel:DWORD dst_unused:UNUSED_PAD src0_sel:DWORD src1_sel:WORD_1
	ds_read2_b32 v[14:15], v16 offset0:12 offset1:77
	ds_read2_b32 v[16:17], v16 offset0:142 offset1:207
	global_store_dwordx4 v[20:21], v[0:3], off
	s_mov_b64 s[20:21], 0
	s_waitcnt lgkmcnt(1)
	v_cvt_pk_bf16_f32 v2, v8, v8
	v_cvt_pk_bf16_f32 v1, v11, v11
	v_cvt_pk_bf16_f32 v3, v9, v9
	v_cvt_pk_bf16_f32 v0, v10, v10
	v_and_b32_e32 v1, 0xffff0000, v1
	v_and_b32_e32 v3, 0xffff0000, v3
	v_or_b32_sdwa v1, v1, v0 dst_sel:DWORD dst_unused:UNUSED_PAD src0_sel:DWORD src1_sel:WORD_1
	v_or_b32_sdwa v0, v3, v2 dst_sel:DWORD dst_unused:UNUSED_PAD src0_sel:DWORD src1_sel:WORD_1
	v_cvt_pk_bf16_f32 v4, v14, v14
	s_waitcnt lgkmcnt(0)
	v_cvt_pk_bf16_f32 v3, v17, v17
	v_cvt_pk_bf16_f32 v5, v15, v15
	v_cvt_pk_bf16_f32 v2, v16, v16
	v_and_b32_e32 v3, 0xffff0000, v3
	v_and_b32_e32 v5, 0xffff0000, v5
	v_or_b32_sdwa v3, v3, v2 dst_sel:DWORD dst_unused:UNUSED_PAD src0_sel:DWORD src1_sel:WORD_1
	v_or_b32_sdwa v2, v5, v4 dst_sel:DWORD dst_unused:UNUSED_PAD src0_sel:DWORD src1_sel:WORD_1
	global_store_dwordx4 v[20:21], v[0:3], off offset:16
	s_barrier
	s_add_u32 s53, s53, 1
	s_cmp_lt_u32 s53, 8
	s_cbranch_scc0 .Lptr_done
	s_add_u32 s34, s34, 1
	s_branch .Lptr_again

.Lggu0_noprio:
	s_and_b32 s4, s10, 7
	s_lshl_b32 s4, s4, 3
	s_bfe_u32 s32, s10, 0x30003
	s_or_b32 s4, s4, s32
	s_mul_i32 s4, s4, 0x50000
	s_add_u32 s2, s16, s4
	s_addc_u32 s3, s17, 0
	s_lshr_b32 s4, s10, 6
	s_mul_i32 s4, s4, 0x40000
	s_add_u32 s6, s18, s4
	s_addc_u32 s7, s19, 0
	s_add_u32 m0, s13, 0x0
	s_nop 0
	global_load_lds_dwordx4 v161, s[2:3]
	s_add_u32 m0, s13, 0x1000
	v_add_u32_e32 v166, 0x10000, v161
	global_load_lds_dwordx4 v166, s[2:3]
	s_add_u32 m0, s13, 0x2000
	v_add_u32_e32 v166, 0x20000, v161
	global_load_lds_dwordx4 v166, s[2:3]
	s_add_u32 m0, s13, 0x3000
	v_add_u32_e32 v166, 0x30000, v161
	global_load_lds_dwordx4 v166, s[2:3]
	s_add_u32 m0, s13, 0x4000
	v_add_u32_e32 v166, 0x40000, v161
	global_load_lds_dwordx4 v166, s[2:3]
	s_add_u32 m0, s13, 0x5000
	s_nop 0
	global_load_lds_dwordx4 v165, s[6:7]
	s_add_u32 m0, s13, 0x6000
	v_add_u32_e32 v166, 0x2000, v165
	global_load_lds_dwordx4 v166, s[6:7]
	s_add_u32 m0, s13, 0x7000
	v_add_u32_e32 v166, 0x10000, v165
	global_load_lds_dwordx4 v166, s[6:7]
	s_add_u32 m0, s13, 0x8000
	v_add_u32_e32 v166, 0x12000, v165
	global_load_lds_dwordx4 v166, s[6:7]
	s_add_u32 s24, s6, 0x20000
	s_addc_u32 s25, s7, 0
	s_add_u32 s2, s2, 0x80
	s_addc_u32 s3, s3, 0
	s_add_u32 s6, s6, 0x80
	s_addc_u32 s7, s7, 0
	s_mov_b32 s48, 0

.Lggu0_pair:
	s_cmp_eq_u32 s12, 8
	s_cselect_b32 s4, s48, 0
	s_cmp_eq_u32 s4, 1
	s_cbranch_scc1 .Lggu0_w10
	s_waitcnt vmcnt(0)
	s_branch .Lggu0_wd
.Lggu0_w10:
	s_waitcnt vmcnt(10)
.Lggu0_wd:
	s_barrier
	ds_read_b128 v[184:187], v116 offset:0
	ds_read_b128 v[204:207], v119 offset:20480
	ds_read_b128 v[208:211], v119 offset:22528
	ds_read_b128 v[212:215], v119 offset:24576
	ds_read_b128 v[216:219], v119 offset:26624
	ds_read_b128 v[188:191], v116 offset:2048
	ds_read_b128 v[192:195], v116 offset:4096
	ds_read_b128 v[196:199], v116 offset:6144
	ds_read_b128 v[200:203], v116 offset:8192
	s_waitcnt lgkmcnt(7)
	v_mfma_f32_16x16x32_bf16 v[0:3], v[204:207], v[184:187], v[0:3]
	s_add_u32 m0, s13, 0x9000
	s_nop 0
	global_load_lds_dwordx4 v165, s[24:25]
	s_waitcnt lgkmcnt(6)
	v_mfma_f32_16x16x32_bf16 v[4:7], v[208:211], v[184:187], v[4:7]
	s_add_u32 m0, s13, 0xa000
	v_add_u32_e32 v166, 0x2000, v165
	global_load_lds_dwordx4 v166, s[24:25]
	s_waitcnt lgkmcnt(5)
	v_mfma_f32_16x16x32_bf16 v[8:11], v[212:215], v[184:187], v[8:11]
	s_add_u32 m0, s13, 0xb000
	v_add_u32_e32 v166, 0x10000, v165
	global_load_lds_dwordx4 v166, s[24:25]
	s_waitcnt lgkmcnt(4)
	v_mfma_f32_16x16x32_bf16 v[12:15], v[216:219], v[184:187], v[12:15]
	s_add_u32 m0, s13, 0xc000
	v_add_u32_e32 v166, 0x12000, v165
	global_load_lds_dwordx4 v166, s[24:25]
	ds_read_b128 v[220:223], v118 offset:0
	ds_read_b128 v[240:243], v160 offset:20480
	ds_read_b128 v[244:247], v160 offset:22528
	ds_read_b128 v[248:251], v160 offset:24576
	ds_read_b128 v[252:255], v160 offset:26624
	s_waitcnt lgkmcnt(8)
	v_mfma_f32_16x16x32_bf16 v[16:19], v[204:207], v[188:191], v[16:19]
	v_mfma_f32_16x16x32_bf16 v[20:23], v[208:211], v[188:191], v[20:23]
	v_mfma_f32_16x16x32_bf16 v[24:27], v[212:215], v[188:191], v[24:27]
	v_mfma_f32_16x16x32_bf16 v[28:31], v[216:219], v[188:191], v[28:31]
	ds_read_b128 v[224:227], v118 offset:2048
	ds_read_b128 v[228:231], v118 offset:4096
	ds_read_b128 v[232:235], v118 offset:6144
	ds_read_b128 v[236:239], v118 offset:8192
	s_waitcnt lgkmcnt(11)
	v_mfma_f32_16x16x32_bf16 v[32:35], v[204:207], v[192:195], v[32:35]
	v_mfma_f32_16x16x32_bf16 v[36:39], v[208:211], v[192:195], v[36:39]
	v_mfma_f32_16x16x32_bf16 v[40:43], v[212:215], v[192:195], v[40:43]
	v_mfma_f32_16x16x32_bf16 v[44:47], v[216:219], v[192:195], v[44:47]
	s_waitcnt lgkmcnt(10)
	v_mfma_f32_16x16x32_bf16 v[48:51], v[204:207], v[196:199], v[48:51]
	v_mfma_f32_16x16x32_bf16 v[52:55], v[208:211], v[196:199], v[52:55]
	v_mfma_f32_16x16x32_bf16 v[56:59], v[212:215], v[196:199], v[56:59]
	v_mfma_f32_16x16x32_bf16 v[60:63], v[216:219], v[196:199], v[60:63]
	s_waitcnt lgkmcnt(9)
	v_mfma_f32_16x16x32_bf16 v[64:67], v[204:207], v[200:203], v[64:67]
	v_mfma_f32_16x16x32_bf16 v[68:71], v[208:211], v[200:203], v[68:71]
	v_mfma_f32_16x16x32_bf16 v[72:75], v[212:215], v[200:203], v[72:75]
	v_mfma_f32_16x16x32_bf16 v[76:79], v[216:219], v[200:203], v[76:79]
	s_waitcnt lgkmcnt(7)
	v_mfma_f32_16x16x32_bf16 v[0:3], v[240:243], v[220:223], v[0:3]
	s_waitcnt lgkmcnt(6)
	v_mfma_f32_16x16x32_bf16 v[4:7], v[244:247], v[220:223], v[4:7]
	s_waitcnt lgkmcnt(5)
	v_mfma_f32_16x16x32_bf16 v[8:11], v[248:251], v[220:223], v[8:11]
	s_waitcnt lgkmcnt(4)
	v_mfma_f32_16x16x32_bf16 v[12:15], v[252:255], v[220:223], v[12:15]
	s_waitcnt lgkmcnt(3)
	v_mfma_f32_16x16x32_bf16 v[16:19], v[240:243], v[224:227], v[16:19]
	v_mfma_f32_16x16x32_bf16 v[20:23], v[244:247], v[224:227], v[20:23]
	v_mfma_f32_16x16x32_bf16 v[24:27], v[248:251], v[224:227], v[24:27]
	v_mfma_f32_16x16x32_bf16 v[28:31], v[252:255], v[224:227], v[28:31]
	s_waitcnt lgkmcnt(2)
	v_mfma_f32_16x16x32_bf16 v[32:35], v[240:243], v[228:231], v[32:35]
	v_mfma_f32_16x16x32_bf16 v[36:39], v[244:247], v[228:231], v[36:39]
	v_mfma_f32_16x16x32_bf16 v[40:43], v[248:251], v[228:231], v[40:43]
	v_mfma_f32_16x16x32_bf16 v[44:47], v[252:255], v[228:231], v[44:47]
	s_waitcnt lgkmcnt(1)
	v_mfma_f32_16x16x32_bf16 v[48:51], v[240:243], v[232:235], v[48:51]
	v_mfma_f32_16x16x32_bf16 v[52:55], v[244:247], v[232:235], v[52:55]
	v_mfma_f32_16x16x32_bf16 v[56:59], v[248:251], v[232:235], v[56:59]
	v_mfma_f32_16x16x32_bf16 v[60:63], v[252:255], v[232:235], v[60:63]
	s_add_u32 s24, s24, 0x80
	s_addc_u32 s25, s25, 0
	s_waitcnt lgkmcnt(0)
	v_mfma_f32_16x16x32_bf16 v[64:67], v[240:243], v[236:239], v[64:67]
	v_mfma_f32_16x16x32_bf16 v[68:71], v[244:247], v[236:239], v[68:71]
	v_mfma_f32_16x16x32_bf16 v[72:75], v[248:251], v[236:239], v[72:75]
	v_mfma_f32_16x16x32_bf16 v[76:79], v[252:255], v[236:239], v[76:79]
	s_waitcnt vmcnt(0)
	s_barrier
	ds_read_b128 v[184:187], v116 offset:0
	ds_read_b128 v[204:207], v119 offset:36864
	ds_read_b128 v[208:211], v119 offset:38912
	ds_read_b128 v[212:215], v119 offset:40960
	ds_read_b128 v[216:219], v119 offset:43008
	ds_read_b128 v[188:191], v116 offset:2048
	ds_read_b128 v[192:195], v116 offset:4096
	ds_read_b128 v[196:199], v116 offset:6144
	ds_read_b128 v[200:203], v116 offset:8192
	s_waitcnt lgkmcnt(7)
	v_mfma_f32_16x16x32_bf16 v[80:83], v[204:207], v[184:187], v[80:83]
	s_add_u32 m0, s13, 0xd100
	s_nop 0
	global_load_lds_dwordx4 v161, s[2:3]
	s_waitcnt lgkmcnt(6)
	v_mfma_f32_16x16x32_bf16 v[84:87], v[208:211], v[184:187], v[84:87]
	s_add_u32 m0, s13, 0xe100
	v_add_u32_e32 v166, 0x10000, v161
	global_load_lds_dwordx4 v166, s[2:3]
	s_waitcnt lgkmcnt(5)
	v_mfma_f32_16x16x32_bf16 v[88:91], v[212:215], v[184:187], v[88:91]
	s_add_u32 m0, s13, 0xf100
	v_add_u32_e32 v166, 0x20000, v161
	global_load_lds_dwordx4 v166, s[2:3]
	s_waitcnt lgkmcnt(4)
	v_mfma_f32_16x16x32_bf16 v[92:95], v[216:219], v[184:187], v[92:95]
	s_add_u32 m0, s13, 0x10100
	v_add_u32_e32 v166, 0x30000, v161
	global_load_lds_dwordx4 v166, s[2:3]
	ds_read_b128 v[220:223], v118 offset:0
	ds_read_b128 v[240:243], v160 offset:36864
	ds_read_b128 v[244:247], v160 offset:38912
	ds_read_b128 v[248:251], v160 offset:40960
	ds_read_b128 v[252:255], v160 offset:43008
	s_waitcnt lgkmcnt(8)
	v_mfma_f32_16x16x32_bf16 v[96:99], v[204:207], v[188:191], v[96:99]
	s_add_u32 m0, s13, 0x11100
	v_add_u32_e32 v166, 0x40000, v161
	global_load_lds_dwordx4 v166, s[2:3]
	v_mfma_f32_16x16x32_bf16 v[100:103], v[208:211], v[188:191], v[100:103]
	s_add_u32 m0, s13, 0x5000
	s_nop 0
	global_load_lds_dwordx4 v165, s[6:7]
	v_mfma_f32_16x16x32_bf16 v[104:107], v[212:215], v[188:191], v[104:107]
	s_add_u32 m0, s13, 0x6000
	v_add_u32_e32 v166, 0x2000, v165
	global_load_lds_dwordx4 v166, s[6:7]
	v_mfma_f32_16x16x32_bf16 v[108:111], v[216:219], v[188:191], v[108:111]
	s_add_u32 m0, s13, 0x7000
	v_add_u32_e32 v166, 0x10000, v165
	global_load_lds_dwordx4 v166, s[6:7]
	ds_read_b128 v[224:227], v118 offset:2048
	ds_read_b128 v[228:231], v118 offset:4096
	ds_read_b128 v[232:235], v118 offset:6144
	ds_read_b128 v[236:239], v118 offset:8192
	s_waitcnt lgkmcnt(11)
	v_mfma_f32_16x16x32_bf16 v[112:115], v[204:207], v[192:195], v[112:115]
	s_add_u32 m0, s13, 0x8000
	v_add_u32_e32 v166, 0x12000, v165
	global_load_lds_dwordx4 v166, s[6:7]
	v_mfma_f32_16x16x32_bf16 v[120:123], v[208:211], v[192:195], v[120:123]
	v_mfma_f32_16x16x32_bf16 v[124:127], v[212:215], v[192:195], v[124:127]
	v_mfma_f32_16x16x32_bf16 v[140:143], v[216:219], v[192:195], v[140:143]
	s_waitcnt lgkmcnt(10)
	v_mfma_f32_16x16x32_bf16 v[144:147], v[204:207], v[196:199], v[144:147]
	v_mfma_f32_16x16x32_bf16 v[148:151], v[208:211], v[196:199], v[148:151]
	v_mfma_f32_16x16x32_bf16 v[152:155], v[212:215], v[196:199], v[152:155]
	v_mfma_f32_16x16x32_bf16 v[156:159], v[216:219], v[196:199], v[156:159]
	s_waitcnt lgkmcnt(9)
	v_mfma_f32_16x16x32_bf16 v[168:171], v[204:207], v[200:203], v[168:171]
	v_mfma_f32_16x16x32_bf16 v[172:175], v[208:211], v[200:203], v[172:175]
	v_mfma_f32_16x16x32_bf16 v[176:179], v[212:215], v[200:203], v[176:179]
	v_mfma_f32_16x16x32_bf16 v[180:183], v[216:219], v[200:203], v[180:183]
	s_waitcnt lgkmcnt(7)
	v_mfma_f32_16x16x32_bf16 v[80:83], v[240:243], v[220:223], v[80:83]
	s_waitcnt lgkmcnt(6)
	v_mfma_f32_16x16x32_bf16 v[84:87], v[244:247], v[220:223], v[84:87]
	s_waitcnt lgkmcnt(5)
	v_mfma_f32_16x16x32_bf16 v[88:91], v[248:251], v[220:223], v[88:91]
	s_waitcnt lgkmcnt(4)
	v_mfma_f32_16x16x32_bf16 v[92:95], v[252:255], v[220:223], v[92:95]
	s_waitcnt lgkmcnt(3)
	v_mfma_f32_16x16x32_bf16 v[96:99], v[240:243], v[224:227], v[96:99]
	v_mfma_f32_16x16x32_bf16 v[100:103], v[244:247], v[224:227], v[100:103]
	v_mfma_f32_16x16x32_bf16 v[104:107], v[248:251], v[224:227], v[104:107]
	v_mfma_f32_16x16x32_bf16 v[108:111], v[252:255], v[224:227], v[108:111]
	s_waitcnt lgkmcnt(2)
	v_mfma_f32_16x16x32_bf16 v[112:115], v[240:243], v[228:231], v[112:115]
	v_mfma_f32_16x16x32_bf16 v[120:123], v[244:247], v[228:231], v[120:123]
	v_mfma_f32_16x16x32_bf16 v[124:127], v[248:251], v[228:231], v[124:127]
	v_mfma_f32_16x16x32_bf16 v[140:143], v[252:255], v[228:231], v[140:143]
	s_waitcnt lgkmcnt(1)
	v_mfma_f32_16x16x32_bf16 v[144:147], v[240:243], v[232:235], v[144:147]
	v_mfma_f32_16x16x32_bf16 v[148:151], v[244:247], v[232:235], v[148:151]
	v_mfma_f32_16x16x32_bf16 v[152:155], v[248:251], v[232:235], v[152:155]
	v_mfma_f32_16x16x32_bf16 v[156:159], v[252:255], v[232:235], v[156:159]
	s_add_u32 s2, s2, 0x80
	s_addc_u32 s3, s3, 0
	s_add_u32 s6, s6, 0x80
	s_addc_u32 s7, s7, 0
	s_waitcnt lgkmcnt(0)
	v_mfma_f32_16x16x32_bf16 v[168:171], v[240:243], v[236:239], v[168:171]
	v_mfma_f32_16x16x32_bf16 v[172:175], v[244:247], v[236:239], v[172:175]
	v_mfma_f32_16x16x32_bf16 v[176:179], v[248:251], v[236:239], v[176:179]
	v_mfma_f32_16x16x32_bf16 v[180:183], v[252:255], v[236:239], v[180:183]
	s_waitcnt vmcnt(0)
	s_barrier
	ds_read_b128 v[184:187], v116 offset:53504
	ds_read_b128 v[204:207], v119 offset:20480
	ds_read_b128 v[208:211], v119 offset:22528
	ds_read_b128 v[212:215], v119 offset:24576
	ds_read_b128 v[216:219], v119 offset:26624
	ds_read_b128 v[188:191], v116 offset:55552
	ds_read_b128 v[192:195], v116 offset:57600
	ds_read_b128 v[196:199], v116 offset:59648
	ds_read_b128 v[200:203], v116 offset:61696
	s_waitcnt lgkmcnt(7)
	v_mfma_f32_16x16x32_bf16 v[0:3], v[204:207], v[184:187], v[0:3]
	s_add_u32 m0, s13, 0x9000
	s_nop 0
	global_load_lds_dwordx4 v165, s[24:25]
	s_waitcnt lgkmcnt(6)
	v_mfma_f32_16x16x32_bf16 v[4:7], v[208:211], v[184:187], v[4:7]
	s_add_u32 m0, s13, 0xa000
	v_add_u32_e32 v166, 0x2000, v165
	global_load_lds_dwordx4 v166, s[24:25]
	s_waitcnt lgkmcnt(5)
	v_mfma_f32_16x16x32_bf16 v[8:11], v[212:215], v[184:187], v[8:11]
	s_add_u32 m0, s13, 0xb000
	v_add_u32_e32 v166, 0x10000, v165
	global_load_lds_dwordx4 v166, s[24:25]
	s_waitcnt lgkmcnt(4)
	v_mfma_f32_16x16x32_bf16 v[12:15], v[216:219], v[184:187], v[12:15]
	s_add_u32 m0, s13, 0xc000
	v_add_u32_e32 v166, 0x12000, v165
	global_load_lds_dwordx4 v166, s[24:25]
	ds_read_b128 v[220:223], v118 offset:53504
	ds_read_b128 v[240:243], v160 offset:20480
	ds_read_b128 v[244:247], v160 offset:22528
	ds_read_b128 v[248:251], v160 offset:24576
	ds_read_b128 v[252:255], v160 offset:26624
	s_waitcnt lgkmcnt(8)
	v_mfma_f32_16x16x32_bf16 v[16:19], v[204:207], v[188:191], v[16:19]
	v_mfma_f32_16x16x32_bf16 v[20:23], v[208:211], v[188:191], v[20:23]
	v_mfma_f32_16x16x32_bf16 v[24:27], v[212:215], v[188:191], v[24:27]
	v_mfma_f32_16x16x32_bf16 v[28:31], v[216:219], v[188:191], v[28:31]
	ds_read_b128 v[224:227], v118 offset:55552
	ds_read_b128 v[228:231], v118 offset:57600
	ds_read_b128 v[232:235], v118 offset:59648
	ds_read_b128 v[236:239], v118 offset:61696
	s_waitcnt lgkmcnt(11)
	v_mfma_f32_16x16x32_bf16 v[32:35], v[204:207], v[192:195], v[32:35]
	v_mfma_f32_16x16x32_bf16 v[36:39], v[208:211], v[192:195], v[36:39]
	v_mfma_f32_16x16x32_bf16 v[40:43], v[212:215], v[192:195], v[40:43]
	v_mfma_f32_16x16x32_bf16 v[44:47], v[216:219], v[192:195], v[44:47]
	s_waitcnt lgkmcnt(10)
	v_mfma_f32_16x16x32_bf16 v[48:51], v[204:207], v[196:199], v[48:51]
	v_mfma_f32_16x16x32_bf16 v[52:55], v[208:211], v[196:199], v[52:55]
	v_mfma_f32_16x16x32_bf16 v[56:59], v[212:215], v[196:199], v[56:59]
	v_mfma_f32_16x16x32_bf16 v[60:63], v[216:219], v[196:199], v[60:63]
	s_waitcnt lgkmcnt(9)
	v_mfma_f32_16x16x32_bf16 v[64:67], v[204:207], v[200:203], v[64:67]
	v_mfma_f32_16x16x32_bf16 v[68:71], v[208:211], v[200:203], v[68:71]
	v_mfma_f32_16x16x32_bf16 v[72:75], v[212:215], v[200:203], v[72:75]
	v_mfma_f32_16x16x32_bf16 v[76:79], v[216:219], v[200:203], v[76:79]
	s_waitcnt lgkmcnt(7)
	v_mfma_f32_16x16x32_bf16 v[0:3], v[240:243], v[220:223], v[0:3]
	s_waitcnt lgkmcnt(6)
	v_mfma_f32_16x16x32_bf16 v[4:7], v[244:247], v[220:223], v[4:7]
	s_waitcnt lgkmcnt(5)
	v_mfma_f32_16x16x32_bf16 v[8:11], v[248:251], v[220:223], v[8:11]
	s_waitcnt lgkmcnt(4)
	v_mfma_f32_16x16x32_bf16 v[12:15], v[252:255], v[220:223], v[12:15]
	s_waitcnt lgkmcnt(3)
	v_mfma_f32_16x16x32_bf16 v[16:19], v[240:243], v[224:227], v[16:19]
	v_mfma_f32_16x16x32_bf16 v[20:23], v[244:247], v[224:227], v[20:23]
	v_mfma_f32_16x16x32_bf16 v[24:27], v[248:251], v[224:227], v[24:27]
	v_mfma_f32_16x16x32_bf16 v[28:31], v[252:255], v[224:227], v[28:31]
	s_waitcnt lgkmcnt(2)
	v_mfma_f32_16x16x32_bf16 v[32:35], v[240:243], v[228:231], v[32:35]
	v_mfma_f32_16x16x32_bf16 v[36:39], v[244:247], v[228:231], v[36:39]
	v_mfma_f32_16x16x32_bf16 v[40:43], v[248:251], v[228:231], v[40:43]
	v_mfma_f32_16x16x32_bf16 v[44:47], v[252:255], v[228:231], v[44:47]
	s_waitcnt lgkmcnt(1)
	v_mfma_f32_16x16x32_bf16 v[48:51], v[240:243], v[232:235], v[48:51]
	v_mfma_f32_16x16x32_bf16 v[52:55], v[244:247], v[232:235], v[52:55]
	v_mfma_f32_16x16x32_bf16 v[56:59], v[248:251], v[232:235], v[56:59]
	v_mfma_f32_16x16x32_bf16 v[60:63], v[252:255], v[232:235], v[60:63]
	s_add_u32 s24, s24, 0x80
	s_addc_u32 s25, s25, 0
	s_waitcnt lgkmcnt(0)
	v_mfma_f32_16x16x32_bf16 v[64:67], v[240:243], v[236:239], v[64:67]
	v_mfma_f32_16x16x32_bf16 v[68:71], v[244:247], v[236:239], v[68:71]
	v_mfma_f32_16x16x32_bf16 v[72:75], v[248:251], v[236:239], v[72:75]
	v_mfma_f32_16x16x32_bf16 v[76:79], v[252:255], v[236:239], v[76:79]
	s_cmp_eq_u32 s12, 1
	s_cselect_b32 s2, s20, s2
	s_cselect_b32 s3, s21, s3
	s_cselect_b32 s6, s22, s6
	s_cselect_b32 s7, s23, s7
	s_add_u32 s4, s22, 0x20000
	s_addc_u32 s32, s23, 0
	s_cmp_eq_u32 s12, 1
	s_cselect_b32 s24, s4, s24
	s_cselect_b32 s25, s32, s25
	s_waitcnt vmcnt(0)
	s_barrier
	ds_read_b128 v[184:187], v116 offset:53504
	ds_read_b128 v[204:207], v119 offset:36864
	ds_read_b128 v[208:211], v119 offset:38912
	ds_read_b128 v[212:215], v119 offset:40960
	ds_read_b128 v[216:219], v119 offset:43008
	ds_read_b128 v[188:191], v116 offset:55552
	ds_read_b128 v[192:195], v116 offset:57600
	ds_read_b128 v[196:199], v116 offset:59648
	ds_read_b128 v[200:203], v116 offset:61696
	s_waitcnt lgkmcnt(7)
	v_mfma_f32_16x16x32_bf16 v[80:83], v[204:207], v[184:187], v[80:83]
	s_add_u32 m0, s13, 0x0
	s_nop 0
	global_load_lds_dwordx4 v161, s[2:3]
	s_waitcnt lgkmcnt(6)
	v_mfma_f32_16x16x32_bf16 v[84:87], v[208:211], v[184:187], v[84:87]
	s_add_u32 m0, s13, 0x1000
	v_add_u32_e32 v166, 0x10000, v161
	global_load_lds_dwordx4 v166, s[2:3]
	s_waitcnt lgkmcnt(5)
	v_mfma_f32_16x16x32_bf16 v[88:91], v[212:215], v[184:187], v[88:91]
	s_add_u32 m0, s13, 0x2000
	v_add_u32_e32 v166, 0x20000, v161
	global_load_lds_dwordx4 v166, s[2:3]
	s_waitcnt lgkmcnt(4)
	v_mfma_f32_16x16x32_bf16 v[92:95], v[216:219], v[184:187], v[92:95]
	s_add_u32 m0, s13, 0x3000
	v_add_u32_e32 v166, 0x30000, v161
	global_load_lds_dwordx4 v166, s[2:3]
	ds_read_b128 v[220:223], v118 offset:53504
	ds_read_b128 v[240:243], v160 offset:36864
	ds_read_b128 v[244:247], v160 offset:38912
	ds_read_b128 v[248:251], v160 offset:40960
	ds_read_b128 v[252:255], v160 offset:43008
	s_waitcnt lgkmcnt(8)
	v_mfma_f32_16x16x32_bf16 v[96:99], v[204:207], v[188:191], v[96:99]
	s_add_u32 m0, s13, 0x4000
	v_add_u32_e32 v166, 0x40000, v161
	global_load_lds_dwordx4 v166, s[2:3]
	v_mfma_f32_16x16x32_bf16 v[100:103], v[208:211], v[188:191], v[100:103]
	s_add_u32 m0, s13, 0x5000
	s_nop 0
	global_load_lds_dwordx4 v165, s[6:7]
	v_mfma_f32_16x16x32_bf16 v[104:107], v[212:215], v[188:191], v[104:107]
	s_add_u32 m0, s13, 0x6000
	v_add_u32_e32 v166, 0x2000, v165
	global_load_lds_dwordx4 v166, s[6:7]
	v_mfma_f32_16x16x32_bf16 v[108:111], v[216:219], v[188:191], v[108:111]
	s_add_u32 m0, s13, 0x7000
	v_add_u32_e32 v166, 0x10000, v165
	global_load_lds_dwordx4 v166, s[6:7]
	ds_read_b128 v[224:227], v118 offset:55552
	ds_read_b128 v[228:231], v118 offset:57600
	ds_read_b128 v[232:235], v118 offset:59648
	ds_read_b128 v[236:239], v118 offset:61696
	s_waitcnt lgkmcnt(11)
	v_mfma_f32_16x16x32_bf16 v[112:115], v[204:207], v[192:195], v[112:115]
	s_add_u32 m0, s13, 0x8000
	v_add_u32_e32 v166, 0x12000, v165
	global_load_lds_dwordx4 v166, s[6:7]
	v_mfma_f32_16x16x32_bf16 v[120:123], v[208:211], v[192:195], v[120:123]
	v_mfma_f32_16x16x32_bf16 v[124:127], v[212:215], v[192:195], v[124:127]
	v_mfma_f32_16x16x32_bf16 v[140:143], v[216:219], v[192:195], v[140:143]
	s_waitcnt lgkmcnt(10)
	v_mfma_f32_16x16x32_bf16 v[144:147], v[204:207], v[196:199], v[144:147]
	v_mfma_f32_16x16x32_bf16 v[148:151], v[208:211], v[196:199], v[148:151]
	v_mfma_f32_16x16x32_bf16 v[152:155], v[212:215], v[196:199], v[152:155]
	v_mfma_f32_16x16x32_bf16 v[156:159], v[216:219], v[196:199], v[156:159]
	s_waitcnt lgkmcnt(9)
	v_mfma_f32_16x16x32_bf16 v[168:171], v[204:207], v[200:203], v[168:171]
	v_mfma_f32_16x16x32_bf16 v[172:175], v[208:211], v[200:203], v[172:175]
	v_mfma_f32_16x16x32_bf16 v[176:179], v[212:215], v[200:203], v[176:179]
	v_mfma_f32_16x16x32_bf16 v[180:183], v[216:219], v[200:203], v[180:183]
	s_waitcnt lgkmcnt(7)
	v_mfma_f32_16x16x32_bf16 v[80:83], v[240:243], v[220:223], v[80:83]
	s_waitcnt lgkmcnt(6)
	v_mfma_f32_16x16x32_bf16 v[84:87], v[244:247], v[220:223], v[84:87]
	s_waitcnt lgkmcnt(5)
	v_mfma_f32_16x16x32_bf16 v[88:91], v[248:251], v[220:223], v[88:91]
	s_waitcnt lgkmcnt(4)
	v_mfma_f32_16x16x32_bf16 v[92:95], v[252:255], v[220:223], v[92:95]
	s_waitcnt lgkmcnt(3)
	v_mfma_f32_16x16x32_bf16 v[96:99], v[240:243], v[224:227], v[96:99]
	v_mfma_f32_16x16x32_bf16 v[100:103], v[244:247], v[224:227], v[100:103]
	v_mfma_f32_16x16x32_bf16 v[104:107], v[248:251], v[224:227], v[104:107]
	v_mfma_f32_16x16x32_bf16 v[108:111], v[252:255], v[224:227], v[108:111]
	s_waitcnt lgkmcnt(2)
	v_mfma_f32_16x16x32_bf16 v[112:115], v[240:243], v[228:231], v[112:115]
	v_mfma_f32_16x16x32_bf16 v[120:123], v[244:247], v[228:231], v[120:123]
	v_mfma_f32_16x16x32_bf16 v[124:127], v[248:251], v[228:231], v[124:127]
	v_mfma_f32_16x16x32_bf16 v[140:143], v[252:255], v[228:231], v[140:143]
	s_waitcnt lgkmcnt(1)
	v_mfma_f32_16x16x32_bf16 v[144:147], v[240:243], v[232:235], v[144:147]
	v_mfma_f32_16x16x32_bf16 v[148:151], v[244:247], v[232:235], v[148:151]
	v_mfma_f32_16x16x32_bf16 v[152:155], v[248:251], v[232:235], v[152:155]
	v_mfma_f32_16x16x32_bf16 v[156:159], v[252:255], v[232:235], v[156:159]
	s_add_u32 s2, s2, 0x80
	s_addc_u32 s3, s3, 0
	s_add_u32 s6, s6, 0x80
	s_addc_u32 s7, s7, 0
	s_waitcnt lgkmcnt(0)
	v_mfma_f32_16x16x32_bf16 v[168:171], v[240:243], v[236:239], v[168:171]
	v_mfma_f32_16x16x32_bf16 v[172:175], v[244:247], v[236:239], v[172:175]
	v_mfma_f32_16x16x32_bf16 v[176:179], v[248:251], v[236:239], v[176:179]
	v_mfma_f32_16x16x32_bf16 v[180:183], v[252:255], v[236:239], v[180:183]
	s_sub_u32 s12, s12, 1
	s_cmp_lg_u32 s12, 0
	s_cbranch_scc1 .Lggu0_pair
	s_and_b32 s4, s10, 7
	s_lshl_b32 s4, s4, 3
	s_bfe_u32 s14, s10, 0x30003
	s_or_b32 s14, s14, s4
	s_lshr_b32 s15, s10, 6
	s_mul_i32 s4, s14, 0xdc000
	s_lshl_b32 s32, s15, 8
	s_add_u32 s4, s4, s32
	s_add_u32 s8, s76, s4
	s_addc_u32 s9, s77, 0
	s_mov_b32 s44, s8
	s_mov_b32 s46, s9
	s_nop 7
	v_mul_f32_e32 v184, 0xbfb8aa3b, v0
	v_mul_f32_e32 v185, 0xbfb8aa3b, v1
	v_mul_f32_e32 v186, 0xbfb8aa3b, v2
	v_mul_f32_e32 v187, 0xbfb8aa3b, v3
	v_exp_f32_e32 v184, v184
	v_exp_f32_e32 v185, v185
	v_exp_f32_e32 v186, v186
	v_exp_f32_e32 v187, v187
	s_nop 0
	v_add_f32_e32 v184, 1.0, v184
	v_add_f32_e32 v185, 1.0, v185
	v_add_f32_e32 v186, 1.0, v186
	v_add_f32_e32 v187, 1.0, v187
	v_rcp_f32_e32 v184, v184
	v_rcp_f32_e32 v185, v185
	v_rcp_f32_e32 v186, v186
	v_rcp_f32_e32 v187, v187
	s_nop 0
	v_mul_f32_e32 v184, v0, v184
	v_mul_f32_e32 v185, v1, v185
	v_mul_f32_e32 v186, v2, v186
	v_mul_f32_e32 v187, v3, v187
	v_mul_f32_e32 v184, v4, v184
	v_mul_f32_e32 v185, v5, v185
	v_mul_f32_e32 v186, v6, v186
	v_mul_f32_e32 v187, v7, v187
	v_mul_f32_e32 v192, 0xbfb8aa3b, v8
	v_mul_f32_e32 v193, 0xbfb8aa3b, v9
	v_mul_f32_e32 v194, 0xbfb8aa3b, v10
	v_mul_f32_e32 v195, 0xbfb8aa3b, v11
	v_exp_f32_e32 v192, v192
	v_exp_f32_e32 v193, v193
	v_exp_f32_e32 v194, v194
	v_exp_f32_e32 v195, v195
	s_nop 0
	v_add_f32_e32 v192, 1.0, v192
	v_add_f32_e32 v193, 1.0, v193
	v_add_f32_e32 v194, 1.0, v194
	v_add_f32_e32 v195, 1.0, v195
	v_rcp_f32_e32 v192, v192
	v_rcp_f32_e32 v193, v193
	v_rcp_f32_e32 v194, v194
	v_rcp_f32_e32 v195, v195
	s_nop 0
	v_mul_f32_e32 v192, v8, v192
	v_mul_f32_e32 v193, v9, v193
	v_mul_f32_e32 v194, v10, v194
	v_mul_f32_e32 v195, v11, v195
	v_mul_f32_e32 v192, v12, v192
	v_mul_f32_e32 v193, v13, v193
	v_mul_f32_e32 v194, v14, v194
	v_mul_f32_e32 v195, v15, v195
	v_cvt_pk_bf16_f32 v200, v184, v185
	v_cvt_pk_bf16_f32 v201, v186, v187
	v_cvt_pk_bf16_f32 v202, v192, v193
	v_cvt_pk_bf16_f32 v203, v194, v195
	global_store_dwordx4 v167, v[200:203], s[8:9]
	s_add_u32 s8, s8, 0x16000
	s_addc_u32 s9, s9, 0
	v_mul_f32_e32 v184, 0xbfb8aa3b, v16
	v_mul_f32_e32 v185, 0xbfb8aa3b, v17
	v_mul_f32_e32 v186, 0xbfb8aa3b, v18
	v_mul_f32_e32 v187, 0xbfb8aa3b, v19
	v_exp_f32_e32 v184, v184
	v_exp_f32_e32 v185, v185
	v_exp_f32_e32 v186, v186
	v_exp_f32_e32 v187, v187
	s_nop 0
	v_add_f32_e32 v184, 1.0, v184
	v_add_f32_e32 v185, 1.0, v185
	v_add_f32_e32 v186, 1.0, v186
	v_add_f32_e32 v187, 1.0, v187
	v_rcp_f32_e32 v184, v184
	v_rcp_f32_e32 v185, v185
	v_rcp_f32_e32 v186, v186
	v_rcp_f32_e32 v187, v187
	s_nop 0
	v_mul_f32_e32 v184, v16, v184
	v_mul_f32_e32 v185, v17, v185
	v_mul_f32_e32 v186, v18, v186
	v_mul_f32_e32 v187, v19, v187
	v_mul_f32_e32 v184, v20, v184
	v_mul_f32_e32 v185, v21, v185
	v_mul_f32_e32 v186, v22, v186
	v_mul_f32_e32 v187, v23, v187
	v_mul_f32_e32 v192, 0xbfb8aa3b, v24
	v_mul_f32_e32 v193, 0xbfb8aa3b, v25
	v_mul_f32_e32 v194, 0xbfb8aa3b, v26
	v_mul_f32_e32 v195, 0xbfb8aa3b, v27
	v_exp_f32_e32 v192, v192
	v_exp_f32_e32 v193, v193
	v_exp_f32_e32 v194, v194
	v_exp_f32_e32 v195, v195
	s_nop 0
	v_add_f32_e32 v192, 1.0, v192
	v_add_f32_e32 v193, 1.0, v193
	v_add_f32_e32 v194, 1.0, v194
	v_add_f32_e32 v195, 1.0, v195
	v_rcp_f32_e32 v192, v192
	v_rcp_f32_e32 v193, v193
	v_rcp_f32_e32 v194, v194
	v_rcp_f32_e32 v195, v195
	s_nop 0
	v_mul_f32_e32 v192, v24, v192
	v_mul_f32_e32 v193, v25, v193
	v_mul_f32_e32 v194, v26, v194
	v_mul_f32_e32 v195, v27, v195
	v_mul_f32_e32 v192, v28, v192
	v_mul_f32_e32 v193, v29, v193
	v_mul_f32_e32 v194, v30, v194
	v_mul_f32_e32 v195, v31, v195
	v_cvt_pk_bf16_f32 v204, v184, v185
	v_cvt_pk_bf16_f32 v205, v186, v187
	v_cvt_pk_bf16_f32 v206, v192, v193
	v_cvt_pk_bf16_f32 v207, v194, v195
	global_store_dwordx4 v167, v[204:207], s[8:9]
	s_add_u32 s8, s8, 0x16000
	s_addc_u32 s9, s9, 0
	v_mul_f32_e32 v184, 0xbfb8aa3b, v32
	v_mul_f32_e32 v185, 0xbfb8aa3b, v33
	v_mul_f32_e32 v186, 0xbfb8aa3b, v34
	v_mul_f32_e32 v187, 0xbfb8aa3b, v35
	v_exp_f32_e32 v184, v184
	v_exp_f32_e32 v185, v185
	v_exp_f32_e32 v186, v186
	v_exp_f32_e32 v187, v187
	s_nop 0
	v_add_f32_e32 v184, 1.0, v184
	v_add_f32_e32 v185, 1.0, v185
	v_add_f32_e32 v186, 1.0, v186
	v_add_f32_e32 v187, 1.0, v187
	v_rcp_f32_e32 v184, v184
	v_rcp_f32_e32 v185, v185
	v_rcp_f32_e32 v186, v186
	v_rcp_f32_e32 v187, v187
	s_nop 0
	v_mul_f32_e32 v184, v32, v184
	v_mul_f32_e32 v185, v33, v185
	v_mul_f32_e32 v186, v34, v186
	v_mul_f32_e32 v187, v35, v187
	v_mul_f32_e32 v184, v36, v184
	v_mul_f32_e32 v185, v37, v185
	v_mul_f32_e32 v186, v38, v186
	v_mul_f32_e32 v187, v39, v187
	v_mul_f32_e32 v192, 0xbfb8aa3b, v40
	v_mul_f32_e32 v193, 0xbfb8aa3b, v41
	v_mul_f32_e32 v194, 0xbfb8aa3b, v42
	v_mul_f32_e32 v195, 0xbfb8aa3b, v43
	v_exp_f32_e32 v192, v192
	v_exp_f32_e32 v193, v193
	v_exp_f32_e32 v194, v194
	v_exp_f32_e32 v195, v195
	s_nop 0
	v_add_f32_e32 v192, 1.0, v192
	v_add_f32_e32 v193, 1.0, v193
	v_add_f32_e32 v194, 1.0, v194
	v_add_f32_e32 v195, 1.0, v195
	v_rcp_f32_e32 v192, v192
	v_rcp_f32_e32 v193, v193
	v_rcp_f32_e32 v194, v194
	v_rcp_f32_e32 v195, v195
	s_nop 0
	v_mul_f32_e32 v192, v40, v192
	v_mul_f32_e32 v193, v41, v193
	v_mul_f32_e32 v194, v42, v194
	v_mul_f32_e32 v195, v43, v195
	v_mul_f32_e32 v192, v44, v192
	v_mul_f32_e32 v193, v45, v193
	v_mul_f32_e32 v194, v46, v194
	v_mul_f32_e32 v195, v47, v195
	v_cvt_pk_bf16_f32 v208, v184, v185
	v_cvt_pk_bf16_f32 v209, v186, v187
	v_cvt_pk_bf16_f32 v210, v192, v193
	v_cvt_pk_bf16_f32 v211, v194, v195
	global_store_dwordx4 v167, v[208:211], s[8:9]
	s_add_u32 s8, s8, 0x16000
	s_addc_u32 s9, s9, 0
	v_mul_f32_e32 v184, 0xbfb8aa3b, v48
	v_mul_f32_e32 v185, 0xbfb8aa3b, v49
	v_mul_f32_e32 v186, 0xbfb8aa3b, v50
	v_mul_f32_e32 v187, 0xbfb8aa3b, v51
	v_exp_f32_e32 v184, v184
	v_exp_f32_e32 v185, v185
	v_exp_f32_e32 v186, v186
	v_exp_f32_e32 v187, v187
	s_nop 0
	v_add_f32_e32 v184, 1.0, v184
	v_add_f32_e32 v185, 1.0, v185
	v_add_f32_e32 v186, 1.0, v186
	v_add_f32_e32 v187, 1.0, v187
	v_rcp_f32_e32 v184, v184
	v_rcp_f32_e32 v185, v185
	v_rcp_f32_e32 v186, v186
	v_rcp_f32_e32 v187, v187
	s_nop 0
	v_mul_f32_e32 v184, v48, v184
	v_mul_f32_e32 v185, v49, v185
	v_mul_f32_e32 v186, v50, v186
	v_mul_f32_e32 v187, v51, v187
	v_mul_f32_e32 v184, v52, v184
	v_mul_f32_e32 v185, v53, v185
	v_mul_f32_e32 v186, v54, v186
	v_mul_f32_e32 v187, v55, v187
	v_mul_f32_e32 v192, 0xbfb8aa3b, v56
	v_mul_f32_e32 v193, 0xbfb8aa3b, v57
	v_mul_f32_e32 v194, 0xbfb8aa3b, v58
	v_mul_f32_e32 v195, 0xbfb8aa3b, v59
	v_exp_f32_e32 v192, v192
	v_exp_f32_e32 v193, v193
	v_exp_f32_e32 v194, v194
	v_exp_f32_e32 v195, v195
	s_nop 0
	v_add_f32_e32 v192, 1.0, v192
	v_add_f32_e32 v193, 1.0, v193
	v_add_f32_e32 v194, 1.0, v194
	v_add_f32_e32 v195, 1.0, v195
	v_rcp_f32_e32 v192, v192
	v_rcp_f32_e32 v193, v193
	v_rcp_f32_e32 v194, v194
	v_rcp_f32_e32 v195, v195
	s_nop 0
	v_mul_f32_e32 v192, v56, v192
	v_mul_f32_e32 v193, v57, v193
	v_mul_f32_e32 v194, v58, v194
	v_mul_f32_e32 v195, v59, v195
	v_mul_f32_e32 v192, v60, v192
	v_mul_f32_e32 v193, v61, v193
	v_mul_f32_e32 v194, v62, v194
	v_mul_f32_e32 v195, v63, v195
	v_cvt_pk_bf16_f32 v212, v184, v185
	v_cvt_pk_bf16_f32 v213, v186, v187
	v_cvt_pk_bf16_f32 v214, v192, v193
	v_cvt_pk_bf16_f32 v215, v194, v195
	global_store_dwordx4 v167, v[212:215], s[8:9]
	s_add_u32 s8, s8, 0x16000
	s_addc_u32 s9, s9, 0
	v_mul_f32_e32 v184, 0xbfb8aa3b, v64
	v_mul_f32_e32 v185, 0xbfb8aa3b, v65
	v_mul_f32_e32 v186, 0xbfb8aa3b, v66
	v_mul_f32_e32 v187, 0xbfb8aa3b, v67
	v_exp_f32_e32 v184, v184
	v_exp_f32_e32 v185, v185
	v_exp_f32_e32 v186, v186
	v_exp_f32_e32 v187, v187
	s_nop 0
	v_add_f32_e32 v184, 1.0, v184
	v_add_f32_e32 v185, 1.0, v185
	v_add_f32_e32 v186, 1.0, v186
	v_add_f32_e32 v187, 1.0, v187
	v_rcp_f32_e32 v184, v184
	v_rcp_f32_e32 v185, v185
	v_rcp_f32_e32 v186, v186
	v_rcp_f32_e32 v187, v187
	s_nop 0
	v_mul_f32_e32 v184, v64, v184
	v_mul_f32_e32 v185, v65, v185
	v_mul_f32_e32 v186, v66, v186
	v_mul_f32_e32 v187, v67, v187
	v_mul_f32_e32 v184, v68, v184
	v_mul_f32_e32 v185, v69, v185
	v_mul_f32_e32 v186, v70, v186
	v_mul_f32_e32 v187, v71, v187
	v_mul_f32_e32 v192, 0xbfb8aa3b, v72
	v_mul_f32_e32 v193, 0xbfb8aa3b, v73
	v_mul_f32_e32 v194, 0xbfb8aa3b, v74
	v_mul_f32_e32 v195, 0xbfb8aa3b, v75
	v_exp_f32_e32 v192, v192
	v_exp_f32_e32 v193, v193
	v_exp_f32_e32 v194, v194
	v_exp_f32_e32 v195, v195
	s_nop 0
	v_add_f32_e32 v192, 1.0, v192
	v_add_f32_e32 v193, 1.0, v193
	v_add_f32_e32 v194, 1.0, v194
	v_add_f32_e32 v195, 1.0, v195
	v_rcp_f32_e32 v192, v192
	v_rcp_f32_e32 v193, v193
	v_rcp_f32_e32 v194, v194
	v_rcp_f32_e32 v195, v195
	s_nop 0
	v_mul_f32_e32 v192, v72, v192
	v_mul_f32_e32 v193, v73, v193
	v_mul_f32_e32 v194, v74, v194
	v_mul_f32_e32 v195, v75, v195
	v_mul_f32_e32 v192, v76, v192
	v_mul_f32_e32 v193, v77, v193
	v_mul_f32_e32 v194, v78, v194
	v_mul_f32_e32 v195, v79, v195
	v_cvt_pk_bf16_f32 v216, v184, v185
	v_cvt_pk_bf16_f32 v217, v186, v187
	v_cvt_pk_bf16_f32 v218, v192, v193
	v_cvt_pk_bf16_f32 v219, v194, v195
	global_store_dwordx4 v167, v[216:219], s[8:9]
	s_add_u32 s8, s44, 0x80
	s_addc_u32 s9, s46, 0
	v_mul_f32_e32 v184, 0xbfb8aa3b, v80
	v_mul_f32_e32 v185, 0xbfb8aa3b, v81
	v_mul_f32_e32 v186, 0xbfb8aa3b, v82
	v_mul_f32_e32 v187, 0xbfb8aa3b, v83
	v_exp_f32_e32 v184, v184
	v_exp_f32_e32 v185, v185
	v_exp_f32_e32 v186, v186
	v_exp_f32_e32 v187, v187
	s_nop 0
	v_add_f32_e32 v184, 1.0, v184
	v_add_f32_e32 v185, 1.0, v185
	v_add_f32_e32 v186, 1.0, v186
	v_add_f32_e32 v187, 1.0, v187
	v_rcp_f32_e32 v184, v184
	v_rcp_f32_e32 v185, v185
	v_rcp_f32_e32 v186, v186
	v_rcp_f32_e32 v187, v187
	s_nop 0
	v_mul_f32_e32 v184, v80, v184
	v_mul_f32_e32 v185, v81, v185
	v_mul_f32_e32 v186, v82, v186
	v_mul_f32_e32 v187, v83, v187
	v_mul_f32_e32 v184, v84, v184
	v_mul_f32_e32 v185, v85, v185
	v_mul_f32_e32 v186, v86, v186
	v_mul_f32_e32 v187, v87, v187
	v_mul_f32_e32 v192, 0xbfb8aa3b, v88
	v_mul_f32_e32 v193, 0xbfb8aa3b, v89
	v_mul_f32_e32 v194, 0xbfb8aa3b, v90
	v_mul_f32_e32 v195, 0xbfb8aa3b, v91
	v_exp_f32_e32 v192, v192
	v_exp_f32_e32 v193, v193
	v_exp_f32_e32 v194, v194
	v_exp_f32_e32 v195, v195
	s_nop 0
	v_add_f32_e32 v192, 1.0, v192
	v_add_f32_e32 v193, 1.0, v193
	v_add_f32_e32 v194, 1.0, v194
	v_add_f32_e32 v195, 1.0, v195
	v_rcp_f32_e32 v192, v192
	v_rcp_f32_e32 v193, v193
	v_rcp_f32_e32 v194, v194
	v_rcp_f32_e32 v195, v195
	s_nop 0
	v_mul_f32_e32 v192, v88, v192
	v_mul_f32_e32 v193, v89, v193
	v_mul_f32_e32 v194, v90, v194
	v_mul_f32_e32 v195, v91, v195
	v_mul_f32_e32 v192, v92, v192
	v_mul_f32_e32 v193, v93, v193
	v_mul_f32_e32 v194, v94, v194
	v_mul_f32_e32 v195, v95, v195
	v_cvt_pk_bf16_f32 v200, v184, v185
	v_cvt_pk_bf16_f32 v201, v186, v187
	v_cvt_pk_bf16_f32 v202, v192, v193
	v_cvt_pk_bf16_f32 v203, v194, v195
	global_store_dwordx4 v167, v[200:203], s[8:9]
	s_add_u32 s8, s8, 0x16000
	s_addc_u32 s9, s9, 0
	v_mul_f32_e32 v184, 0xbfb8aa3b, v96
	v_mul_f32_e32 v185, 0xbfb8aa3b, v97
	v_mul_f32_e32 v186, 0xbfb8aa3b, v98
	v_mul_f32_e32 v187, 0xbfb8aa3b, v99
	v_exp_f32_e32 v184, v184
	v_exp_f32_e32 v185, v185
	v_exp_f32_e32 v186, v186
	v_exp_f32_e32 v187, v187
	s_nop 0
	v_add_f32_e32 v184, 1.0, v184
	v_add_f32_e32 v185, 1.0, v185
	v_add_f32_e32 v186, 1.0, v186
	v_add_f32_e32 v187, 1.0, v187
	v_rcp_f32_e32 v184, v184
	v_rcp_f32_e32 v185, v185
	v_rcp_f32_e32 v186, v186
	v_rcp_f32_e32 v187, v187
	s_nop 0
	v_mul_f32_e32 v184, v96, v184
	v_mul_f32_e32 v185, v97, v185
	v_mul_f32_e32 v186, v98, v186
	v_mul_f32_e32 v187, v99, v187
	v_mul_f32_e32 v184, v100, v184
	v_mul_f32_e32 v185, v101, v185
	v_mul_f32_e32 v186, v102, v186
	v_mul_f32_e32 v187, v103, v187
	v_mul_f32_e32 v192, 0xbfb8aa3b, v104
	v_mul_f32_e32 v193, 0xbfb8aa3b, v105
	v_mul_f32_e32 v194, 0xbfb8aa3b, v106
	v_mul_f32_e32 v195, 0xbfb8aa3b, v107
	v_exp_f32_e32 v192, v192
	v_exp_f32_e32 v193, v193
	v_exp_f32_e32 v194, v194
	v_exp_f32_e32 v195, v195
	s_nop 0
	v_add_f32_e32 v192, 1.0, v192
	v_add_f32_e32 v193, 1.0, v193
	v_add_f32_e32 v194, 1.0, v194
	v_add_f32_e32 v195, 1.0, v195
	v_rcp_f32_e32 v192, v192
	v_rcp_f32_e32 v193, v193
	v_rcp_f32_e32 v194, v194
	v_rcp_f32_e32 v195, v195
	s_nop 0
	v_mul_f32_e32 v192, v104, v192
	v_mul_f32_e32 v193, v105, v193
	v_mul_f32_e32 v194, v106, v194
	v_mul_f32_e32 v195, v107, v195
	v_mul_f32_e32 v192, v108, v192
	v_mul_f32_e32 v193, v109, v193
	v_mul_f32_e32 v194, v110, v194
	v_mul_f32_e32 v195, v111, v195
	v_cvt_pk_bf16_f32 v204, v184, v185
	v_cvt_pk_bf16_f32 v205, v186, v187
	v_cvt_pk_bf16_f32 v206, v192, v193
	v_cvt_pk_bf16_f32 v207, v194, v195
	global_store_dwordx4 v167, v[204:207], s[8:9]
	s_add_u32 s8, s8, 0x16000
	s_addc_u32 s9, s9, 0
	v_mul_f32_e32 v184, 0xbfb8aa3b, v112
	v_mul_f32_e32 v185, 0xbfb8aa3b, v113
	v_mul_f32_e32 v186, 0xbfb8aa3b, v114
	v_mul_f32_e32 v187, 0xbfb8aa3b, v115
	v_exp_f32_e32 v184, v184
	v_exp_f32_e32 v185, v185
	v_exp_f32_e32 v186, v186
	v_exp_f32_e32 v187, v187
	s_nop 0
	v_add_f32_e32 v184, 1.0, v184
	v_add_f32_e32 v185, 1.0, v185
	v_add_f32_e32 v186, 1.0, v186
	v_add_f32_e32 v187, 1.0, v187
	v_rcp_f32_e32 v184, v184
	v_rcp_f32_e32 v185, v185
	v_rcp_f32_e32 v186, v186
	v_rcp_f32_e32 v187, v187
	s_nop 0
	v_mul_f32_e32 v184, v112, v184
	v_mul_f32_e32 v185, v113, v185
	v_mul_f32_e32 v186, v114, v186
	v_mul_f32_e32 v187, v115, v187
	v_mul_f32_e32 v184, v120, v184
	v_mul_f32_e32 v185, v121, v185
	v_mul_f32_e32 v186, v122, v186
	v_mul_f32_e32 v187, v123, v187
	v_mul_f32_e32 v192, 0xbfb8aa3b, v124
	v_mul_f32_e32 v193, 0xbfb8aa3b, v125
	v_mul_f32_e32 v194, 0xbfb8aa3b, v126
	v_mul_f32_e32 v195, 0xbfb8aa3b, v127
	v_exp_f32_e32 v192, v192
	v_exp_f32_e32 v193, v193
	v_exp_f32_e32 v194, v194
	v_exp_f32_e32 v195, v195
	s_nop 0
	v_add_f32_e32 v192, 1.0, v192
	v_add_f32_e32 v193, 1.0, v193
	v_add_f32_e32 v194, 1.0, v194
	v_add_f32_e32 v195, 1.0, v195
	v_rcp_f32_e32 v192, v192
	v_rcp_f32_e32 v193, v193
	v_rcp_f32_e32 v194, v194
	v_rcp_f32_e32 v195, v195
	s_nop 0
	v_mul_f32_e32 v192, v124, v192
	v_mul_f32_e32 v193, v125, v193
	v_mul_f32_e32 v194, v126, v194
	v_mul_f32_e32 v195, v127, v195
	v_mul_f32_e32 v192, v140, v192
	v_mul_f32_e32 v193, v141, v193
	v_mul_f32_e32 v194, v142, v194
	v_mul_f32_e32 v195, v143, v195
	v_cvt_pk_bf16_f32 v208, v184, v185
	v_cvt_pk_bf16_f32 v209, v186, v187
	v_cvt_pk_bf16_f32 v210, v192, v193
	v_cvt_pk_bf16_f32 v211, v194, v195
	global_store_dwordx4 v167, v[208:211], s[8:9]
	s_add_u32 s8, s8, 0x16000
	s_addc_u32 s9, s9, 0
	v_mul_f32_e32 v184, 0xbfb8aa3b, v144
	v_mul_f32_e32 v185, 0xbfb8aa3b, v145
	v_mul_f32_e32 v186, 0xbfb8aa3b, v146
	v_mul_f32_e32 v187, 0xbfb8aa3b, v147
	v_exp_f32_e32 v184, v184
	v_exp_f32_e32 v185, v185
	v_exp_f32_e32 v186, v186
	v_exp_f32_e32 v187, v187
	s_nop 0
	v_add_f32_e32 v184, 1.0, v184
	v_add_f32_e32 v185, 1.0, v185
	v_add_f32_e32 v186, 1.0, v186
	v_add_f32_e32 v187, 1.0, v187
	v_rcp_f32_e32 v184, v184
	v_rcp_f32_e32 v185, v185
	v_rcp_f32_e32 v186, v186
	v_rcp_f32_e32 v187, v187
	s_nop 0
	v_mul_f32_e32 v184, v144, v184
	v_mul_f32_e32 v185, v145, v185
	v_mul_f32_e32 v186, v146, v186
	v_mul_f32_e32 v187, v147, v187
	v_mul_f32_e32 v184, v148, v184
	v_mul_f32_e32 v185, v149, v185
	v_mul_f32_e32 v186, v150, v186
	v_mul_f32_e32 v187, v151, v187
	v_mul_f32_e32 v192, 0xbfb8aa3b, v152
	v_mul_f32_e32 v193, 0xbfb8aa3b, v153
	v_mul_f32_e32 v194, 0xbfb8aa3b, v154
	v_mul_f32_e32 v195, 0xbfb8aa3b, v155
	v_exp_f32_e32 v192, v192
	v_exp_f32_e32 v193, v193
	v_exp_f32_e32 v194, v194
	v_exp_f32_e32 v195, v195
	s_nop 0
	v_add_f32_e32 v192, 1.0, v192
	v_add_f32_e32 v193, 1.0, v193
	v_add_f32_e32 v194, 1.0, v194
	v_add_f32_e32 v195, 1.0, v195
	v_rcp_f32_e32 v192, v192
	v_rcp_f32_e32 v193, v193
	v_rcp_f32_e32 v194, v194
	v_rcp_f32_e32 v195, v195
	s_nop 0
	v_mul_f32_e32 v192, v152, v192
	v_mul_f32_e32 v193, v153, v193
	v_mul_f32_e32 v194, v154, v194
	v_mul_f32_e32 v195, v155, v195
	v_mul_f32_e32 v192, v156, v192
	v_mul_f32_e32 v193, v157, v193
	v_mul_f32_e32 v194, v158, v194
	v_mul_f32_e32 v195, v159, v195
	v_cvt_pk_bf16_f32 v212, v184, v185
	v_cvt_pk_bf16_f32 v213, v186, v187
	v_cvt_pk_bf16_f32 v214, v192, v193
	v_cvt_pk_bf16_f32 v215, v194, v195
	global_store_dwordx4 v167, v[212:215], s[8:9]
	s_add_u32 s8, s8, 0x16000
	s_addc_u32 s9, s9, 0
	v_mul_f32_e32 v184, 0xbfb8aa3b, v168
	v_mul_f32_e32 v185, 0xbfb8aa3b, v169
	v_mul_f32_e32 v186, 0xbfb8aa3b, v170
	v_mul_f32_e32 v187, 0xbfb8aa3b, v171
	v_exp_f32_e32 v184, v184
	v_exp_f32_e32 v185, v185
	v_exp_f32_e32 v186, v186
	v_exp_f32_e32 v187, v187
	s_nop 0
	v_add_f32_e32 v184, 1.0, v184
	v_add_f32_e32 v185, 1.0, v185
	v_add_f32_e32 v186, 1.0, v186
	v_add_f32_e32 v187, 1.0, v187
	v_rcp_f32_e32 v184, v184
	v_rcp_f32_e32 v185, v185
	v_rcp_f32_e32 v186, v186
	v_rcp_f32_e32 v187, v187
	s_nop 0
	v_mul_f32_e32 v184, v168, v184
	v_mul_f32_e32 v185, v169, v185
	v_mul_f32_e32 v186, v170, v186
	v_mul_f32_e32 v187, v171, v187
	v_mul_f32_e32 v184, v172, v184
	v_mul_f32_e32 v185, v173, v185
	v_mul_f32_e32 v186, v174, v186
	v_mul_f32_e32 v187, v175, v187
	v_mul_f32_e32 v192, 0xbfb8aa3b, v176
	v_mul_f32_e32 v193, 0xbfb8aa3b, v177
	v_mul_f32_e32 v194, 0xbfb8aa3b, v178
	v_mul_f32_e32 v195, 0xbfb8aa3b, v179
	v_exp_f32_e32 v192, v192
	v_exp_f32_e32 v193, v193
	v_exp_f32_e32 v194, v194
	v_exp_f32_e32 v195, v195
	s_nop 0
	v_add_f32_e32 v192, 1.0, v192
	v_add_f32_e32 v193, 1.0, v193
	v_add_f32_e32 v194, 1.0, v194
	v_add_f32_e32 v195, 1.0, v195
	v_rcp_f32_e32 v192, v192
	v_rcp_f32_e32 v193, v193
	v_rcp_f32_e32 v194, v194
	v_rcp_f32_e32 v195, v195
	s_nop 0
	v_mul_f32_e32 v192, v176, v192
	v_mul_f32_e32 v193, v177, v193
	v_mul_f32_e32 v194, v178, v194
	v_mul_f32_e32 v195, v179, v195
	v_mul_f32_e32 v192, v180, v192
	v_mul_f32_e32 v193, v181, v193
	v_mul_f32_e32 v194, v182, v194
	v_mul_f32_e32 v195, v183, v195
	v_cvt_pk_bf16_f32 v216, v184, v185
	v_cvt_pk_bf16_f32 v217, v186, v187
	v_cvt_pk_bf16_f32 v218, v192, v193
	v_cvt_pk_bf16_f32 v219, v194, v195
	global_store_dwordx4 v167, v[216:219], s[8:9]
	s_mov_b32 s48, 1
	s_add_u32 s10, s10, s11
	s_cmp_lt_u32 s10, 0x580
	s_cbranch_scc1 .Lggu0_tile

.Ltrp_1:
	s_or_b64 exec, exec, s[24:25]
	s_movk_i32 s4, 0x104
	v_lshlrev_b32_e32 v1, 2, v1
	v_mul_lo_u32 v10, v9, s4
	v_add_u32_e32 v10, v1, v10
	s_waitcnt vmcnt(0)
	ds_write2_b32 v10, v168, v169 offset1:1
	ds_write2_b32 v10, v170, v171 offset0:2 offset1:3
	v_add_u32_e32 v4, 0x1040, v10
	ds_write2_b32 v4, v172, v173 offset1:1
	v_add_u32_e32 v0, 0x1048, v10
	ds_write2_b32 v0, v174, v175 offset1:1
	v_add_u32_e32 v1, 0x2080, v10
	ds_write2_b32 v1, v176, v177 offset1:1
	v_add_u32_e32 v2, 0x2088, v10
	ds_write2_b32 v2, v178, v179 offset1:1
	v_add_u32_e32 v3, 0x30c0, v10
	ds_write2_b32 v3, v180, v181 offset1:1
	v_add_u32_e32 v5, 0x30c8, v10
	ds_write2_b32 v5, v182, v183 offset1:1
	v_lshlrev_b32_e32 v0, 4, v8
	v_and_b32_e32 v18, 48, v0
	v_and_b32_e32 v0, -4, v8
	s_movk_i32 s2, 0x104
	v_mad_u32_u24 v12, v18, s2, v0
	s_waitcnt lgkmcnt(0)
	s_barrier
	ds_read2_b32 v[0:1], v12 offset1:65
	ds_read2_b32 v[2:3], v12 offset0:130 offset1:195
	v_ashrrev_i32_e32 v16, 2, v8
	v_add_u32_e32 v6, 0x400, v12
	v_add_u32_e32 v16, s3, v16
	ds_read2_b32 v[4:5], v6 offset0:4 offset1:69
	ds_read2_b32 v[6:7], v6 offset0:134 offset1:199
	v_ashrrev_i32_e32 v17, 31, v16
	v_mul_lo_u32 v19, s22, v17
	v_mul_lo_u32 v20, s23, v16
	v_mad_u64_u32 v[16:17], s[2:3], s22, v16, 0
	v_lshlrev_b32_e32 v116, 1, v18
	s_waitcnt lgkmcnt(2)
	v_add3_u32 v17, v17, v19, v20
	v_cvt_pk_bf16_f32 v2, v2, v2
	v_cvt_pk_bf16_f32 v0, v0, v0
	v_and_b32_sdwa v19, v1, v129 dst_sel:DWORD dst_unused:UNUSED_PAD src0_sel:WORD_1 src1_sel:DWORD
	v_cvt_pk_bf16_f32 v3, v3, v3
	v_cvt_pk_bf16_f32 v1, v1, v1
	v_and_b32_e32 v3, 0xffff0000, v3
	v_add_u32_e32 v10, 0x800, v12
	v_and_b32_e32 v18, 0xffff0000, v1
	v_or_b32_sdwa v1, v3, v2 dst_sel:DWORD dst_unused:UNUSED_PAD src0_sel:DWORD src1_sel:WORD_1
	s_waitcnt lgkmcnt(0)
	ds_read2_b32 v[8:9], v10 offset0:8 offset1:73
	ds_read2_b32 v[10:11], v10 offset0:138 offset1:203
	v_cvt_pk_bf16_f32 v4, v4, v4
	v_cvt_pk_bf16_f32 v2, v6, v6
	v_and_b32_sdwa v6, v5, v129 dst_sel:DWORD dst_unused:UNUSED_PAD src0_sel:WORD_1 src1_sel:DWORD
	v_lshl_add_u64 v[16:17], v[16:17], 1, s[20:21]
	s_lshl_b32 s36, s36, 1
	v_cvt_pk_bf16_f32 v3, v7, v7
	v_cvt_pk_bf16_f32 v5, v5, v5
	v_lshl_add_u64 v[16:17], v[16:17], 0, s[36:37]
	v_and_b32_e32 v3, 0xffff0000, v3
	v_and_b32_e32 v5, 0xffff0000, v5
	v_add_u32_e32 v14, 0xc00, v12
	v_lshl_add_u64 v[16:17], v[16:17], 0, v[116:117]
	v_or_b32_sdwa v0, v18, v0 dst_sel:DWORD dst_unused:UNUSED_PAD src0_sel:DWORD src1_sel:WORD_1
	v_or_b32_sdwa v3, v3, v2 dst_sel:DWORD dst_unused:UNUSED_PAD src0_sel:DWORD src1_sel:WORD_1
	v_or_b32_sdwa v2, v5, v4 dst_sel:DWORD dst_unused:UNUSED_PAD src0_sel:DWORD src1_sel:WORD_1
	ds_read2_b32 v[12:13], v14 offset0:12 offset1:77
	ds_read2_b32 v[14:15], v14 offset0:142 offset1:207
	global_store_dwordx4 v[16:17], v[0:3], off
	s_mov_b64 s[20:21], 0
	s_waitcnt lgkmcnt(1)
	v_cvt_pk_bf16_f32 v2, v8, v8
	v_cvt_pk_bf16_f32 v1, v11, v11
	v_cvt_pk_bf16_f32 v3, v9, v9
	v_cvt_pk_bf16_f32 v0, v10, v10
	v_and_b32_e32 v1, 0xffff0000, v1
	v_and_b32_e32 v3, 0xffff0000, v3
	v_or_b32_sdwa v1, v1, v0 dst_sel:DWORD dst_unused:UNUSED_PAD src0_sel:DWORD src1_sel:WORD_1
	v_or_b32_sdwa v0, v3, v2 dst_sel:DWORD dst_unused:UNUSED_PAD src0_sel:DWORD src1_sel:WORD_1
	v_cvt_pk_bf16_f32 v4, v12, v12
	s_waitcnt lgkmcnt(0)
	v_cvt_pk_bf16_f32 v3, v15, v15
	v_cvt_pk_bf16_f32 v5, v13, v13
	v_cvt_pk_bf16_f32 v2, v14, v14
	v_and_b32_e32 v3, 0xffff0000, v3
	v_and_b32_e32 v5, 0xffff0000, v5
	v_or_b32_sdwa v3, v3, v2 dst_sel:DWORD dst_unused:UNUSED_PAD src0_sel:DWORD src1_sel:WORD_1
	v_or_b32_sdwa v2, v5, v4 dst_sel:DWORD dst_unused:UNUSED_PAD src0_sel:DWORD src1_sel:WORD_1
	global_store_dwordx4 v[16:17], v[0:3], off offset:16
	s_barrier
	s_add_u32 s53, s53, 1
	s_cmp_lt_u32 s53, 8
	s_cbranch_scc0 .Ltr_done
	s_add_u32 s35, s35, 1
	s_branch .Ltr_again

.LBB0_636:
	v_lshl_add_u64 v[22:23], v[2:3], 0, s[20:21]
	global_load_dwordx4 v[6:9], v[22:23], off offset:560
	global_load_dwordx4 v[10:13], v[22:23], off offset:544
	global_load_dwordx4 v[14:17], v[22:23], off offset:528
	global_load_dwordx4 v[18:21], v[22:23], off offset:512
	s_add_u32 s20, s20, 0x80
	s_addc_u32 s21, s21, 0
	s_cmpk_lg_i32 s20, 0x100
	s_waitcnt vmcnt(0)
	v_lshlrev_b32_e32 v25, 16, v18
	v_and_b32_e32 v27, 0xffff0000, v18
	v_lshlrev_b32_e32 v29, 16, v19
	v_and_b32_e32 v19, 0xffff0000, v19
	v_lshlrev_b32_e32 v31, 16, v20
	v_and_b32_e32 v33, 0xffff0000, v20
	v_lshlrev_b32_e32 v35, 16, v21
	v_and_b32_e32 v21, 0xffff0000, v21
	v_mul_f32_e32 v24, v25, v25
	v_mul_f32_e32 v26, v27, v27
	v_mul_f32_e32 v28, v29, v29
	v_mul_f32_e32 v18, v19, v19
	v_mul_f32_e32 v30, v31, v31
	v_mul_f32_e32 v32, v33, v33
	v_mul_f32_e32 v34, v35, v35
	v_mul_f32_e32 v20, v21, v21
	v_pk_add_f32 v[24:25], v[24:25], v[26:27]
	v_pk_add_f32 v[18:19], v[28:29], v[18:19]
	v_pk_add_f32 v[20:21], v[34:35], v[20:21]
	v_pk_add_f32 v[18:19], v[24:25], v[18:19]
	v_pk_add_f32 v[24:25], v[30:31], v[32:33]
	v_lshlrev_b32_e32 v27, 16, v16
	v_pk_add_f32 v[20:21], v[24:25], v[20:21]
	v_lshlrev_b32_e32 v25, 16, v15
	v_pk_add_f32 v[18:19], v[18:19], v[20:21]
	v_and_b32_e32 v21, 0xffff0000, v14
	v_pk_add_f32 v[4:5], v[4:5], v[18:19]
	v_lshlrev_b32_e32 v19, 16, v14
	v_and_b32_e32 v15, 0xffff0000, v15
	v_and_b32_e32 v29, 0xffff0000, v16
	v_lshlrev_b32_e32 v31, 16, v17
	v_and_b32_e32 v17, 0xffff0000, v17
	v_mul_f32_e32 v18, v19, v19
	v_mul_f32_e32 v20, v21, v21
	v_mul_f32_e32 v24, v25, v25
	v_mul_f32_e32 v14, v15, v15
	v_mul_f32_e32 v26, v27, v27
	v_mul_f32_e32 v28, v29, v29
	v_mul_f32_e32 v30, v31, v31
	v_mul_f32_e32 v16, v17, v17
	v_pk_add_f32 v[18:19], v[18:19], v[20:21]
	v_pk_add_f32 v[14:15], v[24:25], v[14:15]
	v_pk_add_f32 v[16:17], v[30:31], v[16:17]
	v_pk_add_f32 v[14:15], v[18:19], v[14:15]
	v_pk_add_f32 v[18:19], v[26:27], v[28:29]
	v_lshlrev_b32_e32 v21, 16, v12
	v_pk_add_f32 v[16:17], v[18:19], v[16:17]
	v_lshlrev_b32_e32 v19, 16, v11
	v_pk_add_f32 v[14:15], v[14:15], v[16:17]
	v_and_b32_e32 v17, 0xffff0000, v10
	v_pk_add_f32 v[4:5], v[4:5], v[14:15]
	v_lshlrev_b32_e32 v15, 16, v10
	v_and_b32_e32 v11, 0xffff0000, v11
	v_and_b32_e32 v25, 0xffff0000, v12
	v_lshlrev_b32_e32 v27, 16, v13
	v_and_b32_e32 v13, 0xffff0000, v13
	v_mul_f32_e32 v14, v15, v15
	v_mul_f32_e32 v16, v17, v17
	v_mul_f32_e32 v18, v19, v19
	v_mul_f32_e32 v10, v11, v11
	v_mul_f32_e32 v20, v21, v21
	v_mul_f32_e32 v24, v25, v25
	v_mul_f32_e32 v26, v27, v27
	v_mul_f32_e32 v12, v13, v13
	v_pk_add_f32 v[14:15], v[14:15], v[16:17]
	v_pk_add_f32 v[10:11], v[18:19], v[10:11]
	v_pk_add_f32 v[12:13], v[26:27], v[12:13]
	v_pk_add_f32 v[10:11], v[14:15], v[10:11]
	v_pk_add_f32 v[14:15], v[20:21], v[24:25]
	v_lshlrev_b32_e32 v17, 16, v8
	v_pk_add_f32 v[12:13], v[14:15], v[12:13]
	v_lshlrev_b32_e32 v15, 16, v7
	v_pk_add_f32 v[10:11], v[10:11], v[12:13]
	v_and_b32_e32 v13, 0xffff0000, v6
	v_pk_add_f32 v[4:5], v[4:5], v[10:11]
	v_lshlrev_b32_e32 v11, 16, v6
	v_and_b32_e32 v7, 0xffff0000, v7
	v_and_b32_e32 v19, 0xffff0000, v8
	v_lshlrev_b32_e32 v21, 16, v9
	v_and_b32_e32 v9, 0xffff0000, v9
	v_mul_f32_e32 v10, v11, v11
	v_mul_f32_e32 v12, v13, v13
	v_mul_f32_e32 v14, v15, v15
	v_mul_f32_e32 v6, v7, v7
	v_mul_f32_e32 v16, v17, v17
	v_mul_f32_e32 v18, v19, v19
	v_mul_f32_e32 v20, v21, v21
	v_mul_f32_e32 v8, v9, v9
	v_pk_add_f32 v[10:11], v[10:11], v[12:13]
	v_pk_add_f32 v[6:7], v[14:15], v[6:7]
	v_pk_add_f32 v[8:9], v[20:21], v[8:9]
	v_pk_add_f32 v[6:7], v[10:11], v[6:7]
	v_pk_add_f32 v[10:11], v[16:17], v[18:19]
	s_nop 0
	v_pk_add_f32 v[8:9], v[10:11], v[8:9]
	s_nop 0
	v_pk_add_f32 v[6:7], v[6:7], v[8:9]
	s_nop 0
	v_pk_add_f32 v[20:21], v[4:5], v[6:7]
	global_load_dwordx4 v[4:7], v[22:23], off offset:624
	global_load_dwordx4 v[8:11], v[22:23], off offset:608
	global_load_dwordx4 v[12:15], v[22:23], off offset:592
	global_load_dwordx4 v[16:19], v[22:23], off offset:576
	s_waitcnt vmcnt(0)
	v_lshlrev_b32_e32 v23, 16, v16
	v_and_b32_e32 v25, 0xffff0000, v16
	v_lshlrev_b32_e32 v27, 16, v17
	v_and_b32_e32 v17, 0xffff0000, v17
	v_lshlrev_b32_e32 v29, 16, v18
	v_and_b32_e32 v31, 0xffff0000, v18
	v_lshlrev_b32_e32 v33, 16, v19
	v_and_b32_e32 v19, 0xffff0000, v19
	v_mul_f32_e32 v22, v23, v23
	v_mul_f32_e32 v24, v25, v25
	v_mul_f32_e32 v26, v27, v27
	v_mul_f32_e32 v16, v17, v17
	v_mul_f32_e32 v28, v29, v29
	v_mul_f32_e32 v30, v31, v31
	v_mul_f32_e32 v32, v33, v33
	v_mul_f32_e32 v18, v19, v19
	v_pk_add_f32 v[22:23], v[22:23], v[24:25]
	v_pk_add_f32 v[16:17], v[26:27], v[16:17]
	v_pk_add_f32 v[18:19], v[32:33], v[18:19]
	v_pk_add_f32 v[16:17], v[22:23], v[16:17]
	v_pk_add_f32 v[22:23], v[28:29], v[30:31]
	v_lshlrev_b32_e32 v25, 16, v14
	v_pk_add_f32 v[18:19], v[22:23], v[18:19]
	v_lshlrev_b32_e32 v23, 16, v13
	v_pk_add_f32 v[16:17], v[16:17], v[18:19]
	v_lshlrev_b32_e32 v19, 16, v12
	v_pk_add_f32 v[16:17], v[20:21], v[16:17]
	v_and_b32_e32 v21, 0xffff0000, v12
	v_and_b32_e32 v13, 0xffff0000, v13
	v_and_b32_e32 v27, 0xffff0000, v14
	v_lshlrev_b32_e32 v29, 16, v15
	v_and_b32_e32 v15, 0xffff0000, v15
	v_mul_f32_e32 v18, v19, v19
	v_mul_f32_e32 v20, v21, v21
	v_mul_f32_e32 v22, v23, v23
	v_mul_f32_e32 v12, v13, v13
	v_mul_f32_e32 v24, v25, v25
	v_mul_f32_e32 v26, v27, v27
	v_mul_f32_e32 v28, v29, v29
	v_mul_f32_e32 v14, v15, v15
	v_pk_add_f32 v[18:19], v[18:19], v[20:21]
	v_pk_add_f32 v[12:13], v[22:23], v[12:13]
	v_pk_add_f32 v[14:15], v[28:29], v[14:15]
	v_pk_add_f32 v[12:13], v[18:19], v[12:13]
	v_pk_add_f32 v[18:19], v[24:25], v[26:27]
	v_lshlrev_b32_e32 v21, 16, v10
	v_pk_add_f32 v[14:15], v[18:19], v[14:15]
	v_lshlrev_b32_e32 v19, 16, v9
	v_pk_add_f32 v[12:13], v[12:13], v[14:15]
	v_lshlrev_b32_e32 v15, 16, v8
	v_pk_add_f32 v[12:13], v[16:17], v[12:13]
	v_and_b32_e32 v17, 0xffff0000, v8
	v_and_b32_e32 v9, 0xffff0000, v9
	v_and_b32_e32 v23, 0xffff0000, v10
	v_lshlrev_b32_e32 v25, 16, v11
	v_and_b32_e32 v11, 0xffff0000, v11
	v_mul_f32_e32 v14, v15, v15
	v_mul_f32_e32 v16, v17, v17
	v_mul_f32_e32 v18, v19, v19
	v_mul_f32_e32 v8, v9, v9
	v_mul_f32_e32 v20, v21, v21
	v_mul_f32_e32 v22, v23, v23
	v_mul_f32_e32 v24, v25, v25
	v_mul_f32_e32 v10, v11, v11
	v_pk_add_f32 v[14:15], v[14:15], v[16:17]
	v_pk_add_f32 v[8:9], v[18:19], v[8:9]
	v_pk_add_f32 v[10:11], v[24:25], v[10:11]
	v_pk_add_f32 v[8:9], v[14:15], v[8:9]
	v_pk_add_f32 v[14:15], v[20:21], v[22:23]
	v_lshlrev_b32_e32 v17, 16, v6
	v_pk_add_f32 v[10:11], v[14:15], v[10:11]
	v_lshlrev_b32_e32 v15, 16, v5
	v_pk_add_f32 v[8:9], v[8:9], v[10:11]
	v_lshlrev_b32_e32 v11, 16, v4
	v_pk_add_f32 v[8:9], v[12:13], v[8:9]
	v_and_b32_e32 v13, 0xffff0000, v4
	v_and_b32_e32 v5, 0xffff0000, v5
	v_and_b32_e32 v19, 0xffff0000, v6
	v_lshlrev_b32_e32 v21, 16, v7
	v_and_b32_e32 v7, 0xffff0000, v7
	v_mul_f32_e32 v10, v11, v11
	v_mul_f32_e32 v12, v13, v13
	v_mul_f32_e32 v14, v15, v15
	v_mul_f32_e32 v4, v5, v5
	v_mul_f32_e32 v16, v17, v17
	v_mul_f32_e32 v18, v19, v19
	v_mul_f32_e32 v20, v21, v21
	v_mul_f32_e32 v6, v7, v7
	v_pk_add_f32 v[10:11], v[10:11], v[12:13]
	v_pk_add_f32 v[4:5], v[14:15], v[4:5]
	v_pk_add_f32 v[6:7], v[20:21], v[6:7]
	v_pk_add_f32 v[4:5], v[10:11], v[4:5]
	v_pk_add_f32 v[10:11], v[16:17], v[18:19]
	s_nop 0
	v_pk_add_f32 v[6:7], v[10:11], v[6:7]
	s_nop 0
	v_pk_add_f32 v[4:5], v[4:5], v[6:7]
	s_nop 0
	v_pk_add_f32 v[4:5], v[8:9], v[4:5]
	s_cbranch_scc1 .LBB0_636
	s_nop 0
	v_mov_b32_dpp v3, v5 quad_perm:[1,0,3,2] row_mask:0xf bank_mask:0xf bound_ctrl:1
	v_mov_b32_dpp v2, v4 quad_perm:[1,0,3,2] row_mask:0xf bank_mask:0xf bound_ctrl:1
	v_pk_add_f32 v[2:3], v[4:5], v[2:3]
	s_mov_b32 s20, 0x3b800000
	v_pk_mul_f32 v[40:41], v[2:3], s[20:21] op_sel_hi:[1,0]
	s_mov_b32 s3, 0x800000
	v_fma_f32 v2, -v41, v41, v40
	v_max_f32_e32 v2, 0, v2
	v_add_f32_e32 v2, 0x358637bd, v2
	v_cmp_gt_f32_e32 vcc, s3, v2
	v_mul_f32_e32 v3, 0x4b800000, v2
	s_and_b32 s2, s35, 3
	v_cndmask_b32_e32 v2, v2, v3, vcc
	v_rsq_f32_e32 v2, v2
	s_lshl_b32 s36, s2, 7
	v_lshl_add_u64 v[0:1], v[0:1], 0, s[36:37]
	s_lshl_b32 s3, s2, 8
	v_mul_f32_e32 v3, 0x45800000, v2
	v_cndmask_b32_e32 v50, v2, v3, vcc
	v_lshlrev_b32_e32 v2, 6, v36
	v_mov_b32_e32 v3, v117
	v_lshl_add_u64 v[12:13], v[0:1], 0, v[2:3]
	v_readlane_b32 s4, v162, 47
	s_add_u32 s22, s4, s3
	v_readlane_b32 s4, v162, 48
	global_load_dwordx4 v[0:3], v[12:13], off offset:560
	global_load_dwordx4 v[4:7], v[12:13], off offset:544
	global_load_dwordx4 v[8:11], v[12:13], off offset:528
	global_load_dwordx4 v[52:55], v[12:13], off offset:512
	s_addc_u32 s23, s4, 0
	v_readlane_b32 s4, v162, 49
	v_lshlrev_b32_e32 v37, 7, v36
	s_add_u32 s20, s4, s3
	v_readlane_b32 s3, v162, 50
	s_addc_u32 s21, s3, 0
	global_load_dwordx4 v[12:15], v37, s[22:23] offset:48
	global_load_dwordx4 v[20:23], v37, s[22:23] offset:32
	global_load_dwordx4 v[28:31], v37, s[22:23] offset:16
	global_load_dwordx4 v[56:59], v37, s[22:23]
	global_load_dwordx4 v[16:19], v37, s[20:21] offset:48
	global_load_dwordx4 v[24:27], v37, s[20:21] offset:32
	global_load_dwordx4 v[32:35], v37, s[20:21] offset:16
	global_load_dwordx4 v[60:63], v37, s[20:21]
	v_lshlrev_b32_e32 v51, 1, v45
	s_movk_i32 s3, 0x880
	v_lshlrev_b32_e32 v40, 3, v36
	v_readlane_b32 s4, v164, 33
	v_readlane_b32 s8, v164, 37
	v_readlane_b32 s9, v164, 38
	v_lshrrev_b32_e32 v48, 1, v42
	v_lshrrev_b32_e32 v46, 4, v42
	v_ashrrev_i32_e32 v44, 6, v42
	v_bfe_u32 v43, v42, 4, 2
	v_readlane_b32 s10, v164, 39
	v_readlane_b32 s11, v164, 40
	v_readlane_b32 s5, v164, 34
	v_readlane_b32 s6, v164, 35
	v_readlane_b32 s7, v164, 36
	v_readlane_b32 s12, v164, 41
	v_readlane_b32 s13, v164, 42
	v_readlane_b32 s14, v164, 43
	v_readlane_b32 s15, v164, 44
	v_readlane_b32 s16, v164, 45
	v_readlane_b32 s17, v164, 46
	v_readlane_b32 s18, v164, 47
	v_readlane_b32 s19, v164, 48
	s_waitcnt vmcnt(8)
	v_lshlrev_b32_e32 v38, 16, v52
	v_and_b32_e32 v39, 0xffff0000, v52
	v_mad_u32_u24 v52, v36, s3, v51
	v_sub_f32_e32 v36, v38, v41
	v_mul_f32_e32 v36, v36, v50
	v_lshlrev_b32_e32 v47, 16, v53
	v_and_b32_e32 v49, 0xffff0000, v53
	s_waitcnt vmcnt(0)
	v_fma_f32 v36, v56, v36, v60
	v_cvt_pk_bf16_f32 v36, v36, v36
	ds_write_b16_d16_hi v52, v36 offset:32768
	v_sub_f32_e32 v36, v39, v41
	v_mul_f32_e32 v36, v36, v50
	v_fma_f32 v36, v57, v36, v61
	v_cvt_pk_bf16_f32 v36, v36, v36
	ds_write_b16_d16_hi v52, v36 offset:37120
	v_sub_f32_e32 v36, v47, v41
	v_mul_f32_e32 v36, v36, v50
	v_fma_f32 v36, v58, v36, v62
	v_cvt_pk_bf16_f32 v36, v36, v36
	ds_write_b16_d16_hi v52, v36 offset:41472
	v_sub_f32_e32 v36, v49, v41
	v_mul_f32_e32 v36, v36, v50
	v_fmac_f32_e32 v63, v59, v36
	v_cvt_pk_bf16_f32 v36, v63, v63
	ds_write_b16_d16_hi v52, v36 offset:45824
	v_lshlrev_b32_e32 v36, 16, v54
	v_sub_f32_e32 v36, v36, v41
	v_mul_f32_e32 v36, v36, v50
	v_fma_f32 v28, v36, v28, v32
	v_or_b32_e32 v49, 1, v40
	s_movk_i32 s3, 0x110
	v_and_b32_e32 v38, 0xffff0000, v54
	v_mad_u32_u24 v53, v49, s3, v51
	v_cvt_pk_bf16_f32 v28, v28, v28
	ds_write_b16_d16_hi v53, v28 offset:32768
	v_sub_f32_e32 v28, v38, v41
	v_mul_f32_e32 v28, v28, v50
	v_fma_f32 v28, v28, v29, v33
	v_lshlrev_b32_e32 v39, 16, v55
	v_cvt_pk_bf16_f32 v28, v28, v28
	ds_write_b16_d16_hi v53, v28 offset:37120
	v_sub_f32_e32 v28, v39, v41
	v_mul_f32_e32 v28, v28, v50
	v_fma_f32 v28, v28, v30, v34
	v_and_b32_e32 v47, 0xffff0000, v55
	v_cvt_pk_bf16_f32 v28, v28, v28
	ds_write_b16_d16_hi v53, v28 offset:41472
	v_sub_f32_e32 v28, v47, v41
	v_mul_f32_e32 v28, v28, v50
	v_fmac_f32_e32 v35, v28, v31
	v_cvt_pk_bf16_f32 v28, v35, v35
	ds_write_b16_d16_hi v53, v28 offset:45824
	v_lshlrev_b32_e32 v28, 16, v8
	v_sub_f32_e32 v28, v28, v41
	v_and_b32_e32 v8, 0xffff0000, v8
	v_mul_f32_e32 v28, v50, v28
	v_fma_f32 v20, v28, v20, v24
	v_sub_f32_e32 v8, v8, v41
	v_mul_f32_e32 v8, v50, v8
	v_cvt_pk_bf16_f32 v20, v20, v20
	v_fma_f32 v8, v8, v21, v25
	ds_write_b16_d16_hi v53, v20 offset:33040
	v_lshlrev_b32_e32 v29, 16, v9
	v_cvt_pk_bf16_f32 v8, v8, v8
	ds_write_b16_d16_hi v53, v8 offset:37392
	v_sub_f32_e32 v8, v29, v41
	v_mul_f32_e32 v8, v50, v8
	v_fma_f32 v8, v8, v22, v26
	v_and_b32_e32 v9, 0xffff0000, v9
	v_cvt_pk_bf16_f32 v8, v8, v8
	ds_write_b16_d16_hi v53, v8 offset:41744
	v_sub_f32_e32 v8, v9, v41
	v_mul_f32_e32 v8, v50, v8
	v_fmac_f32_e32 v27, v8, v23
	v_cvt_pk_bf16_f32 v8, v27, v27
	ds_write_b16_d16_hi v53, v8 offset:46096
	v_lshlrev_b32_e32 v8, 16, v10
	v_sub_f32_e32 v8, v8, v41
	v_mul_f32_e32 v8, v50, v8
	v_fma_f32 v8, v8, v12, v16
	v_and_b32_e32 v9, 0xffff0000, v10
	v_cvt_pk_bf16_f32 v8, v8, v8
	ds_write_b16_d16_hi v52, v8 offset:33584
	v_sub_f32_e32 v8, v9, v41
	v_mul_f32_e32 v8, v50, v8
	v_fma_f32 v8, v8, v13, v17
	v_lshlrev_b32_e32 v10, 16, v11
	v_cvt_pk_bf16_f32 v8, v8, v8
	ds_write_b16_d16_hi v52, v8 offset:37936
	v_sub_f32_e32 v8, v10, v41
	v_mul_f32_e32 v8, v50, v8
	v_fma_f32 v8, v8, v14, v18
	v_and_b32_e32 v11, 0xffff0000, v11
	v_cvt_pk_bf16_f32 v8, v8, v8
	ds_write_b16_d16_hi v52, v8 offset:42288
	v_sub_f32_e32 v8, v11, v41
	v_mul_f32_e32 v8, v50, v8
	v_fmac_f32_e32 v19, v8, v15
	v_cvt_pk_bf16_f32 v8, v19, v19
	ds_write_b16_d16_hi v52, v8 offset:46640
	global_load_dwordx4 v[8:11], v37, s[22:23] offset:112
	global_load_dwordx4 v[12:15], v37, s[22:23] offset:96
	global_load_dwordx4 v[16:19], v37, s[22:23] offset:80
	global_load_dwordx4 v[32:35], v37, s[22:23] offset:64
	global_load_dwordx4 v[20:23], v37, s[20:21] offset:112
	global_load_dwordx4 v[24:27], v37, s[20:21] offset:96
	global_load_dwordx4 v[28:31], v37, s[20:21] offset:80
	s_nop 0
	global_load_dwordx4 v[36:39], v37, s[20:21] offset:64
	v_lshlrev_b32_e32 v55, 16, v4
	v_sub_f32_e32 v55, v55, v41
	v_mul_f32_e32 v55, v50, v55
	v_or_b32_e32 v47, 4, v40
	v_and_b32_e32 v54, 0xffff0000, v4
	v_lshlrev_b32_e32 v53, 16, v5
	v_and_b32_e32 v4, 0xffff0000, v5
	v_mad_u32_u24 v5, v47, s3, v51
	v_sub_f32_e32 v4, v4, v41
	v_mul_f32_e32 v4, v50, v4
	s_mov_b32 s21, s37
	v_or_b32_e32 v49, 2, v40
	s_waitcnt vmcnt(0)
	v_fma_f32 v32, v55, v32, v36
	v_cvt_pk_bf16_f32 v32, v32, v32
	ds_write_b16_d16_hi v5, v32 offset:32768
	v_sub_f32_e32 v32, v54, v41
	v_mul_f32_e32 v32, v50, v32
	v_fma_f32 v32, v32, v33, v37
	v_fmac_f32_e32 v39, v4, v35
	v_cvt_pk_bf16_f32 v32, v32, v32
	v_cvt_pk_bf16_f32 v4, v39, v39
	ds_write_b16_d16_hi v5, v32 offset:37120
	v_sub_f32_e32 v32, v53, v41
	ds_write_b16_d16_hi v5, v4 offset:45824
	v_lshlrev_b32_e32 v4, 16, v6
	v_mul_f32_e32 v32, v50, v32
	v_sub_f32_e32 v4, v4, v41
	v_fma_f32 v32, v32, v34, v38
	v_mul_f32_e32 v4, v50, v4
	v_fma_f32 v4, v4, v16, v28
	v_cvt_pk_bf16_f32 v32, v32, v32
	ds_write_b16_d16_hi v5, v32 offset:41472
	v_and_b32_e32 v5, 0xffff0000, v6
	v_cvt_pk_bf16_f32 v4, v4, v4
	ds_write_b16_d16_hi v52, v4 offset:34128
	v_sub_f32_e32 v4, v5, v41
	v_mul_f32_e32 v4, v50, v4
	v_fma_f32 v4, v4, v17, v29
	v_lshlrev_b32_e32 v6, 16, v7
	v_cvt_pk_bf16_f32 v4, v4, v4
	ds_write_b16_d16_hi v52, v4 offset:38480
	v_sub_f32_e32 v4, v6, v41
	v_mul_f32_e32 v4, v50, v4
	v_fma_f32 v4, v4, v18, v30
	v_and_b32_e32 v7, 0xffff0000, v7
	v_cvt_pk_bf16_f32 v4, v4, v4
	ds_write_b16_d16_hi v52, v4 offset:42832
	v_sub_f32_e32 v4, v7, v41
	v_mul_f32_e32 v4, v50, v4
	v_lshlrev_b32_e32 v5, 16, v0
	v_fmac_f32_e32 v31, v4, v19
	v_sub_f32_e32 v5, v5, v41
	v_and_b32_e32 v0, 0xffff0000, v0
	v_mul_f32_e32 v5, v50, v5
	v_cvt_pk_bf16_f32 v4, v31, v31
	v_fma_f32 v5, v5, v12, v24
	v_sub_f32_e32 v0, v0, v41
	ds_write_b16_d16_hi v52, v4 offset:47184
	v_or_b32_e32 v4, 6, v40
	v_mul_f32_e32 v0, v50, v0
	v_mad_u32_u24 v7, v4, s3, v51
	v_cvt_pk_bf16_f32 v5, v5, v5
	v_fma_f32 v0, v0, v13, v25
	ds_write_b16_d16_hi v7, v5 offset:32768
	v_lshlrev_b32_e32 v6, 16, v1
	v_cvt_pk_bf16_f32 v0, v0, v0
	ds_write_b16_d16_hi v7, v0 offset:37120
	v_sub_f32_e32 v0, v6, v41
	v_mul_f32_e32 v0, v50, v0
	v_fma_f32 v0, v0, v14, v26
	v_and_b32_e32 v1, 0xffff0000, v1
	v_cvt_pk_bf16_f32 v0, v0, v0
	ds_write_b16_d16_hi v7, v0 offset:41472
	v_sub_f32_e32 v0, v1, v41
	v_mul_f32_e32 v0, v50, v0
	v_fmac_f32_e32 v27, v0, v15
	v_cvt_pk_bf16_f32 v0, v27, v27
	ds_write_b16_d16_hi v7, v0 offset:45824
	v_lshlrev_b32_e32 v0, 16, v2
	v_sub_f32_e32 v0, v0, v41
	v_mul_f32_e32 v0, v50, v0
	v_fma_f32 v0, v0, v8, v20
	v_and_b32_e32 v1, 0xffff0000, v2
	v_cvt_pk_bf16_f32 v0, v0, v0
	ds_write_b16_d16_hi v52, v0 offset:34672
	v_sub_f32_e32 v0, v1, v41
	v_mul_f32_e32 v0, v50, v0
	v_fma_f32 v0, v0, v9, v21
	v_lshlrev_b32_e32 v2, 16, v3
	v_cvt_pk_bf16_f32 v0, v0, v0
	ds_write_b16_d16_hi v52, v0 offset:39024
	v_sub_f32_e32 v0, v2, v41
	v_mul_f32_e32 v0, v50, v0
	v_fma_f32 v0, v0, v10, v22
	v_and_b32_e32 v3, 0xffff0000, v3
	v_cvt_pk_bf16_f32 v0, v0, v0
	ds_write_b16_d16_hi v52, v0 offset:43376
	v_sub_f32_e32 v0, v3, v41
	v_mul_f32_e32 v0, v50, v0
	v_readlane_b32 s3, v162, 45
	v_fmac_f32_e32 v23, v0, v11
	s_or_b32 s2, s2, s3
	s_lshl_b32 s20, s2, 14
	v_cvt_pk_bf16_f32 v0, v23, v23
	s_lshl_b64 s[20:21], s[20:21], 2
	ds_write_b16_d16_hi v52, v0 offset:47728
	s_add_u32 s20, s8, s20
	v_lshlrev_b32_e32 v0, 7, v45
	s_addc_u32 s21, s9, s21
	v_ashrrev_i32_e32 v1, 31, v0
	v_lshl_add_u64 v[0:1], v[0:1], 2, s[20:21]
	v_lshl_add_u64 v[2:3], v[0:1], 0, v[116:117]
	global_load_dwordx4 v[6:9], v[2:3], off offset:48
	global_load_dwordx4 v[10:13], v[2:3], off offset:32
	global_load_dwordx4 v[18:21], v[2:3], off offset:16
	global_load_dwordx4 v[22:25], v[2:3], off
	v_lshlrev_b32_e32 v16, 8, v45
	v_bitop3_b32 v5, v40, v48, 15 bitop3:0x78
	v_lshl_or_b32 v5, v5, 4, v16
	v_bfe_u32 v17, v42, 1, 4
	v_lshlrev_b32_e32 v116, 5, v49
	v_lshlrev_b32_e32 v41, 13, v44
	s_waitcnt vmcnt(0)
	v_cvt_pk_bf16_f32 v14, v25, v25
	v_cvt_pk_bf16_f32 v15, v23, v23
	v_cvt_pk_bf16_f32 v3, v22, v22
	v_cvt_pk_bf16_f32 v2, v24, v24
	v_and_b32_e32 v14, 0xffff0000, v14
	v_and_b32_e32 v15, 0xffff0000, v15
	v_or_b32_sdwa v23, v14, v2 dst_sel:DWORD dst_unused:UNUSED_PAD src0_sel:DWORD src1_sel:WORD_1
	v_or_b32_sdwa v22, v15, v3 dst_sel:DWORD dst_unused:UNUSED_PAD src0_sel:DWORD src1_sel:WORD_1
	v_cvt_pk_bf16_f32 v14, v21, v21
	v_cvt_pk_bf16_f32 v15, v19, v19
	v_cvt_pk_bf16_f32 v3, v18, v18
	v_cvt_pk_bf16_f32 v2, v20, v20
	v_and_b32_e32 v14, 0xffff0000, v14
	v_and_b32_e32 v15, 0xffff0000, v15
	v_or_b32_sdwa v25, v14, v2 dst_sel:DWORD dst_unused:UNUSED_PAD src0_sel:DWORD src1_sel:WORD_1
	v_or_b32_sdwa v24, v15, v3 dst_sel:DWORD dst_unused:UNUSED_PAD src0_sel:DWORD src1_sel:WORD_1
	ds_write_b128 v5, v[22:25]
	v_cvt_pk_bf16_f32 v5, v10, v10
	v_cvt_pk_bf16_f32 v3, v12, v12
	v_cvt_pk_bf16_f32 v10, v13, v13
	v_cvt_pk_bf16_f32 v11, v11, v11
	v_and_b32_e32 v10, 0xffff0000, v10
	v_and_b32_e32 v12, 0xffff0000, v11
	v_or_b32_sdwa v11, v10, v3 dst_sel:DWORD dst_unused:UNUSED_PAD src0_sel:DWORD src1_sel:WORD_1
	v_or_b32_sdwa v10, v12, v5 dst_sel:DWORD dst_unused:UNUSED_PAD src0_sel:DWORD src1_sel:WORD_1
	v_cvt_pk_bf16_f32 v5, v6, v6
	v_cvt_pk_bf16_f32 v3, v8, v8
	v_cvt_pk_bf16_f32 v6, v9, v9
	v_cvt_pk_bf16_f32 v7, v7, v7
	v_bitop3_b32 v2, v40, v17, 1 bitop3:0x36
	v_and_b32_e32 v6, 0xffff0000, v6
	v_and_b32_e32 v7, 0xffff0000, v7
	v_lshl_or_b32 v2, v2, 4, v16
	v_or_b32_sdwa v13, v6, v3 dst_sel:DWORD dst_unused:UNUSED_PAD src0_sel:DWORD src1_sel:WORD_1
	v_or_b32_sdwa v12, v7, v5 dst_sel:DWORD dst_unused:UNUSED_PAD src0_sel:DWORD src1_sel:WORD_1
	ds_write_b128 v2, v[10:13]
	v_lshl_add_u64 v[2:3], v[0:1], 0, v[116:117]
	global_load_dwordx4 v[6:9], v[2:3], off offset:48
	global_load_dwordx4 v[10:13], v[2:3], off offset:32
	global_load_dwordx4 v[18:21], v[2:3], off offset:16
	global_load_dwordx4 v[22:25], v[2:3], off
	v_bitop3_b32 v5, v40, v17, 2 bitop3:0x36
	v_lshl_or_b32 v5, v5, 4, v16
	v_lshlrev_b32_e32 v116, 5, v47
	s_waitcnt vmcnt(0)
	v_cvt_pk_bf16_f32 v14, v25, v25
	v_cvt_pk_bf16_f32 v15, v23, v23
	v_cvt_pk_bf16_f32 v3, v22, v22
	v_cvt_pk_bf16_f32 v2, v24, v24
	v_and_b32_e32 v14, 0xffff0000, v14
	v_and_b32_e32 v15, 0xffff0000, v15
	v_or_b32_sdwa v23, v14, v2 dst_sel:DWORD dst_unused:UNUSED_PAD src0_sel:DWORD src1_sel:WORD_1
	v_or_b32_sdwa v22, v15, v3 dst_sel:DWORD dst_unused:UNUSED_PAD src0_sel:DWORD src1_sel:WORD_1
	v_cvt_pk_bf16_f32 v14, v21, v21
	v_cvt_pk_bf16_f32 v15, v19, v19
	v_cvt_pk_bf16_f32 v3, v18, v18
	v_cvt_pk_bf16_f32 v2, v20, v20
	v_and_b32_e32 v14, 0xffff0000, v14
	v_and_b32_e32 v15, 0xffff0000, v15
	v_or_b32_sdwa v25, v14, v2 dst_sel:DWORD dst_unused:UNUSED_PAD src0_sel:DWORD src1_sel:WORD_1
	v_or_b32_sdwa v24, v15, v3 dst_sel:DWORD dst_unused:UNUSED_PAD src0_sel:DWORD src1_sel:WORD_1
	ds_write_b128 v5, v[22:25]
	v_cvt_pk_bf16_f32 v5, v10, v10
	v_cvt_pk_bf16_f32 v3, v12, v12
	v_cvt_pk_bf16_f32 v10, v13, v13
	v_cvt_pk_bf16_f32 v11, v11, v11
	v_and_b32_e32 v10, 0xffff0000, v10
	v_and_b32_e32 v12, 0xffff0000, v11
	v_or_b32_sdwa v11, v10, v3 dst_sel:DWORD dst_unused:UNUSED_PAD src0_sel:DWORD src1_sel:WORD_1
	v_or_b32_sdwa v10, v12, v5 dst_sel:DWORD dst_unused:UNUSED_PAD src0_sel:DWORD src1_sel:WORD_1
	v_cvt_pk_bf16_f32 v5, v6, v6
	v_cvt_pk_bf16_f32 v3, v8, v8
	v_cvt_pk_bf16_f32 v6, v9, v9
	v_cvt_pk_bf16_f32 v7, v7, v7
	v_bitop3_b32 v2, v40, v17, 3 bitop3:0x36
	v_and_b32_e32 v6, 0xffff0000, v6
	v_and_b32_e32 v7, 0xffff0000, v7
	v_lshl_or_b32 v2, v2, 4, v16
	v_or_b32_sdwa v13, v6, v3 dst_sel:DWORD dst_unused:UNUSED_PAD src0_sel:DWORD src1_sel:WORD_1
	v_or_b32_sdwa v12, v7, v5 dst_sel:DWORD dst_unused:UNUSED_PAD src0_sel:DWORD src1_sel:WORD_1
	ds_write_b128 v2, v[10:13]
	v_lshl_add_u64 v[2:3], v[0:1], 0, v[116:117]
	global_load_dwordx4 v[6:9], v[2:3], off offset:48
	global_load_dwordx4 v[10:13], v[2:3], off offset:32
	global_load_dwordx4 v[18:21], v[2:3], off offset:16
	global_load_dwordx4 v[22:25], v[2:3], off
	v_bitop3_b32 v5, v40, v17, 4 bitop3:0x36
	v_lshl_or_b32 v5, v5, 4, v16
	v_lshlrev_b32_e32 v116, 5, v4
	s_waitcnt vmcnt(0)
	v_cvt_pk_bf16_f32 v14, v25, v25
	v_cvt_pk_bf16_f32 v15, v23, v23
	v_cvt_pk_bf16_f32 v3, v22, v22
	v_cvt_pk_bf16_f32 v2, v24, v24
	v_and_b32_e32 v14, 0xffff0000, v14
	v_and_b32_e32 v15, 0xffff0000, v15
	v_or_b32_sdwa v23, v14, v2 dst_sel:DWORD dst_unused:UNUSED_PAD src0_sel:DWORD src1_sel:WORD_1
	v_or_b32_sdwa v22, v15, v3 dst_sel:DWORD dst_unused:UNUSED_PAD src0_sel:DWORD src1_sel:WORD_1
	v_cvt_pk_bf16_f32 v14, v21, v21
	v_cvt_pk_bf16_f32 v15, v19, v19
	v_cvt_pk_bf16_f32 v3, v18, v18
	v_cvt_pk_bf16_f32 v2, v20, v20
	v_and_b32_e32 v14, 0xffff0000, v14
	v_and_b32_e32 v15, 0xffff0000, v15
	v_or_b32_sdwa v25, v14, v2 dst_sel:DWORD dst_unused:UNUSED_PAD src0_sel:DWORD src1_sel:WORD_1
	v_or_b32_sdwa v24, v15, v3 dst_sel:DWORD dst_unused:UNUSED_PAD src0_sel:DWORD src1_sel:WORD_1
	ds_write_b128 v5, v[22:25]
	v_cvt_pk_bf16_f32 v5, v10, v10
	v_cvt_pk_bf16_f32 v3, v12, v12
	v_cvt_pk_bf16_f32 v10, v13, v13
	v_cvt_pk_bf16_f32 v11, v11, v11
	v_and_b32_e32 v10, 0xffff0000, v10
	v_and_b32_e32 v12, 0xffff0000, v11
	v_or_b32_sdwa v11, v10, v3 dst_sel:DWORD dst_unused:UNUSED_PAD src0_sel:DWORD src1_sel:WORD_1
	v_or_b32_sdwa v10, v12, v5 dst_sel:DWORD dst_unused:UNUSED_PAD src0_sel:DWORD src1_sel:WORD_1
	v_cvt_pk_bf16_f32 v5, v6, v6
	v_cvt_pk_bf16_f32 v3, v8, v8
	v_cvt_pk_bf16_f32 v6, v9, v9
	v_cvt_pk_bf16_f32 v7, v7, v7
	v_bitop3_b32 v2, v40, v17, 5 bitop3:0x36
	v_and_b32_e32 v6, 0xffff0000, v6
	v_and_b32_e32 v7, 0xffff0000, v7
	v_lshl_or_b32 v2, v2, 4, v16
	v_or_b32_sdwa v13, v6, v3 dst_sel:DWORD dst_unused:UNUSED_PAD src0_sel:DWORD src1_sel:WORD_1
	v_or_b32_sdwa v12, v7, v5 dst_sel:DWORD dst_unused:UNUSED_PAD src0_sel:DWORD src1_sel:WORD_1
	ds_write_b128 v2, v[10:13]
	v_lshl_add_u64 v[12:13], v[0:1], 0, v[116:117]
	v_bitop3_b32 v0, v40, v17, 6 bitop3:0x36
	v_lshl_or_b32 v18, v0, 4, v16
	global_load_dwordx4 v[0:3], v[12:13], off offset:48
	global_load_dwordx4 v[4:7], v[12:13], off offset:32
	global_load_dwordx4 v[8:11], v[12:13], off offset:16
	s_nop 0
	global_load_dwordx4 v[12:15], v[12:13], off
	s_waitcnt vmcnt(0)
	v_cvt_pk_bf16_f32 v14, v14, v14
	v_cvt_pk_bf16_f32 v12, v12, v12
	v_cvt_pk_bf16_f32 v15, v15, v15
	v_cvt_pk_bf16_f32 v13, v13, v13
	v_and_b32_e32 v15, 0xffff0000, v15
	v_and_b32_e32 v19, 0xffff0000, v13
	v_or_b32_sdwa v13, v15, v14 dst_sel:DWORD dst_unused:UNUSED_PAD src0_sel:DWORD src1_sel:WORD_1
	v_cvt_pk_bf16_f32 v8, v8, v8
	v_cvt_pk_bf16_f32 v10, v10, v10
	v_cvt_pk_bf16_f32 v9, v9, v9
	v_cvt_pk_bf16_f32 v11, v11, v11
	v_and_b32_e32 v9, 0xffff0000, v9
	v_and_b32_e32 v11, 0xffff0000, v11
	v_or_b32_sdwa v14, v9, v8 dst_sel:DWORD dst_unused:UNUSED_PAD src0_sel:DWORD src1_sel:WORD_1
	v_or_b32_sdwa v15, v11, v10 dst_sel:DWORD dst_unused:UNUSED_PAD src0_sel:DWORD src1_sel:WORD_1
	v_cvt_pk_bf16_f32 v6, v6, v6
	v_cvt_pk_bf16_f32 v4, v4, v4
	v_cvt_pk_bf16_f32 v7, v7, v7
	v_cvt_pk_bf16_f32 v5, v5, v5
	v_and_b32_e32 v7, 0xffff0000, v7
	v_and_b32_e32 v9, 0xffff0000, v5
	v_or_b32_sdwa v5, v7, v6 dst_sel:DWORD dst_unused:UNUSED_PAD src0_sel:DWORD src1_sel:WORD_1
	v_cvt_pk_bf16_f32 v0, v0, v0
	v_cvt_pk_bf16_f32 v2, v2, v2
	v_cvt_pk_bf16_f32 v3, v3, v3
	v_cvt_pk_bf16_f32 v1, v1, v1
	v_bitop3_b32 v8, v40, v17, 7 bitop3:0x36
	v_and_b32_e32 v3, 0xffff0000, v3
	v_and_b32_e32 v1, 0xffff0000, v1
	v_and_b32_e32 v40, 15, v42
	v_lshl_or_b32 v8, v8, 4, v16
	v_or_b32_sdwa v4, v9, v4 dst_sel:DWORD dst_unused:UNUSED_PAD src0_sel:DWORD src1_sel:WORD_1
	v_or_b32_sdwa v7, v3, v2 dst_sel:DWORD dst_unused:UNUSED_PAD src0_sel:DWORD src1_sel:WORD_1
	v_or_b32_sdwa v6, v1, v0 dst_sel:DWORD dst_unused:UNUSED_PAD src0_sel:DWORD src1_sel:WORD_1
	v_bitop3_b32 v0, v46, v40, 3 bitop3:0x6c
	ds_write_b128 v8, v[4:7]
	v_lshlrev_b32_e32 v0, 4, v0
	v_lshlrev_b32_e32 v42, 8, v40
	v_mul_u32_u24_e32 v8, 0x110, v40
	v_or_b32_sdwa v12, v19, v12 dst_sel:DWORD dst_unused:UNUSED_PAD src0_sel:DWORD src1_sel:WORD_1
	v_or3_b32 v4, v0, v41, v42
	v_lshl_add_u32 v45, v43, 4, v8
	ds_write_b128 v18, v[12:15]
	s_waitcnt lgkmcnt(0)
	s_barrier
	ds_read_b128 v[0:3], v4
	ds_read_b128 v[4:7], v4 offset:4096
	ds_read_b128 v[8:11], v45 offset:32768
	ds_read_b128 v[12:15], v45 offset:37120
	ds_read_b128 v[16:19], v45 offset:41472
	ds_read_b128 v[20:23], v45 offset:45824
	s_waitcnt lgkmcnt(3)
	v_mfma_f32_16x16x32_bf16 v[24:27], v[0:3], v[8:11], 0
	v_lshlrev_b32_e32 v116, 3, v40
	s_waitcnt lgkmcnt(2)
	v_mfma_f32_16x16x32_bf16 v[28:31], v[0:3], v[12:15], 0
	s_waitcnt lgkmcnt(1)
	v_mfma_f32_16x16x32_bf16 v[32:35], v[0:3], v[16:19], 0
	s_waitcnt lgkmcnt(0)
	v_mfma_f32_16x16x32_bf16 v[0:3], v[0:3], v[20:23], 0
	v_mfma_f32_16x16x32_bf16 v[8:11], v[4:7], v[8:11], 0
	v_mfma_f32_16x16x32_bf16 v[12:15], v[4:7], v[12:15], 0
	v_mfma_f32_16x16x32_bf16 v[16:19], v[4:7], v[16:19], 0
	v_mfma_f32_16x16x32_bf16 v[4:7], v[4:7], v[20:23], 0
	v_bitop3_b32 v20, v43, v40, 4 bitop3:0x36
	v_lshlrev_b32_e32 v20, 4, v20
	v_or3_b32 v36, v20, v41, v42
	ds_read_b128 v[20:23], v36
	ds_read_b128 v[36:39], v36 offset:4096
	ds_read_b128 v[46:49], v45 offset:32832
	ds_read_b128 v[50:53], v45 offset:37184
	ds_read_b128 v[54:57], v45 offset:41536
	ds_read_b128 v[58:61], v45 offset:45888
	s_waitcnt lgkmcnt(3)
	v_mfma_f32_16x16x32_bf16 v[24:27], v[20:23], v[46:49], v[24:27]
	s_waitcnt lgkmcnt(2)
	v_mfma_f32_16x16x32_bf16 v[28:31], v[20:23], v[50:53], v[28:31]
	s_waitcnt lgkmcnt(1)
	v_mfma_f32_16x16x32_bf16 v[32:35], v[20:23], v[54:57], v[32:35]
	s_waitcnt lgkmcnt(0)
	v_mfma_f32_16x16x32_bf16 v[0:3], v[20:23], v[58:61], v[0:3]
	v_bitop3_b32 v20, v43, v40, 8 bitop3:0x36
	v_lshlrev_b32_e32 v20, 4, v20
	v_mfma_f32_16x16x32_bf16 v[8:11], v[36:39], v[46:49], v[8:11]
	v_mfma_f32_16x16x32_bf16 v[12:15], v[36:39], v[50:53], v[12:15]
	v_mfma_f32_16x16x32_bf16 v[16:19], v[36:39], v[54:57], v[16:19]
	v_mfma_f32_16x16x32_bf16 v[4:7], v[36:39], v[58:61], v[4:7]
	v_or3_b32 v36, v20, v41, v42
	ds_read_b128 v[20:23], v36
	ds_read_b128 v[36:39], v36 offset:4096
	ds_read_b128 v[46:49], v45 offset:32896
	ds_read_b128 v[50:53], v45 offset:37248
	ds_read_b128 v[54:57], v45 offset:41600
	ds_read_b128 v[58:61], v45 offset:45952
	s_waitcnt lgkmcnt(3)
	v_mfma_f32_16x16x32_bf16 v[24:27], v[20:23], v[46:49], v[24:27]
	v_mfma_f32_16x16x32_bf16 v[8:11], v[36:39], v[46:49], v[8:11]
	s_waitcnt lgkmcnt(2)
	v_mfma_f32_16x16x32_bf16 v[46:49], v[36:39], v[50:53], v[12:15]
	s_nop 2
	v_bitop3_b32 v12, v43, v40, 12 bitop3:0x36
	v_lshlrev_b32_e32 v12, 4, v12
	v_mfma_f32_16x16x32_bf16 v[62:65], v[20:23], v[50:53], v[28:31]
	s_waitcnt lgkmcnt(1)
	v_mfma_f32_16x16x32_bf16 v[50:53], v[36:39], v[54:57], v[16:19]
	s_nop 2
	v_or3_b32 v16, v12, v41, v42
	v_mfma_f32_16x16x32_bf16 v[32:35], v[20:23], v[54:57], v[32:35]
	s_waitcnt lgkmcnt(0)
	v_mfma_f32_16x16x32_bf16 v[0:3], v[20:23], v[58:61], v[0:3]
	v_mfma_f32_16x16x32_bf16 v[4:7], v[36:39], v[58:61], v[4:7]
	ds_read_b128 v[12:15], v16
	ds_read_b128 v[36:39], v16 offset:4096
	ds_read_b128 v[54:57], v45 offset:32960
	ds_read_b128 v[58:61], v45 offset:37312
	ds_read_b128 v[66:69], v45 offset:41664
	ds_read_b128 v[70:73], v45 offset:46016
	s_waitcnt lgkmcnt(3)
	v_mfma_f32_16x16x32_bf16 v[28:31], v[12:15], v[54:57], v[24:27]
	s_waitcnt lgkmcnt(1)
	v_mfma_f32_16x16x32_bf16 v[24:27], v[12:15], v[66:69], v[32:35]
	s_nop 2
	v_lshlrev_b32_e32 v32, 5, v44
	v_lshl_or_b32 v34, v43, 2, v32
	v_lshl_add_u32 v32, s2, 7, v34
	v_add_u32_e32 v34, s24, v34
	v_ashrrev_i32_e32 v35, 31, v34
	v_mfma_f32_16x16x32_bf16 v[16:19], v[12:15], v[58:61], v[62:65]
	v_ashrrev_i32_e32 v33, 31, v32
	v_lshl_add_u64 v[32:33], v[32:33], 2, s[10:11]
	v_mov_b32_e32 v44, v28
	s_waitcnt lgkmcnt(0)
	v_mfma_f32_16x16x32_bf16 v[20:23], v[12:15], v[70:73], v[0:3]
	v_mov_b32_e32 v45, v24
	v_lshlrev_b64 v[40:41], 11, v[34:35]
	v_lshl_add_u64 v[40:41], s[80:81], 0, v[40:41]
	v_mfma_f32_16x16x32_bf16 v[12:15], v[36:39], v[54:57], v[8:11]
	v_lshl_add_u64 v[40:41], v[40:41], 0, s[36:37]
	v_lshl_add_u64 v[40:41], v[40:41], 0, v[116:117]
	v_mfma_f32_16x16x32_bf16 v[0:3], v[36:39], v[58:61], v[46:49]
	v_mfma_f32_16x16x32_bf16 v[8:11], v[36:39], v[66:69], v[50:53]
	v_mfma_f32_16x16x32_bf16 v[4:7], v[36:39], v[70:73], v[4:7]
	v_lshlrev_b64 v[38:39], 10, v[34:35]
	v_lshl_add_u64 v[38:39], s[70:71], 0, v[38:39]
	v_lshl_add_u64 v[38:39], v[38:39], 0, s[36:37]
	v_lshl_add_u64 v[38:39], v[38:39], 0, v[116:117]
	global_load_dword v36, v[32:33], off
	s_waitcnt vmcnt(0)
	v_pk_add_f32 v[44:45], v[44:45], v[36:37] op_sel_hi:[1,0]
	global_load_dwordx2 v[38:39], v[38:39], off
	s_waitcnt vmcnt(0)
	v_lshlrev_b32_e32 v43, 16, v39
	v_lshlrev_b32_e32 v42, 16, v38
	v_pk_mul_f32 v[42:43], v[44:45], v[42:43]
	v_mov_b32_e32 v44, v16
	v_mov_b32_e32 v45, v20
	v_and_b32_e32 v39, 0xffff0000, v39
	v_and_b32_e32 v38, 0xffff0000, v38
	v_pk_add_f32 v[36:37], v[44:45], v[36:37] op_sel_hi:[1,0]
	v_pk_mul_f32 v[36:37], v[36:37], v[38:39]
	v_cvt_pk_bf16_f32 v24, v37, v37
	v_cvt_pk_bf16_f32 v28, v36, v36
	v_cvt_pk_bf16_f32 v20, v42, v42
	v_cvt_pk_bf16_f32 v16, v43, v43
	v_and_b32_e32 v24, 0xffff0000, v24
	v_and_b32_e32 v28, 0xffff0000, v28
	v_or_b32_sdwa v37, v24, v16 dst_sel:DWORD dst_unused:UNUSED_PAD src0_sel:DWORD src1_sel:WORD_1
	v_or_b32_sdwa v36, v28, v20 dst_sel:DWORD dst_unused:UNUSED_PAD src0_sel:DWORD src1_sel:WORD_1
	global_store_dwordx2 v[40:41], v[36:37], off offset:1024
	v_add_u32_e32 v36, 1, v34
	v_ashrrev_i32_e32 v37, 31, v36
	v_lshlrev_b64 v[38:39], 10, v[36:37]
	v_lshl_add_u64 v[38:39], s[70:71], 0, v[38:39]
	v_lshl_add_u64 v[38:39], v[38:39], 0, s[36:37]
	v_lshl_add_u64 v[38:39], v[38:39], 0, v[116:117]
	global_load_dword v16, v[32:33], off offset:4
	v_mov_b32_e32 v24, v29
	global_load_dwordx2 v[38:39], v[38:39], off
	v_mov_b32_e32 v20, v17
	v_lshlrev_b64 v[36:37], 11, v[36:37]
	v_lshl_add_u64 v[36:37], s[80:81], 0, v[36:37]
	v_lshl_add_u64 v[36:37], v[36:37], 0, s[36:37]
	v_lshl_add_u64 v[36:37], v[36:37], 0, v[116:117]
	s_waitcnt vmcnt(1)
	v_pk_add_f32 v[24:25], v[24:25], v[16:17] op_sel_hi:[1,0]
	v_pk_add_f32 v[16:17], v[20:21], v[16:17] op_sel_hi:[1,0]
	s_waitcnt vmcnt(0)
	v_lshlrev_b32_e32 v41, 16, v39
	v_lshlrev_b32_e32 v40, 16, v38
	v_and_b32_e32 v39, 0xffff0000, v39
	v_and_b32_e32 v38, 0xffff0000, v38
	v_pk_mul_f32 v[24:25], v[24:25], v[40:41]
	v_pk_mul_f32 v[16:17], v[16:17], v[38:39]
	v_cvt_pk_bf16_f32 v21, v24, v24
	v_cvt_pk_bf16_f32 v20, v25, v25
	v_cvt_pk_bf16_f32 v17, v17, v17
	v_cvt_pk_bf16_f32 v16, v16, v16
	v_and_b32_e32 v17, 0xffff0000, v17
	v_and_b32_e32 v16, 0xffff0000, v16
	v_or_b32_sdwa v17, v17, v20 dst_sel:DWORD dst_unused:UNUSED_PAD src0_sel:DWORD src1_sel:WORD_1
	v_add_u32_e32 v20, 2, v34
	v_or_b32_sdwa v16, v16, v21 dst_sel:DWORD dst_unused:UNUSED_PAD src0_sel:DWORD src1_sel:WORD_1
	v_ashrrev_i32_e32 v21, 31, v20
	v_lshlrev_b64 v[24:25], 10, v[20:21]
	v_lshl_add_u64 v[24:25], s[70:71], 0, v[24:25]
	v_lshl_add_u64 v[24:25], v[24:25], 0, s[36:37]
	global_store_dwordx2 v[36:37], v[16:17], off offset:1024
	v_lshl_add_u64 v[24:25], v[24:25], 0, v[116:117]
	global_load_dword v16, v[32:33], off offset:8
	v_mov_b32_e32 v36, v30
	global_load_dwordx2 v[24:25], v[24:25], off
	v_mov_b32_e32 v37, v26
	v_lshlrev_b64 v[20:21], 11, v[20:21]
	v_lshl_add_u64 v[20:21], s[80:81], 0, v[20:21]
	v_lshl_add_u64 v[20:21], v[20:21], 0, s[36:37]
	v_lshl_add_u64 v[20:21], v[20:21], 0, v[116:117]
	v_mov_b32_e32 v26, v31
	s_waitcnt vmcnt(1)
	v_pk_add_f32 v[36:37], v[36:37], v[16:17] op_sel_hi:[1,0]
	s_waitcnt vmcnt(0)
	v_lshlrev_b32_e32 v29, 16, v25
	v_lshlrev_b32_e32 v28, 16, v24
	v_pk_mul_f32 v[28:29], v[36:37], v[28:29]
	v_mov_b32_e32 v36, v18
	v_mov_b32_e32 v37, v22
	v_and_b32_e32 v25, 0xffff0000, v25
	v_and_b32_e32 v24, 0xffff0000, v24
	v_pk_add_f32 v[16:17], v[36:37], v[16:17] op_sel_hi:[1,0]
	v_pk_mul_f32 v[16:17], v[16:17], v[24:25]
	v_cvt_pk_bf16_f32 v17, v17, v17
	v_cvt_pk_bf16_f32 v16, v16, v16
	v_cvt_pk_bf16_f32 v22, v28, v28
	v_cvt_pk_bf16_f32 v18, v29, v29
	v_and_b32_e32 v17, 0xffff0000, v17
	v_and_b32_e32 v16, 0xffff0000, v16
	v_or_b32_sdwa v17, v17, v18 dst_sel:DWORD dst_unused:UNUSED_PAD src0_sel:DWORD src1_sel:WORD_1
	v_or_b32_sdwa v16, v16, v22 dst_sel:DWORD dst_unused:UNUSED_PAD src0_sel:DWORD src1_sel:WORD_1
	global_store_dwordx2 v[20:21], v[16:17], off offset:1024
	v_add_u32_e32 v20, 3, v34
	v_ashrrev_i32_e32 v21, 31, v20
	v_lshlrev_b64 v[24:25], 10, v[20:21]
	v_lshl_add_u64 v[24:25], s[70:71], 0, v[24:25]
	v_lshl_add_u64 v[24:25], v[24:25], 0, s[36:37]
	v_lshl_add_u64 v[24:25], v[24:25], 0, v[116:117]
	global_load_dword v16, v[32:33], off offset:12
	v_mov_b32_e32 v22, v19
	global_load_dwordx2 v[24:25], v[24:25], off
	v_lshlrev_b64 v[20:21], 11, v[20:21]
	v_lshl_add_u64 v[20:21], s[80:81], 0, v[20:21]
	v_lshl_add_u64 v[20:21], v[20:21], 0, s[36:37]
	v_lshl_add_u64 v[20:21], v[20:21], 0, v[116:117]
	s_waitcnt vmcnt(1)
	v_pk_add_f32 v[26:27], v[26:27], v[16:17] op_sel_hi:[1,0]
	v_pk_add_f32 v[16:17], v[22:23], v[16:17] op_sel_hi:[1,0]
	s_waitcnt vmcnt(0)
	v_lshlrev_b32_e32 v29, 16, v25
	v_lshlrev_b32_e32 v28, 16, v24
	v_and_b32_e32 v25, 0xffff0000, v25
	v_and_b32_e32 v24, 0xffff0000, v24
	v_pk_mul_f32 v[16:17], v[16:17], v[24:25]
	v_pk_mul_f32 v[26:27], v[26:27], v[28:29]
	v_cvt_pk_bf16_f32 v17, v17, v17
	v_cvt_pk_bf16_f32 v18, v27, v27
	v_cvt_pk_bf16_f32 v16, v16, v16
	v_and_b32_e32 v17, 0xffff0000, v17
	v_cvt_pk_bf16_f32 v19, v26, v26
	v_and_b32_e32 v16, 0xffff0000, v16
	v_or_b32_sdwa v17, v17, v18 dst_sel:DWORD dst_unused:UNUSED_PAD src0_sel:DWORD src1_sel:WORD_1
	v_add_u32_e32 v18, 16, v34
	v_or_b32_sdwa v16, v16, v19 dst_sel:DWORD dst_unused:UNUSED_PAD src0_sel:DWORD src1_sel:WORD_1
	v_ashrrev_i32_e32 v19, 31, v18
	global_store_dwordx2 v[20:21], v[16:17], off offset:1024
	v_lshlrev_b64 v[20:21], 10, v[18:19]
	v_lshl_add_u64 v[20:21], s[70:71], 0, v[20:21]
	v_lshl_add_u64 v[20:21], v[20:21], 0, s[36:37]
	v_lshl_add_u64 v[20:21], v[20:21], 0, v[116:117]
	global_load_dword v16, v[32:33], off offset:64
	v_mov_b32_e32 v24, v12
	global_load_dwordx2 v[20:21], v[20:21], off
	v_mov_b32_e32 v25, v8
	v_lshlrev_b64 v[18:19], 11, v[18:19]
	v_lshl_add_u64 v[18:19], s[80:81], 0, v[18:19]
	v_lshl_add_u64 v[18:19], v[18:19], 0, s[36:37]
	v_lshl_add_u64 v[18:19], v[18:19], 0, v[116:117]
	s_waitcnt vmcnt(1)
	v_pk_add_f32 v[24:25], v[24:25], v[16:17] op_sel_hi:[1,0]
	s_waitcnt vmcnt(0)
	v_lshlrev_b32_e32 v23, 16, v21
	v_lshlrev_b32_e32 v22, 16, v20
	v_pk_mul_f32 v[22:23], v[24:25], v[22:23]
	v_mov_b32_e32 v24, v0
	v_mov_b32_e32 v25, v4
	v_and_b32_e32 v21, 0xffff0000, v21
	v_and_b32_e32 v20, 0xffff0000, v20
	v_pk_add_f32 v[16:17], v[24:25], v[16:17] op_sel_hi:[1,0]
	v_pk_mul_f32 v[16:17], v[16:17], v[20:21]
	v_cvt_pk_bf16_f32 v8, v17, v17
	v_cvt_pk_bf16_f32 v12, v16, v16
	v_cvt_pk_bf16_f32 v4, v22, v22
	v_cvt_pk_bf16_f32 v0, v23, v23
	v_and_b32_e32 v8, 0xffff0000, v8
	v_and_b32_e32 v12, 0xffff0000, v12
	v_or_b32_sdwa v17, v8, v0 dst_sel:DWORD dst_unused:UNUSED_PAD src0_sel:DWORD src1_sel:WORD_1
	v_or_b32_sdwa v16, v12, v4 dst_sel:DWORD dst_unused:UNUSED_PAD src0_sel:DWORD src1_sel:WORD_1
	global_store_dwordx2 v[18:19], v[16:17], off offset:1024
	v_add_u32_e32 v16, 17, v34
	v_ashrrev_i32_e32 v17, 31, v16
	v_lshlrev_b64 v[18:19], 10, v[16:17]
	v_lshl_add_u64 v[18:19], s[70:71], 0, v[18:19]
	v_lshl_add_u64 v[18:19], v[18:19], 0, s[36:37]
	v_lshl_add_u64 v[18:19], v[18:19], 0, v[116:117]
	global_load_dword v0, v[32:33], off offset:68
	v_mov_b32_e32 v8, v13
	global_load_dwordx2 v[18:19], v[18:19], off
	v_mov_b32_e32 v4, v1
	v_lshlrev_b64 v[16:17], 11, v[16:17]
	v_lshl_add_u64 v[16:17], s[80:81], 0, v[16:17]
	v_lshl_add_u64 v[16:17], v[16:17], 0, s[36:37]
	v_lshl_add_u64 v[16:17], v[16:17], 0, v[116:117]
	s_waitcnt vmcnt(1)
	v_pk_add_f32 v[8:9], v[8:9], v[0:1] op_sel_hi:[1,0]
	v_pk_add_f32 v[0:1], v[4:5], v[0:1] op_sel_hi:[1,0]
	s_waitcnt vmcnt(0)
	v_lshlrev_b32_e32 v21, 16, v19
	v_lshlrev_b32_e32 v20, 16, v18
	v_and_b32_e32 v19, 0xffff0000, v19
	v_and_b32_e32 v18, 0xffff0000, v18
	v_pk_mul_f32 v[8:9], v[8:9], v[20:21]
	v_pk_mul_f32 v[0:1], v[0:1], v[18:19]
	v_cvt_pk_bf16_f32 v5, v8, v8
	v_cvt_pk_bf16_f32 v4, v9, v9
	v_cvt_pk_bf16_f32 v1, v1, v1
	v_cvt_pk_bf16_f32 v0, v0, v0
	v_and_b32_e32 v1, 0xffff0000, v1
	v_and_b32_e32 v0, 0xffff0000, v0
	v_or_b32_sdwa v1, v1, v4 dst_sel:DWORD dst_unused:UNUSED_PAD src0_sel:DWORD src1_sel:WORD_1
	v_add_u32_e32 v4, 18, v34
	v_or_b32_sdwa v0, v0, v5 dst_sel:DWORD dst_unused:UNUSED_PAD src0_sel:DWORD src1_sel:WORD_1
	v_ashrrev_i32_e32 v5, 31, v4
	v_lshlrev_b64 v[8:9], 10, v[4:5]
	v_lshl_add_u64 v[8:9], s[70:71], 0, v[8:9]
	v_lshl_add_u64 v[8:9], v[8:9], 0, s[36:37]
	global_store_dwordx2 v[16:17], v[0:1], off offset:1024
	v_lshl_add_u64 v[8:9], v[8:9], 0, v[116:117]
	global_load_dword v0, v[32:33], off offset:72
	v_mov_b32_e32 v16, v14
	global_load_dwordx2 v[8:9], v[8:9], off
	v_mov_b32_e32 v17, v10
	v_lshlrev_b64 v[4:5], 11, v[4:5]
	v_lshl_add_u64 v[4:5], s[80:81], 0, v[4:5]
	v_lshl_add_u64 v[4:5], v[4:5], 0, s[36:37]
	v_lshl_add_u64 v[4:5], v[4:5], 0, v[116:117]
	v_mov_b32_e32 v10, v15
	s_waitcnt vmcnt(1)
	v_pk_add_f32 v[16:17], v[16:17], v[0:1] op_sel_hi:[1,0]
	s_waitcnt vmcnt(0)
	v_lshlrev_b32_e32 v13, 16, v9
	v_lshlrev_b32_e32 v12, 16, v8
	v_pk_mul_f32 v[12:13], v[16:17], v[12:13]
	v_mov_b32_e32 v16, v2
	v_mov_b32_e32 v17, v6
	v_and_b32_e32 v9, 0xffff0000, v9
	v_and_b32_e32 v8, 0xffff0000, v8
	v_pk_add_f32 v[0:1], v[16:17], v[0:1] op_sel_hi:[1,0]
	v_pk_mul_f32 v[0:1], v[0:1], v[8:9]
	v_cvt_pk_bf16_f32 v1, v1, v1
	v_cvt_pk_bf16_f32 v0, v0, v0
	v_cvt_pk_bf16_f32 v6, v12, v12
	v_cvt_pk_bf16_f32 v2, v13, v13
	v_and_b32_e32 v1, 0xffff0000, v1
	v_and_b32_e32 v0, 0xffff0000, v0
	v_or_b32_sdwa v1, v1, v2 dst_sel:DWORD dst_unused:UNUSED_PAD src0_sel:DWORD src1_sel:WORD_1
	v_or_b32_sdwa v0, v0, v6 dst_sel:DWORD dst_unused:UNUSED_PAD src0_sel:DWORD src1_sel:WORD_1
	global_store_dwordx2 v[4:5], v[0:1], off offset:1024
	v_add_u32_e32 v4, 19, v34
	v_ashrrev_i32_e32 v5, 31, v4
	v_lshlrev_b64 v[8:9], 10, v[4:5]
	v_lshl_add_u64 v[8:9], s[70:71], 0, v[8:9]
	v_lshl_add_u64 v[8:9], v[8:9], 0, s[36:37]
	v_lshl_add_u64 v[8:9], v[8:9], 0, v[116:117]
	global_load_dword v0, v[32:33], off offset:76
	v_mov_b32_e32 v6, v3
	global_load_dwordx2 v[8:9], v[8:9], off
	v_lshlrev_b64 v[4:5], 11, v[4:5]
	v_lshl_add_u64 v[4:5], s[80:81], 0, v[4:5]
	v_lshl_add_u64 v[4:5], v[4:5], 0, s[36:37]
	v_lshl_add_u64 v[4:5], v[4:5], 0, v[116:117]
	s_waitcnt vmcnt(1)
	v_pk_add_f32 v[10:11], v[10:11], v[0:1] op_sel_hi:[1,0]
	v_pk_add_f32 v[0:1], v[6:7], v[0:1] op_sel_hi:[1,0]
	s_waitcnt vmcnt(0)
	v_lshlrev_b32_e32 v13, 16, v9
	v_lshlrev_b32_e32 v12, 16, v8
	v_and_b32_e32 v9, 0xffff0000, v9
	v_and_b32_e32 v8, 0xffff0000, v8
	v_pk_mul_f32 v[0:1], v[0:1], v[8:9]
	v_pk_mul_f32 v[10:11], v[10:11], v[12:13]
	v_and_b32_sdwa v6, v1, v129 dst_sel:DWORD dst_unused:UNUSED_PAD src0_sel:WORD_1 src1_sel:DWORD
	v_and_b32_sdwa v7, v0, v129 dst_sel:DWORD dst_unused:UNUSED_PAD src0_sel:WORD_1 src1_sel:DWORD
	v_cvt_pk_bf16_f32 v1, v1, v1
	v_cvt_pk_bf16_f32 v0, v0, v0
	v_cvt_pk_bf16_f32 v3, v10, v10
	v_cvt_pk_bf16_f32 v2, v11, v11
	v_and_b32_e32 v1, 0xffff0000, v1
	v_and_b32_e32 v0, 0xffff0000, v0
	v_or_b32_sdwa v1, v1, v2 dst_sel:DWORD dst_unused:UNUSED_PAD src0_sel:DWORD src1_sel:WORD_1
	v_or_b32_sdwa v0, v0, v3 dst_sel:DWORD dst_unused:UNUSED_PAD src0_sel:DWORD src1_sel:WORD_1
	global_store_dwordx2 v[4:5], v[0:1], off offset:1024

.LBB0_641:
	v_lshl_add_u64 v[40:41], v[64:65], 0, s[38:39]
	s_barrier
	global_load_dwordx4 v[24:27], v[40:41], off offset:48
	global_load_dwordx4 v[28:31], v[40:41], off offset:32
	global_load_dwordx4 v[32:35], v[40:41], off offset:16
	global_load_dwordx4 v[36:39], v[40:41], off
	s_waitcnt vmcnt(0)
	v_cvt_pk_bf16_f32 v38, v38, v38
	v_cvt_pk_bf16_f32 v36, v36, v36
	v_cvt_pk_bf16_f32 v39, v39, v39
	v_cvt_pk_bf16_f32 v37, v37, v37
	v_and_b32_e32 v39, 0xffff0000, v39
	v_and_b32_e32 v42, 0xffff0000, v37
	v_or_b32_sdwa v37, v39, v38 dst_sel:DWORD dst_unused:UNUSED_PAD src0_sel:DWORD src1_sel:WORD_1
	v_cvt_pk_bf16_f32 v32, v32, v32
	v_cvt_pk_bf16_f32 v33, v33, v33
	v_cvt_pk_bf16_f32 v34, v34, v34
	v_and_b32_e32 v33, 0xffff0000, v33
	v_cvt_pk_bf16_f32 v35, v35, v35
	v_or_b32_sdwa v38, v33, v32 dst_sel:DWORD dst_unused:UNUSED_PAD src0_sel:DWORD src1_sel:WORD_1
	v_cvt_pk_bf16_f32 v30, v30, v30
	v_cvt_pk_bf16_f32 v28, v28, v28
	v_cvt_pk_bf16_f32 v31, v31, v31
	v_cvt_pk_bf16_f32 v29, v29, v29
	v_and_b32_e32 v31, 0xffff0000, v31
	v_and_b32_e32 v32, 0xffff0000, v29
	v_or_b32_sdwa v29, v31, v30 dst_sel:DWORD dst_unused:UNUSED_PAD src0_sel:DWORD src1_sel:WORD_1
	v_cvt_pk_bf16_f32 v24, v24, v24
	v_cvt_pk_bf16_f32 v26, v26, v26
	v_cvt_pk_bf16_f32 v27, v27, v27
	v_cvt_pk_bf16_f32 v25, v25, v25
	v_and_b32_e32 v35, 0xffff0000, v35
	v_and_b32_e32 v27, 0xffff0000, v27
	v_and_b32_e32 v25, 0xffff0000, v25
	v_or_b32_sdwa v36, v42, v36 dst_sel:DWORD dst_unused:UNUSED_PAD src0_sel:DWORD src1_sel:WORD_1
	v_or_b32_sdwa v39, v35, v34 dst_sel:DWORD dst_unused:UNUSED_PAD src0_sel:DWORD src1_sel:WORD_1
	v_or_b32_sdwa v28, v32, v28 dst_sel:DWORD dst_unused:UNUSED_PAD src0_sel:DWORD src1_sel:WORD_1
	v_or_b32_sdwa v31, v27, v26 dst_sel:DWORD dst_unused:UNUSED_PAD src0_sel:DWORD src1_sel:WORD_1
	v_or_b32_sdwa v30, v25, v24 dst_sel:DWORD dst_unused:UNUSED_PAD src0_sel:DWORD src1_sel:WORD_1
	ds_write_b128 v59, v[36:39]
	ds_write_b128 v87, v[28:31]
	global_load_dwordx4 v[24:27], v[40:41], off offset:112
	global_load_dwordx4 v[28:31], v[40:41], off offset:96
	global_load_dwordx4 v[32:35], v[40:41], off offset:80
	global_load_dwordx4 v[36:39], v[40:41], off offset:64
	s_waitcnt vmcnt(0)
	v_cvt_pk_bf16_f32 v38, v38, v38
	v_cvt_pk_bf16_f32 v36, v36, v36
	v_cvt_pk_bf16_f32 v39, v39, v39
	v_cvt_pk_bf16_f32 v37, v37, v37
	v_and_b32_e32 v39, 0xffff0000, v39
	v_and_b32_e32 v40, 0xffff0000, v37
	v_or_b32_sdwa v37, v39, v38 dst_sel:DWORD dst_unused:UNUSED_PAD src0_sel:DWORD src1_sel:WORD_1
	v_cvt_pk_bf16_f32 v32, v32, v32
	v_cvt_pk_bf16_f32 v33, v33, v33
	v_cvt_pk_bf16_f32 v34, v34, v34
	v_and_b32_e32 v33, 0xffff0000, v33
	v_cvt_pk_bf16_f32 v35, v35, v35
	v_or_b32_sdwa v38, v33, v32 dst_sel:DWORD dst_unused:UNUSED_PAD src0_sel:DWORD src1_sel:WORD_1
	v_cvt_pk_bf16_f32 v30, v30, v30
	v_cvt_pk_bf16_f32 v28, v28, v28
	v_cvt_pk_bf16_f32 v31, v31, v31
	v_cvt_pk_bf16_f32 v29, v29, v29
	v_and_b32_e32 v31, 0xffff0000, v31
	v_and_b32_e32 v32, 0xffff0000, v29
	v_or_b32_sdwa v29, v31, v30 dst_sel:DWORD dst_unused:UNUSED_PAD src0_sel:DWORD src1_sel:WORD_1
	v_cvt_pk_bf16_f32 v24, v24, v24
	v_cvt_pk_bf16_f32 v26, v26, v26
	v_cvt_pk_bf16_f32 v27, v27, v27
	v_cvt_pk_bf16_f32 v25, v25, v25
	v_and_b32_e32 v35, 0xffff0000, v35
	v_and_b32_e32 v27, 0xffff0000, v27
	v_and_b32_e32 v25, 0xffff0000, v25
	v_or_b32_sdwa v36, v40, v36 dst_sel:DWORD dst_unused:UNUSED_PAD src0_sel:DWORD src1_sel:WORD_1
	v_or_b32_sdwa v39, v35, v34 dst_sel:DWORD dst_unused:UNUSED_PAD src0_sel:DWORD src1_sel:WORD_1
	v_or_b32_sdwa v28, v32, v28 dst_sel:DWORD dst_unused:UNUSED_PAD src0_sel:DWORD src1_sel:WORD_1
	v_or_b32_sdwa v31, v27, v26 dst_sel:DWORD dst_unused:UNUSED_PAD src0_sel:DWORD src1_sel:WORD_1
	v_or_b32_sdwa v30, v25, v24 dst_sel:DWORD dst_unused:UNUSED_PAD src0_sel:DWORD src1_sel:WORD_1
	ds_write_b128 v88, v[36:39]
	ds_write_b128 v89, v[28:31]
	v_lshl_add_u64 v[40:41], v[62:63], 0, s[38:39]
	global_load_dwordx4 v[24:27], v[40:41], off offset:48
	global_load_dwordx4 v[28:31], v[40:41], off offset:32
	global_load_dwordx4 v[32:35], v[40:41], off offset:16
	global_load_dwordx4 v[36:39], v[40:41], off
	s_add_u32 s38, s38, 0x40000
	s_addc_u32 s39, s39, 0
	s_cmp_lg_u32 s38, 0x80000
	s_waitcnt vmcnt(0)
	v_cvt_pk_bf16_f32 v36, v36, v36
	ds_write_b16_d16_hi v90, v36 offset:16384
	v_cvt_pk_bf16_f32 v36, v37, v37
	ds_write_b16_d16_hi v90, v36 offset:20736
	v_cvt_pk_bf16_f32 v36, v38, v38
	ds_write_b16_d16_hi v90, v36 offset:25088
	v_cvt_pk_bf16_f32 v36, v39, v39
	ds_write_b16_d16_hi v90, v36 offset:29440
	v_cvt_pk_bf16_f32 v32, v32, v32
	ds_write_b16_d16_hi v90, v32 offset:16656
	v_cvt_pk_bf16_f32 v32, v33, v33
	ds_write_b16_d16_hi v90, v32 offset:21008
	v_cvt_pk_bf16_f32 v32, v34, v34
	ds_write_b16_d16_hi v90, v32 offset:25360
	v_cvt_pk_bf16_f32 v32, v35, v35
	ds_write_b16_d16_hi v90, v32 offset:29712
	v_cvt_pk_bf16_f32 v28, v28, v28
	ds_write_b16_d16_hi v90, v28 offset:16928
	v_cvt_pk_bf16_f32 v28, v29, v29
	ds_write_b16_d16_hi v90, v28 offset:21280
	v_cvt_pk_bf16_f32 v28, v30, v30
	ds_write_b16_d16_hi v90, v28 offset:25632
	v_cvt_pk_bf16_f32 v28, v31, v31
	ds_write_b16_d16_hi v90, v28 offset:29984
	v_cvt_pk_bf16_f32 v24, v24, v24
	ds_write_b16_d16_hi v90, v24 offset:17200
	v_cvt_pk_bf16_f32 v24, v25, v25
	ds_write_b16_d16_hi v90, v24 offset:21552
	v_cvt_pk_bf16_f32 v24, v26, v26
	ds_write_b16_d16_hi v90, v24 offset:25904
	v_cvt_pk_bf16_f32 v24, v27, v27
	ds_write_b16_d16_hi v90, v24 offset:30256
	global_load_dwordx4 v[24:27], v[40:41], off offset:112
	global_load_dwordx4 v[28:31], v[40:41], off offset:96
	global_load_dwordx4 v[32:35], v[40:41], off offset:80
	global_load_dwordx4 v[36:39], v[40:41], off offset:64
	s_waitcnt vmcnt(0)
	v_cvt_pk_bf16_f32 v36, v36, v36
	ds_write_b16_d16_hi v90, v36 offset:17472
	v_cvt_pk_bf16_f32 v36, v37, v37
	ds_write_b16_d16_hi v90, v36 offset:21824
	v_cvt_pk_bf16_f32 v36, v38, v38
	ds_write_b16_d16_hi v90, v36 offset:26176
	v_cvt_pk_bf16_f32 v36, v39, v39
	ds_write_b16_d16_hi v90, v36 offset:30528
	v_cvt_pk_bf16_f32 v32, v32, v32
	ds_write_b16_d16_hi v90, v32 offset:17744
	v_cvt_pk_bf16_f32 v32, v33, v33
	ds_write_b16_d16_hi v90, v32 offset:22096
	v_cvt_pk_bf16_f32 v32, v34, v34
	ds_write_b16_d16_hi v90, v32 offset:26448
	v_cvt_pk_bf16_f32 v32, v35, v35
	ds_write_b16_d16_hi v90, v32 offset:30800
	v_cvt_pk_bf16_f32 v28, v28, v28
	ds_write_b16_d16_hi v90, v28 offset:18016
	v_cvt_pk_bf16_f32 v28, v29, v29
	ds_write_b16_d16_hi v90, v28 offset:22368
	v_cvt_pk_bf16_f32 v28, v30, v30
	ds_write_b16_d16_hi v90, v28 offset:26720
	v_cvt_pk_bf16_f32 v28, v31, v31
	ds_write_b16_d16_hi v90, v28 offset:31072
	v_cvt_pk_bf16_f32 v24, v24, v24
	ds_write_b16_d16_hi v90, v24 offset:18288
	v_cvt_pk_bf16_f32 v24, v25, v25
	ds_write_b16_d16_hi v90, v24 offset:22640
	v_cvt_pk_bf16_f32 v24, v26, v26
	ds_write_b16_d16_hi v90, v24 offset:26992
	v_cvt_pk_bf16_f32 v24, v27, v27
	ds_write_b16_d16_hi v90, v24 offset:31344
	s_waitcnt lgkmcnt(0)
	s_barrier
	ds_read_b128 v[24:27], v91
	ds_read_b128 v[28:31], v92
	s_waitcnt lgkmcnt(1)
	v_mfma_f32_16x16x32_bf16 v[24:27], v[0:3], v[24:27], 0
	ds_read_b128 v[32:35], v92 offset:2048
	ds_read_b128 v[36:39], v92 offset:4096
	ds_read_b128 v[40:43], v92 offset:6144
	s_waitcnt lgkmcnt(3)
	v_mfma_f32_16x16x32_bf16 v[24:27], v[4:7], v[28:31], v[24:27]
	ds_read_b128 v[28:31], v91 offset:2048
	ds_read_b128 v[44:47], v92 offset:8192
	ds_read_b128 v[48:51], v92 offset:10240
	s_waitcnt lgkmcnt(2)
	v_mfma_f32_16x16x32_bf16 v[28:31], v[0:3], v[28:31], 0
	ds_read_b128 v[52:55], v92 offset:12288
	ds_read_b128 v[68:71], v92 offset:14336
	s_nop 0
	v_mul_f32_e32 v98, 0x3e000000, v26
	v_mfma_f32_16x16x32_bf16 v[28:31], v[4:7], v[32:35], v[28:31]
	ds_read_b128 v[32:35], v91 offset:4096
	v_mul_f32_e32 v100, 0x3e000000, v27
	s_waitcnt lgkmcnt(0)
	v_mfma_f32_16x16x32_bf16 v[32:35], v[0:3], v[32:35], 0
	s_nop 3
	v_mul_f32_e32 v72, 0x3e000000, v29
	v_mfma_f32_16x16x32_bf16 v[32:35], v[4:7], v[36:39], v[32:35]
	ds_read_b128 v[36:39], v91 offset:6144
	v_mul_f32_e32 v99, 0x3e000000, v30
	v_mul_f32_e32 v101, 0x3e000000, v31
	s_waitcnt lgkmcnt(0)
	v_mfma_f32_16x16x32_bf16 v[36:39], v[0:3], v[36:39], 0
	s_nop 2
	v_mul_f32_e32 v74, 0x3e000000, v33
	v_mfma_f32_16x16x32_bf16 v[36:39], v[4:7], v[40:43], v[36:39]
	ds_read_b128 v[40:43], v91 offset:8192
	v_mul_f32_e32 v102, 0x3e000000, v34
	v_mul_f32_e32 v103, 0x3e000000, v35
	s_waitcnt lgkmcnt(0)
	v_mfma_f32_16x16x32_bf16 v[40:43], v[0:3], v[40:43], 0
	s_nop 2
	v_mul_f32_e32 v73, 0x3e000000, v36
	v_mfma_f32_16x16x32_bf16 v[40:43], v[4:7], v[44:47], v[40:43]
	ds_read_b128 v[44:47], v91 offset:10240
	v_mul_f32_e32 v76, 0x3e000000, v37
	v_mul_f32_e32 v104, 0x3e000000, v38
	s_waitcnt lgkmcnt(0)
	v_mfma_f32_16x16x32_bf16 v[44:47], v[0:3], v[44:47], 0
	v_mul_f32_e32 v105, 0x3e000000, v39
	s_nop 1
	v_mul_f32_e32 v75, 0x3e000000, v40
	v_mul_f32_e32 v78, 0x3e000000, v41
	v_mfma_f32_16x16x32_bf16 v[44:47], v[4:7], v[48:51], v[44:47]
	ds_read_b128 v[48:51], v91 offset:12288
	v_mul_f32_e32 v106, 0x3e000000, v42
	v_mul_f32_e32 v107, 0x3e000000, v43
	s_waitcnt lgkmcnt(0)
	v_mfma_f32_16x16x32_bf16 v[48:51], v[0:3], v[48:51], 0
	s_nop 2
	v_mul_f32_e32 v77, 0x3e000000, v44
	v_mfma_f32_16x16x32_bf16 v[48:51], v[4:7], v[52:55], v[48:51]
	ds_read_b128 v[52:55], v91 offset:14336
	v_mul_f32_e32 v80, 0x3e000000, v45
	v_mul_f32_e32 v108, 0x3e000000, v46
	s_waitcnt lgkmcnt(0)
	v_mfma_f32_16x16x32_bf16 v[52:55], v[0:3], v[52:55], 0
	v_mul_f32_e32 v109, 0x3e000000, v47
	s_nop 1
	v_mul_f32_e32 v79, 0x3e000000, v48
	v_mul_f32_e32 v82, 0x3e000000, v49
	v_mfma_f32_16x16x32_bf16 v[52:55], v[4:7], v[68:71], v[52:55]
	v_mul_f32_e32 v68, 0x3e000000, v24
	v_mul_f32_e32 v69, 0x3e000000, v28
	v_mul_f32_e32 v71, 0x3e000000, v32
	v_max_f32_e32 v68, v68, v69
	v_max3_f32 v68, v68, v71, v73
	s_nop 2
	v_mul_f32_e32 v81, 0x3e000000, v52
	v_max3_f32 v68, v68, v75, v77
	v_max3_f32 v68, v68, v79, v81
	v_mul_f32_e32 v70, 0x3e000000, v25
	v_mul_f32_e32 v112, 0x3e000000, v53
	v_mov_b32_dpp v69, v68 quad_perm:[1,0,3,2] row_mask:0xf bank_mask:0xf bound_ctrl:1
	v_max_f32_e32 v69, v69, v69
	v_max_f32_e32 v68, v68, v69
	v_mul_f32_e32 v110, 0x3e000000, v50
	v_mul_f32_e32 v113, 0x3e000000, v54
	v_mov_b32_dpp v69, v68 quad_perm:[2,3,0,1] row_mask:0xf bank_mask:0xf bound_ctrl:1
	v_max_f32_e32 v69, v69, v69
	v_max_f32_e32 v68, v68, v69
	v_mul_f32_e32 v111, 0x3e000000, v51
	v_mul_f32_e32 v114, 0x3e000000, v55
	v_mov_b32_dpp v69, v68 row_half_mirror row_mask:0xf bank_mask:0xf bound_ctrl:1
	v_max_f32_e32 v69, v69, v69
	v_max_f32_e32 v68, v68, v69
	s_nop 1
	v_mov_b32_dpp v69, v68 row_mirror row_mask:0xf bank_mask:0xf bound_ctrl:1
	v_max3_f32 v95, v67, v68, v69
	v_fma_f32 v24, v24, s90, -v95
	v_mul_f32_e32 v24, 0x3fb8aa3b, v24
	v_exp_f32_e32 v81, v24
	v_fma_f32 v24, v28, s90, -v95
	v_mul_f32_e32 v24, 0x3fb8aa3b, v24
	v_exp_f32_e32 v79, v24
	v_fma_f32 v24, v32, s90, -v95
	v_mul_f32_e32 v24, 0x3fb8aa3b, v24
	v_exp_f32_e32 v77, v24
	v_fma_f32 v24, v36, s90, -v95
	v_mul_f32_e32 v24, 0x3fb8aa3b, v24
	v_exp_f32_e32 v75, v24
	v_fma_f32 v24, v40, s90, -v95
	v_mul_f32_e32 v24, 0x3fb8aa3b, v24
	v_exp_f32_e32 v73, v24
	v_fma_f32 v24, v44, s90, -v95
	v_mul_f32_e32 v24, 0x3fb8aa3b, v24
	v_exp_f32_e32 v71, v24
	v_fma_f32 v24, v48, s90, -v95
	v_mul_f32_e32 v24, 0x3fb8aa3b, v24
	v_exp_f32_e32 v69, v24
	v_fma_f32 v24, v52, s90, -v95
	v_sub_f32_e32 v67, v67, v95
	v_mul_f32_e32 v24, 0x3fb8aa3b, v24
	v_mul_f32_e32 v68, 0x3fb8aa3b, v67
	v_exp_f32_e32 v67, v24
	v_max_f32_e32 v24, v70, v72
	v_max3_f32 v24, v24, v74, v76
	v_max3_f32 v24, v24, v78, v80
	v_max3_f32 v24, v24, v82, v112
	v_exp_f32_e32 v83, v68
	s_nop 0
	v_mov_b32_dpp v28, v24 quad_perm:[1,0,3,2] row_mask:0xf bank_mask:0xf bound_ctrl:1
	v_max_f32_e32 v28, v28, v28
	v_max_f32_e32 v24, v24, v28
	s_nop 1
	v_mov_b32_dpp v28, v24 quad_perm:[2,3,0,1] row_mask:0xf bank_mask:0xf bound_ctrl:1
	v_max_f32_e32 v28, v28, v28
	v_max_f32_e32 v24, v24, v28
	s_nop 1
	v_mov_b32_dpp v28, v24 row_half_mirror row_mask:0xf bank_mask:0xf bound_ctrl:1
	v_max_f32_e32 v28, v28, v28
	v_max_f32_e32 v24, v24, v28
	s_nop 1
	v_mov_b32_dpp v28, v24 row_mirror row_mask:0xf bank_mask:0xf bound_ctrl:1
	v_max3_f32 v28, v66, v24, v28
	v_sub_f32_e32 v24, v66, v28
	v_mul_f32_e32 v32, 0x3fb8aa3b, v24
	v_fma_f32 v24, v25, s90, -v28
	v_mul_f32_e32 v24, 0x3fb8aa3b, v24
	v_exp_f32_e32 v80, v24
	v_fma_f32 v24, v29, s90, -v28
	v_fma_f32 v29, v33, s90, -v28
	v_mul_f32_e32 v29, 0x3fb8aa3b, v29
	v_exp_f32_e32 v76, v29
	v_fma_f32 v29, v37, s90, -v28
	v_mul_f32_e32 v29, 0x3fb8aa3b, v29
	v_exp_f32_e32 v74, v29
	v_fma_f32 v29, v41, s90, -v28
	v_mul_f32_e32 v24, 0x3fb8aa3b, v24
	v_mul_f32_e32 v29, 0x3fb8aa3b, v29
	v_exp_f32_e32 v78, v24
	v_exp_f32_e32 v72, v29
	v_fma_f32 v29, v45, s90, -v28
	v_mul_f32_e32 v29, 0x3fb8aa3b, v29
	v_exp_f32_e32 v70, v29
	v_fma_f32 v29, v49, s90, -v28
	v_pk_add_f32 v[24:25], v[80:81], 0 op_sel_hi:[1,0]
	v_mul_f32_e32 v29, 0x3fb8aa3b, v29
	v_pk_add_f32 v[24:25], v[78:79], v[24:25]
	v_exp_f32_e32 v68, v29
	v_fma_f32 v29, v53, s90, -v28
	v_mul_f32_e32 v29, 0x3fb8aa3b, v29
	v_pk_add_f32 v[24:25], v[76:77], v[24:25]
	v_exp_f32_e32 v66, v29
	v_pk_add_f32 v[24:25], v[74:75], v[24:25]
	v_exp_f32_e32 v82, v32
	v_pk_add_f32 v[24:25], v[72:73], v[24:25]
	s_nop 0
	v_pk_add_f32 v[24:25], v[70:71], v[24:25]
	s_nop 0
	v_pk_add_f32 v[24:25], v[68:69], v[24:25]
	s_nop 0
	v_pk_add_f32 v[24:25], v[66:67], v[24:25]
	s_nop 1
	v_mov_b32_dpp v33, v25 quad_perm:[1,0,3,2] row_mask:0xf bank_mask:0xf bound_ctrl:1
	v_mov_b32_dpp v32, v24 quad_perm:[1,0,3,2] row_mask:0xf bank_mask:0xf bound_ctrl:1
	v_pk_add_f32 v[24:25], v[24:25], v[32:33]
	s_nop 1
	v_mov_b32_dpp v33, v25 quad_perm:[2,3,0,1] row_mask:0xf bank_mask:0xf bound_ctrl:1
	v_mov_b32_dpp v32, v24 quad_perm:[2,3,0,1] row_mask:0xf bank_mask:0xf bound_ctrl:1
	v_pk_add_f32 v[24:25], v[24:25], v[32:33]
	s_nop 1
	v_mov_b32_dpp v33, v25 row_half_mirror row_mask:0xf bank_mask:0xf bound_ctrl:1
	v_mov_b32_dpp v32, v24 row_half_mirror row_mask:0xf bank_mask:0xf bound_ctrl:1
	v_pk_add_f32 v[24:25], v[24:25], v[32:33]
	s_nop 1
	v_mov_b32_dpp v33, v25 row_mirror row_mask:0xf bank_mask:0xf bound_ctrl:1
	v_mov_b32_dpp v32, v24 row_mirror row_mask:0xf bank_mask:0xf bound_ctrl:1
	v_pk_add_f32 v[24:25], v[24:25], v[32:33]
	s_nop 0
	v_pk_fma_f32 v[60:61], v[60:61], v[82:83], v[24:25]
	v_max_f32_e32 v24, v98, v99
	v_max3_f32 v24, v24, v102, v104
	v_max3_f32 v24, v24, v106, v108
	v_max3_f32 v24, v24, v110, v113
	s_nop 1
	v_mov_b32_dpp v25, v24 quad_perm:[1,0,3,2] row_mask:0xf bank_mask:0xf bound_ctrl:1
	v_max_f32_e32 v25, v25, v25
	v_max_f32_e32 v24, v24, v25
	s_nop 1
	v_mov_b32_dpp v25, v24 quad_perm:[2,3,0,1] row_mask:0xf bank_mask:0xf bound_ctrl:1
	v_max_f32_e32 v25, v25, v25
	v_max_f32_e32 v24, v24, v25
	s_nop 1
	v_mov_b32_dpp v25, v24 row_half_mirror row_mask:0xf bank_mask:0xf bound_ctrl:1
	v_max_f32_e32 v25, v25, v25
	v_max_f32_e32 v24, v24, v25
	s_nop 1
	v_mov_b32_dpp v25, v24 row_mirror row_mask:0xf bank_mask:0xf bound_ctrl:1
	v_max3_f32 v29, v97, v24, v25
	v_sub_f32_e32 v24, v97, v29
	v_mul_f32_e32 v24, 0x3fb8aa3b, v24
	v_exp_f32_e32 v99, v24
	v_max_f32_e32 v24, v100, v101
	v_max3_f32 v24, v24, v103, v105
	v_max3_f32 v24, v24, v107, v109
	v_max3_f32 v24, v24, v111, v114
	v_fma_f32 v25, v26, s90, -v29
	v_mul_f32_e32 v25, 0x3fb8aa3b, v25
	v_mov_b32_dpp v26, v24 quad_perm:[1,0,3,2] row_mask:0xf bank_mask:0xf bound_ctrl:1
	v_max_f32_e32 v26, v26, v26
	v_max_f32_e32 v24, v24, v26
	v_exp_f32_e32 v33, v25
	v_fma_f32 v25, v30, s90, -v29
	v_mov_b32_dpp v26, v24 quad_perm:[2,3,0,1] row_mask:0xf bank_mask:0xf bound_ctrl:1
	v_max_f32_e32 v26, v26, v26
	v_max_f32_e32 v24, v24, v26
	v_mul_f32_e32 v25, 0x3fb8aa3b, v25
	v_exp_f32_e32 v37, v25
	v_mov_b32_dpp v26, v24 row_half_mirror row_mask:0xf bank_mask:0xf bound_ctrl:1
	v_max_f32_e32 v26, v26, v26
	v_max_f32_e32 v24, v24, v26
	v_fma_f32 v25, v34, s90, -v29
	v_mul_f32_e32 v25, 0x3fb8aa3b, v25
	v_mov_b32_dpp v26, v24 row_mirror row_mask:0xf bank_mask:0xf bound_ctrl:1
	v_max3_f32 v26, v96, v24, v26
	v_sub_f32_e32 v24, v96, v26
	v_mul_f32_e32 v34, 0x3fb8aa3b, v24
	v_fma_f32 v24, v27, s90, -v26
	v_mul_f32_e32 v24, 0x3fb8aa3b, v24
	v_cvt_pk_bf16_f32 v27, v81, v81
	v_exp_f32_e32 v32, v24
	ds_write_b16_d16_hi v93, v27 offset:33792
	v_cvt_pk_bf16_f32 v27, v80, v80
	ds_write_b16_d16_hi v93, v27 offset:34064
	v_cvt_pk_bf16_f32 v27, v33, v33
	ds_write_b16_d16_hi v93, v27 offset:34336
	v_cvt_pk_bf16_f32 v27, v32, v32
	v_fma_f32 v24, v31, s90, -v26
	ds_write_b16_d16_hi v93, v27 offset:34608
	v_mul_f32_e32 v24, 0x3fb8aa3b, v24
	v_cvt_pk_bf16_f32 v27, v79, v79
	v_exp_f32_e32 v36, v24
	ds_write_b16_d16_hi v93, v27 offset:33824
	v_cvt_pk_bf16_f32 v27, v78, v78
	ds_write_b16_d16_hi v93, v27 offset:34096
	v_cvt_pk_bf16_f32 v27, v37, v37
	ds_write_b16_d16_hi v93, v27 offset:34368
	v_cvt_pk_bf16_f32 v27, v36, v36
	v_exp_f32_e32 v41, v25
	v_fma_f32 v24, v35, s90, -v26
	ds_write_b16_d16_hi v93, v27 offset:34640
	v_mul_f32_e32 v24, 0x3fb8aa3b, v24
	v_cvt_pk_bf16_f32 v27, v77, v77
	v_exp_f32_e32 v40, v24
	ds_write_b16_d16_hi v93, v27 offset:33856
	v_cvt_pk_bf16_f32 v27, v76, v76
	ds_write_b16_d16_hi v93, v27 offset:34128
	v_cvt_pk_bf16_f32 v27, v41, v41
	v_fma_f32 v25, v38, s90, -v29
	ds_write_b16_d16_hi v93, v27 offset:34400
	v_mul_f32_e32 v25, 0x3fb8aa3b, v25
	v_cvt_pk_bf16_f32 v27, v40, v40
	v_exp_f32_e32 v45, v25
	v_fma_f32 v24, v39, s90, -v26
	ds_write_b16_d16_hi v93, v27 offset:34672
	v_mul_f32_e32 v24, 0x3fb8aa3b, v24
	v_cvt_pk_bf16_f32 v27, v75, v75
	v_exp_f32_e32 v44, v24
	ds_write_b16_d16_hi v93, v27 offset:33888
	v_cvt_pk_bf16_f32 v27, v74, v74
	ds_write_b16_d16_hi v93, v27 offset:34160
	v_cvt_pk_bf16_f32 v27, v45, v45
	v_fma_f32 v25, v42, s90, -v29
	ds_write_b16_d16_hi v93, v27 offset:34432
	v_mul_f32_e32 v25, 0x3fb8aa3b, v25
	v_cvt_pk_bf16_f32 v27, v44, v44
	v_exp_f32_e32 v49, v25
	v_fma_f32 v24, v43, s90, -v26
	ds_write_b16_d16_hi v93, v27 offset:34704
	v_mul_f32_e32 v24, 0x3fb8aa3b, v24
	v_cvt_pk_bf16_f32 v27, v73, v73
	v_exp_f32_e32 v48, v24
	ds_write_b16_d16_hi v93, v27 offset:33920
	v_cvt_pk_bf16_f32 v27, v72, v72
	ds_write_b16_d16_hi v93, v27 offset:34192
	v_cvt_pk_bf16_f32 v27, v49, v49
	v_fma_f32 v25, v46, s90, -v29
	ds_write_b16_d16_hi v93, v27 offset:34464
	v_mul_f32_e32 v25, 0x3fb8aa3b, v25
	v_cvt_pk_bf16_f32 v27, v48, v48
	v_exp_f32_e32 v53, v25
	v_fma_f32 v24, v47, s90, -v26
	ds_write_b16_d16_hi v93, v27 offset:34736
	v_mul_f32_e32 v24, 0x3fb8aa3b, v24
	v_cvt_pk_bf16_f32 v27, v71, v71
	v_exp_f32_e32 v52, v24
	ds_write_b16_d16_hi v93, v27 offset:33952
	v_cvt_pk_bf16_f32 v27, v70, v70
	ds_write_b16_d16_hi v93, v27 offset:34224
	v_cvt_pk_bf16_f32 v27, v53, v53
	v_fma_f32 v25, v50, s90, -v29
	v_fma_f32 v24, v51, s90, -v26
	ds_write_b16_d16_hi v93, v27 offset:34496
	v_mul_f32_e32 v25, 0x3fb8aa3b, v25
	v_pk_add_f32 v[30:31], v[32:33], 0 op_sel_hi:[1,0]
	v_mul_f32_e32 v24, 0x3fb8aa3b, v24
	v_cvt_pk_bf16_f32 v27, v52, v52
	v_exp_f32_e32 v97, v25
	v_fma_f32 v25, v54, s90, -v29
	v_pk_add_f32 v[30:31], v[36:37], v[30:31]
	v_exp_f32_e32 v96, v24
	v_fma_f32 v24, v55, s90, -v26
	ds_write_b16_d16_hi v93, v27 offset:34768
	v_mul_f32_e32 v25, 0x3fb8aa3b, v25
	v_mul_f32_e32 v24, 0x3fb8aa3b, v24
	v_pk_add_f32 v[30:31], v[40:41], v[30:31]
	v_cvt_pk_bf16_f32 v27, v69, v69
	v_exp_f32_e32 v25, v25
	v_exp_f32_e32 v24, v24
	v_pk_add_f32 v[30:31], v[44:45], v[30:31]
	ds_write_b16_d16_hi v93, v27 offset:33984
	v_pk_add_f32 v[30:31], v[48:49], v[30:31]
	v_cvt_pk_bf16_f32 v27, v68, v68
	v_pk_add_f32 v[30:31], v[52:53], v[30:31]
	ds_write_b16_d16_hi v93, v27 offset:34256
	v_pk_add_f32 v[30:31], v[96:97], v[30:31]
	v_cvt_pk_bf16_f32 v27, v97, v97
	v_pk_add_f32 v[30:31], v[24:25], v[30:31]
	ds_write_b16_d16_hi v93, v27 offset:34528
	v_exp_f32_e32 v98, v34
	v_mov_b32_dpp v35, v31 quad_perm:[1,0,3,2] row_mask:0xf bank_mask:0xf bound_ctrl:1
	v_mov_b32_dpp v34, v30 quad_perm:[1,0,3,2] row_mask:0xf bank_mask:0xf bound_ctrl:1
	v_cvt_pk_bf16_f32 v27, v96, v96
	v_pk_add_f32 v[30:31], v[30:31], v[34:35]
	ds_write_b16_d16_hi v93, v27 offset:34800
	v_mov_b32_dpp v35, v31 quad_perm:[2,3,0,1] row_mask:0xf bank_mask:0xf bound_ctrl:1
	v_mov_b32_dpp v34, v30 quad_perm:[2,3,0,1] row_mask:0xf bank_mask:0xf bound_ctrl:1
	v_cvt_pk_bf16_f32 v27, v67, v67
	v_pk_add_f32 v[30:31], v[30:31], v[34:35]
	ds_write_b16_d16_hi v93, v27 offset:34016
	v_mov_b32_dpp v35, v31 row_half_mirror row_mask:0xf bank_mask:0xf bound_ctrl:1
	v_mov_b32_dpp v34, v30 row_half_mirror row_mask:0xf bank_mask:0xf bound_ctrl:1
	v_cvt_pk_bf16_f32 v27, v66, v66
	v_pk_add_f32 v[30:31], v[30:31], v[34:35]
	ds_write_b16_d16_hi v93, v27 offset:34288
	v_bfe_u32 v27, v25, 16, 1
	v_mov_b32_dpp v35, v31 row_mirror row_mask:0xf bank_mask:0xf bound_ctrl:1
	v_mov_b32_dpp v34, v30 row_mirror row_mask:0xf bank_mask:0xf bound_ctrl:1
	v_cvt_pk_bf16_f32 v25, v25, v25
	v_pk_add_f32 v[30:31], v[30:31], v[34:35]
	ds_write_b16_d16_hi v93, v25 offset:34560
	v_pk_fma_f32 v[56:57], v[56:57], v[98:99], v[30:31]
	v_mov_b32_e32 v30, v99
	v_mov_b32_e32 v31, v98
	v_mov_b32_e32 v34, v83
	v_mov_b32_e32 v35, v82
	v_cvt_pk_bf16_f32 v24, v24, v24
	v_pk_mul_f32 v[22:23], v[22:23], v[30:31]
	v_pk_mul_f32 v[20:21], v[20:21], v[34:35]
	v_pk_mul_f32 v[18:19], v[18:19], v[30:31]
	v_pk_mul_f32 v[16:17], v[16:17], v[34:35]
	v_pk_mul_f32 v[14:15], v[14:15], v[30:31]
	v_pk_mul_f32 v[12:13], v[12:13], v[34:35]
	v_pk_mul_f32 v[10:11], v[10:11], v[30:31]
	v_pk_mul_f32 v[8:9], v[8:9], v[34:35]
	ds_write_b16_d16_hi v93, v24 offset:34832
	s_waitcnt lgkmcnt(0)
	s_barrier
	ds_read_b128 v[30:33], v58 offset:33792
	ds_read_b128 v[34:37], v94 offset:16384
	s_waitcnt lgkmcnt(0)
	v_mfma_f32_16x16x32_bf16 v[20:23], v[30:33], v[34:37], v[20:23]
	ds_read_b128 v[34:37], v94 offset:20736
	v_mov_b32_e32 v96, v26
	v_mov_b32_e32 v97, v29
	s_waitcnt lgkmcnt(0)
	v_mfma_f32_16x16x32_bf16 v[16:19], v[30:33], v[34:37], v[16:19]
	ds_read_b128 v[34:37], v94 offset:25088
	v_mov_b32_e32 v66, v28
	v_mov_b32_e32 v67, v95
	s_waitcnt lgkmcnt(0)
	v_mfma_f32_16x16x32_bf16 v[12:15], v[30:33], v[34:37], v[12:15]
	ds_read_b128 v[34:37], v94 offset:29440
	s_waitcnt lgkmcnt(0)
	v_mfma_f32_16x16x32_bf16 v[8:11], v[30:33], v[34:37], v[8:11]
	ds_read_b128 v[30:33], v58 offset:33856
	ds_read_b128 v[34:37], v94 offset:16448
	s_waitcnt lgkmcnt(0)
	v_mfma_f32_16x16x32_bf16 v[20:23], v[30:33], v[34:37], v[20:23]
	ds_read_b128 v[34:37], v94 offset:20800
	s_waitcnt lgkmcnt(0)
	v_mfma_f32_16x16x32_bf16 v[16:19], v[30:33], v[34:37], v[16:19]
	ds_read_b128 v[34:37], v94 offset:25152
	s_waitcnt lgkmcnt(0)
	v_mfma_f32_16x16x32_bf16 v[12:15], v[30:33], v[34:37], v[12:15]
	ds_read_b128 v[34:37], v94 offset:29504
	s_waitcnt lgkmcnt(0)
	v_mfma_f32_16x16x32_bf16 v[8:11], v[30:33], v[34:37], v[8:11]
	ds_read_b128 v[30:33], v58 offset:33920
	ds_read_b128 v[34:37], v94 offset:16512
	s_waitcnt lgkmcnt(0)
	v_mfma_f32_16x16x32_bf16 v[20:23], v[30:33], v[34:37], v[20:23]
	ds_read_b128 v[34:37], v94 offset:20864
	s_waitcnt lgkmcnt(0)
	v_mfma_f32_16x16x32_bf16 v[16:19], v[30:33], v[34:37], v[16:19]
	ds_read_b128 v[34:37], v94 offset:25216
	s_waitcnt lgkmcnt(0)
	v_mfma_f32_16x16x32_bf16 v[12:15], v[30:33], v[34:37], v[12:15]
	ds_read_b128 v[34:37], v94 offset:29568
	s_waitcnt lgkmcnt(0)
	v_mfma_f32_16x16x32_bf16 v[8:11], v[30:33], v[34:37], v[8:11]
	ds_read_b128 v[30:33], v58 offset:33984
	ds_read_b128 v[34:37], v94 offset:16576
	s_waitcnt lgkmcnt(0)
	v_mfma_f32_16x16x32_bf16 v[20:23], v[30:33], v[34:37], v[20:23]
	ds_read_b128 v[34:37], v94 offset:20928
	s_waitcnt lgkmcnt(0)
	v_mfma_f32_16x16x32_bf16 v[16:19], v[30:33], v[34:37], v[16:19]
	ds_read_b128 v[34:37], v94 offset:25280
	s_waitcnt lgkmcnt(0)
	v_mfma_f32_16x16x32_bf16 v[12:15], v[30:33], v[34:37], v[12:15]
	ds_read_b128 v[34:37], v94 offset:29632
	s_waitcnt lgkmcnt(0)
	v_mfma_f32_16x16x32_bf16 v[8:11], v[30:33], v[34:37], v[8:11]
	s_cbranch_scc1 .LBB0_641
	v_div_scale_f32 v1, s[2:3], v61, v61, 1.0
	v_rcp_f32_e32 v2, v1
	v_or_b32_e32 v0, v85, v86
	v_mov_b32_e32 v6, v20
	v_mov_b32_e32 v7, v12
	v_fma_f32 v3, -v1, v2, 1.0
	v_fmac_f32_e32 v2, v3, v2
	v_div_scale_f32 v3, vcc, 1.0, v61, 1.0
	v_mul_f32_e32 v4, v3, v2
	v_fma_f32 v5, -v1, v4, v3
	v_fmac_f32_e32 v4, v5, v2
	v_fma_f32 v1, -v1, v4, v3
	v_div_fmas_f32 v1, v1, v2, v4
	v_div_fixup_f32 v2, v1, v61, 1.0
	v_ashrrev_i32_e32 v1, 31, v0
	v_pk_mul_f32 v[6:7], v[2:3], v[6:7] op_sel_hi:[0,1]
	v_mov_b32_e32 v24, v16
	v_mov_b32_e32 v25, v8
	v_lshlrev_b64 v[4:5], 11, v[0:1]
	v_pk_mul_f32 v[2:3], v[2:3], v[24:25] op_sel_hi:[0,1]
	v_cvt_pk_bf16_f32 v1, v7, v7
	v_cvt_pk_bf16_f32 v6, v6, v6
	v_cvt_pk_bf16_f32 v3, v3, v3
	v_div_scale_f32 v7, s[2:3], v60, v60, 1.0
	v_cvt_pk_bf16_f32 v2, v2, v2
	v_rcp_f32_e32 v8, v7
	v_lshl_add_u64 v[4:5], s[80:81], 0, v[4:5]
	s_lshl_b32 s36, s20, 1
	v_and_b32_e32 v3, 0xffff0000, v3
	v_lshl_add_u64 v[4:5], v[4:5], 0, s[36:37]
	v_lshlrev_b32_e32 v116, 3, v84
	v_and_b32_e32 v2, 0xffff0000, v2
	v_or_b32_sdwa v3, v3, v1 dst_sel:DWORD dst_unused:UNUSED_PAD src0_sel:DWORD src1_sel:WORD_1
	v_fma_f32 v1, -v7, v8, 1.0
	v_lshl_add_u64 v[4:5], v[4:5], 0, v[116:117]
	v_or_b32_sdwa v2, v2, v6 dst_sel:DWORD dst_unused:UNUSED_PAD src0_sel:DWORD src1_sel:WORD_1
	v_fmac_f32_e32 v8, v1, v8
	v_div_scale_f32 v1, vcc, 1.0, v60, 1.0
	global_store_dwordx2 v[4:5], v[2:3], off
	v_mul_f32_e32 v2, v1, v8
	v_fma_f32 v3, -v7, v2, v1
	v_fmac_f32_e32 v2, v3, v8
	v_fma_f32 v1, -v7, v2, v1
	v_div_fmas_f32 v1, v1, v8, v2
	v_div_fixup_f32 v2, v1, v60, 1.0
	v_mov_b32_e32 v12, v21
	v_pk_mul_f32 v[6:7], v[2:3], v[12:13] op_sel_hi:[0,1]
	v_mov_b32_e32 v8, v17
	v_pk_mul_f32 v[2:3], v[2:3], v[8:9] op_sel_hi:[0,1]
	v_cvt_pk_bf16_f32 v1, v7, v7
	v_cvt_pk_bf16_f32 v6, v6, v6
	v_cvt_pk_bf16_f32 v3, v3, v3
	v_div_scale_f32 v7, s[2:3], v57, v57, 1.0
	v_or_b32_e32 v4, 1, v0
	v_cvt_pk_bf16_f32 v2, v2, v2
	v_rcp_f32_e32 v8, v7
	v_ashrrev_i32_e32 v5, 31, v4
	v_lshlrev_b64 v[4:5], 11, v[4:5]
	v_lshl_add_u64 v[4:5], s[80:81], 0, v[4:5]
	v_and_b32_e32 v3, 0xffff0000, v3
	v_lshl_add_u64 v[4:5], v[4:5], 0, s[36:37]
	v_and_b32_e32 v2, 0xffff0000, v2
	v_or_b32_sdwa v3, v3, v1 dst_sel:DWORD dst_unused:UNUSED_PAD src0_sel:DWORD src1_sel:WORD_1
	v_fma_f32 v1, -v7, v8, 1.0
	v_lshl_add_u64 v[4:5], v[4:5], 0, v[116:117]
	v_or_b32_sdwa v2, v2, v6 dst_sel:DWORD dst_unused:UNUSED_PAD src0_sel:DWORD src1_sel:WORD_1
	v_fmac_f32_e32 v8, v1, v8
	v_div_scale_f32 v1, vcc, 1.0, v57, 1.0
	global_store_dwordx2 v[4:5], v[2:3], off
	v_mul_f32_e32 v2, v1, v8
	v_fma_f32 v3, -v7, v2, v1
	v_fmac_f32_e32 v2, v3, v8
	v_fma_f32 v1, -v7, v2, v1
	v_div_fmas_f32 v1, v1, v8, v2
	v_div_fixup_f32 v2, v1, v57, 1.0
	v_mov_b32_e32 v6, v22
	v_mov_b32_e32 v7, v14
	v_pk_mul_f32 v[6:7], v[2:3], v[6:7] op_sel_hi:[0,1]
	v_mov_b32_e32 v8, v18
	v_mov_b32_e32 v9, v10
	v_pk_mul_f32 v[2:3], v[2:3], v[8:9] op_sel_hi:[0,1]
	v_cvt_pk_bf16_f32 v1, v7, v7
	v_cvt_pk_bf16_f32 v6, v6, v6
	v_cvt_pk_bf16_f32 v3, v3, v3
	v_div_scale_f32 v7, s[2:3], v56, v56, 1.0
	v_or_b32_e32 v4, 2, v0
	v_cvt_pk_bf16_f32 v2, v2, v2
	v_rcp_f32_e32 v8, v7
	v_ashrrev_i32_e32 v5, 31, v4
	v_lshlrev_b64 v[4:5], 11, v[4:5]
	v_lshl_add_u64 v[4:5], s[80:81], 0, v[4:5]
	v_and_b32_e32 v3, 0xffff0000, v3
	v_lshl_add_u64 v[4:5], v[4:5], 0, s[36:37]
	v_and_b32_e32 v2, 0xffff0000, v2
	v_or_b32_sdwa v3, v3, v1 dst_sel:DWORD dst_unused:UNUSED_PAD src0_sel:DWORD src1_sel:WORD_1
	v_fma_f32 v1, -v7, v8, 1.0
	v_lshl_add_u64 v[4:5], v[4:5], 0, v[116:117]
	v_or_b32_sdwa v2, v2, v6 dst_sel:DWORD dst_unused:UNUSED_PAD src0_sel:DWORD src1_sel:WORD_1
	v_fmac_f32_e32 v8, v1, v8
	v_div_scale_f32 v1, vcc, 1.0, v56, 1.0
	global_store_dwordx2 v[4:5], v[2:3], off
	v_mul_f32_e32 v2, v1, v8
	v_fma_f32 v3, -v7, v2, v1
	v_fmac_f32_e32 v2, v3, v8
	v_fma_f32 v1, -v7, v2, v1
	v_div_fmas_f32 v1, v1, v8, v2
	v_div_fixup_f32 v2, v1, v56, 1.0
	v_mov_b32_e32 v14, v23
	v_or_b32_e32 v0, 3, v0
	v_pk_mul_f32 v[4:5], v[2:3], v[14:15] op_sel_hi:[0,1]
	v_mov_b32_e32 v10, v19
	v_ashrrev_i32_e32 v1, 31, v0
	v_pk_mul_f32 v[2:3], v[2:3], v[10:11] op_sel_hi:[0,1]
	v_lshlrev_b64 v[0:1], 11, v[0:1]
	v_cvt_pk_bf16_f32 v4, v4, v4
	v_cvt_pk_bf16_f32 v5, v5, v5
	v_and_b32_sdwa v6, v3, v129 dst_sel:DWORD dst_unused:UNUSED_PAD src0_sel:WORD_1 src1_sel:DWORD
	v_and_b32_sdwa v7, v2, v129 dst_sel:DWORD dst_unused:UNUSED_PAD src0_sel:WORD_1 src1_sel:DWORD
	v_lshl_add_u64 v[0:1], s[80:81], 0, v[0:1]
	v_cvt_pk_bf16_f32 v3, v3, v3
	v_cvt_pk_bf16_f32 v2, v2, v2
	v_lshl_add_u64 v[0:1], v[0:1], 0, s[36:37]
	v_and_b32_e32 v3, 0xffff0000, v3
	v_and_b32_e32 v2, 0xffff0000, v2
	v_lshl_add_u64 v[0:1], v[0:1], 0, v[116:117]
	v_or_b32_sdwa v3, v3, v5 dst_sel:DWORD dst_unused:UNUSED_PAD src0_sel:DWORD src1_sel:WORD_1
	v_or_b32_sdwa v2, v2, v4 dst_sel:DWORD dst_unused:UNUSED_PAD src0_sel:DWORD src1_sel:WORD_1
	global_store_dwordx2 v[0:1], v[2:3], off

.LBB0_654:
	v_max_f32_e32 v25, v55, v55
	v_max_f32_e32 v27, v100, v100
	v_max_f32_e32 v25, v27, v25
	v_max3_f32 v25, v25, v104, v106
	v_max3_f32 v25, v25, v42, v37
	v_max3_f32 v25, v25, v33, v31
	s_add_i32 s36, s36, 1
	s_add_u32 s22, s22, 0x40000
	v_mov_b32_dpp v27, v25 quad_perm:[1,0,3,2] row_mask:0xf bank_mask:0xf bound_ctrl:1
	v_max_f32_e32 v27, v27, v27
	v_max_f32_e32 v25, v25, v27
	s_addc_u32 s23, s23, 0
	s_add_u32 s24, s24, 0x40000
	v_mov_b32_dpp v27, v25 quad_perm:[2,3,0,1] row_mask:0xf bank_mask:0xf bound_ctrl:1
	v_max_f32_e32 v27, v27, v27
	v_max_f32_e32 v25, v25, v27
	s_addc_u32 s25, s25, 0
	v_add_u32_e32 v81, 0x80, v81
	v_mov_b32_dpp v27, v25 row_half_mirror row_mask:0xf bank_mask:0xf bound_ctrl:1
	v_max_f32_e32 v27, v27, v27
	v_max_f32_e32 v25, v25, v27
	v_add_u32_e32 v82, 2, v82
	s_cmp_lg_u32 s36, 6
	v_mov_b32_dpp v27, v25 row_mirror row_mask:0xf bank_mask:0xf bound_ctrl:1
	v_max3_f32 v98, v97, v25, v27
	v_sub_f32_e32 v27, v100, v98
	v_mul_f32_e32 v27, 0x3fb8aa3b, v27
	v_sub_f32_e32 v35, v55, v98
	v_exp_f32_e32 v101, v27
	v_mul_f32_e32 v35, 0x3fb8aa3b, v35
	v_exp_f32_e32 v100, v35
	v_sub_f32_e32 v25, v97, v98
	v_add_f32_e32 v27, 0, v101
	v_mul_f32_e32 v25, 0x3fb8aa3b, v25
	v_add_f32_e32 v55, v100, v27
	v_sub_f32_e32 v27, v104, v98
	v_mul_f32_e32 v27, 0x3fb8aa3b, v27
	v_exp_f32_e32 v43, v27
	v_sub_f32_e32 v27, v106, v98
	v_mul_f32_e32 v27, 0x3fb8aa3b, v27
	v_exp_f32_e32 v41, v27
	v_sub_f32_e32 v27, v42, v98
	v_mul_f32_e32 v27, 0x3fb8aa3b, v27
	v_exp_f32_e32 v39, v27
	v_sub_f32_e32 v27, v37, v98
	v_mul_f32_e32 v27, 0x3fb8aa3b, v27
	v_exp_f32_e32 v37, v27
	v_sub_f32_e32 v27, v33, v98
	v_mul_f32_e32 v27, 0x3fb8aa3b, v27
	v_exp_f32_e32 v35, v27
	v_sub_f32_e32 v27, v31, v98
	v_mul_f32_e32 v27, 0x3fb8aa3b, v27
	v_exp_f32_e32 v33, v27
	v_max_f32_e32 v27, v54, v54
	v_max_f32_e32 v31, v99, v99
	v_max_f32_e32 v27, v31, v27
	v_max3_f32 v27, v27, v51, v40
	v_max3_f32 v27, v27, v36, v32
	v_max3_f32 v27, v27, v34, v24
	v_exp_f32_e32 v25, v25
	s_nop 0
	v_mov_b32_dpp v31, v27 quad_perm:[1,0,3,2] row_mask:0xf bank_mask:0xf bound_ctrl:1
	v_max_f32_e32 v31, v31, v31
	v_max_f32_e32 v27, v27, v31
	s_nop 1
	v_mov_b32_dpp v31, v27 quad_perm:[2,3,0,1] row_mask:0xf bank_mask:0xf bound_ctrl:1
	v_max_f32_e32 v31, v31, v31
	v_max_f32_e32 v27, v27, v31
	s_nop 1
	v_mov_b32_dpp v31, v27 row_half_mirror row_mask:0xf bank_mask:0xf bound_ctrl:1
	v_max_f32_e32 v31, v31, v31
	v_max_f32_e32 v27, v27, v31
	s_nop 1
	v_mov_b32_dpp v31, v27 row_mirror row_mask:0xf bank_mask:0xf bound_ctrl:1
	v_max3_f32 v97, v96, v27, v31
	v_sub_f32_e32 v31, v99, v97
	v_mul_f32_e32 v31, 0x3fb8aa3b, v31
	v_sub_f32_e32 v38, v54, v97
	v_exp_f32_e32 v104, v31
	v_mul_f32_e32 v38, 0x3fb8aa3b, v38
	v_exp_f32_e32 v99, v38
	v_sub_f32_e32 v27, v96, v97
	v_add_f32_e32 v31, 0, v104
	v_sub_f32_e32 v24, v24, v97
	v_add_f32_e32 v54, v99, v31
	v_sub_f32_e32 v31, v51, v97
	v_mul_f32_e32 v31, 0x3fb8aa3b, v31
	v_exp_f32_e32 v42, v31
	v_sub_f32_e32 v31, v40, v97
	v_mul_f32_e32 v31, 0x3fb8aa3b, v31
	v_exp_f32_e32 v40, v31
	v_sub_f32_e32 v31, v36, v97
	v_mul_f32_e32 v31, 0x3fb8aa3b, v31
	v_exp_f32_e32 v38, v31
	v_sub_f32_e32 v31, v32, v97
	v_mul_f32_e32 v31, 0x3fb8aa3b, v31
	v_exp_f32_e32 v36, v31
	v_sub_f32_e32 v31, v34, v97
	v_mul_f32_e32 v27, 0x3fb8aa3b, v27
	v_mul_f32_e32 v31, 0x3fb8aa3b, v31
	v_mul_f32_e32 v24, 0x3fb8aa3b, v24
	v_exp_f32_e32 v34, v31
	v_exp_f32_e32 v32, v24
	v_exp_f32_e32 v24, v27
	v_max_f32_e32 v27, v49, v49
	v_max_f32_e32 v31, v53, v53
	v_max_f32_e32 v27, v31, v27
	v_max3_f32 v27, v27, v45, v47
	v_max3_f32 v27, v27, v102, v105
	v_pk_add_f32 v[54:55], v[42:43], v[54:55]
	v_max3_f32 v27, v27, v29, v30
	v_pk_add_f32 v[54:55], v[40:41], v[54:55]
	s_nop 0
	v_mov_b32_dpp v31, v27 quad_perm:[1,0,3,2] row_mask:0xf bank_mask:0xf bound_ctrl:1
	v_pk_add_f32 v[54:55], v[38:39], v[54:55]
	v_max_f32_e32 v31, v31, v31
	v_pk_add_f32 v[54:55], v[36:37], v[54:55]
	v_max_f32_e32 v27, v27, v31
	v_pk_add_f32 v[54:55], v[34:35], v[54:55]
	s_nop 0
	v_mov_b32_dpp v31, v27 quad_perm:[2,3,0,1] row_mask:0xf bank_mask:0xf bound_ctrl:1
	v_pk_add_f32 v[54:55], v[32:33], v[54:55]
	v_max_f32_e32 v31, v31, v31
	v_max_f32_e32 v27, v27, v31
	v_mov_b32_dpp v107, v55 quad_perm:[1,0,3,2] row_mask:0xf bank_mask:0xf bound_ctrl:1
	v_mov_b32_dpp v106, v54 quad_perm:[1,0,3,2] row_mask:0xf bank_mask:0xf bound_ctrl:1
	v_pk_add_f32 v[54:55], v[54:55], v[106:107]
	v_mov_b32_dpp v31, v27 row_half_mirror row_mask:0xf bank_mask:0xf bound_ctrl:1
	v_max_f32_e32 v31, v31, v31
	v_mov_b32_dpp v107, v55 quad_perm:[2,3,0,1] row_mask:0xf bank_mask:0xf bound_ctrl:1
	v_mov_b32_dpp v106, v54 quad_perm:[2,3,0,1] row_mask:0xf bank_mask:0xf bound_ctrl:1
	v_pk_add_f32 v[54:55], v[54:55], v[106:107]
	v_max_f32_e32 v27, v27, v31
	s_nop 0
	v_mov_b32_dpp v107, v55 row_half_mirror row_mask:0xf bank_mask:0xf bound_ctrl:1
	v_mov_b32_dpp v106, v54 row_half_mirror row_mask:0xf bank_mask:0xf bound_ctrl:1
	v_mov_b32_dpp v31, v27 row_mirror row_mask:0xf bank_mask:0xf bound_ctrl:1
	v_pk_add_f32 v[54:55], v[54:55], v[106:107]
	v_max3_f32 v96, v95, v27, v31
	v_sub_f32_e32 v45, v45, v96
	v_mov_b32_dpp v107, v55 row_mirror row_mask:0xf bank_mask:0xf bound_ctrl:1
	v_mov_b32_dpp v106, v54 row_mirror row_mask:0xf bank_mask:0xf bound_ctrl:1
	v_pk_add_f32 v[54:55], v[54:55], v[106:107]
	v_mul_f32_e32 v45, 0x3fb8aa3b, v45
	v_pk_fma_f32 v[62:63], v[62:63], v[24:25], v[54:55]
	v_exp_f32_e32 v55, v45
	v_sub_f32_e32 v45, v47, v96
	v_mul_f32_e32 v45, 0x3fb8aa3b, v45
	v_sub_f32_e32 v31, v53, v96
	v_exp_f32_e32 v53, v45
	v_sub_f32_e32 v45, v102, v96
	v_sub_f32_e32 v29, v29, v96
	v_mul_f32_e32 v45, 0x3fb8aa3b, v45
	v_mul_f32_e32 v29, 0x3fb8aa3b, v29
	v_sub_f32_e32 v49, v49, v96
	v_exp_f32_e32 v51, v45
	v_sub_f32_e32 v45, v105, v96
	v_exp_f32_e32 v47, v29
	v_sub_f32_e32 v29, v30, v96
	v_mul_f32_e32 v49, 0x3fb8aa3b, v49
	v_mul_f32_e32 v45, 0x3fb8aa3b, v45
	v_mul_f32_e32 v29, 0x3fb8aa3b, v29
	v_exp_f32_e32 v109, v49
	v_exp_f32_e32 v49, v45
	v_exp_f32_e32 v45, v29
	v_max_f32_e32 v29, v48, v48
	v_max_f32_e32 v30, v52, v52
	v_max_f32_e32 v29, v30, v29
	v_max3_f32 v29, v29, v44, v46
	v_max3_f32 v29, v29, v50, v103
	v_max3_f32 v29, v29, v28, v26
	v_sub_f32_e32 v27, v95, v96
	v_mul_f32_e32 v31, 0x3fb8aa3b, v31
	v_mov_b32_dpp v30, v29 quad_perm:[1,0,3,2] row_mask:0xf bank_mask:0xf bound_ctrl:1
	v_max_f32_e32 v30, v30, v30
	v_max_f32_e32 v29, v29, v30
	v_mov_b32_e32 v106, v25
	v_mov_b32_e32 v107, v24
	v_mov_b32_dpp v30, v29 quad_perm:[2,3,0,1] row_mask:0xf bank_mask:0xf bound_ctrl:1
	v_max_f32_e32 v30, v30, v30
	v_max_f32_e32 v29, v29, v30
	v_exp_f32_e32 v108, v31
	v_pk_mul_f32 v[24:25], v[12:13], v[106:107]
	v_mov_b32_dpp v30, v29 row_half_mirror row_mask:0xf bank_mask:0xf bound_ctrl:1
	v_max_f32_e32 v30, v30, v30
	v_max_f32_e32 v29, v29, v30
	v_pk_mul_f32 v[12:13], v[16:17], v[106:107]
	v_mov_b32_dpp v30, v29 row_mirror row_mask:0xf bank_mask:0xf bound_ctrl:1
	v_max3_f32 v95, v94, v29, v30
	v_sub_f32_e32 v30, v52, v95
	v_mul_f32_e32 v30, 0x3fb8aa3b, v30
	v_cvt_pk_bf16_f32 v16, v101, v101
	v_sub_f32_e32 v29, v94, v95
	v_exp_f32_e32 v94, v30
	ds_write_b16_d16_hi v90, v16 offset:33792
	v_cvt_pk_bf16_f32 v16, v104, v104
	ds_write_b16_d16_hi v90, v16 offset:34064
	v_cvt_pk_bf16_f32 v16, v108, v108
	ds_write_b16_d16_hi v90, v16 offset:34336
	v_cvt_pk_bf16_f32 v16, v94, v94
	v_sub_f32_e32 v48, v48, v95
	ds_write_b16_d16_hi v91, v16 offset:33792
	v_mul_f32_e32 v48, 0x3fb8aa3b, v48
	v_cvt_pk_bf16_f32 v16, v100, v100
	v_exp_f32_e32 v105, v48
	ds_write_b16_d16_hi v90, v16 offset:33824
	v_cvt_pk_bf16_f32 v16, v99, v99
	ds_write_b16_d16_hi v90, v16 offset:34096
	v_cvt_pk_bf16_f32 v16, v109, v109
	ds_write_b16_d16_hi v90, v16 offset:34368
	v_cvt_pk_bf16_f32 v16, v105, v105
	v_sub_f32_e32 v44, v44, v95
	ds_write_b16_d16_hi v91, v16 offset:33824
	v_mul_f32_e32 v44, 0x3fb8aa3b, v44
	v_cvt_pk_bf16_f32 v16, v43, v43
	v_exp_f32_e32 v54, v44
	ds_write_b16_d16_hi v90, v16 offset:33856
	v_cvt_pk_bf16_f32 v16, v42, v42
	ds_write_b16_d16_hi v90, v16 offset:34128
	v_cvt_pk_bf16_f32 v16, v55, v55
	ds_write_b16_d16_hi v90, v16 offset:34400
	v_cvt_pk_bf16_f32 v16, v54, v54
	v_sub_f32_e32 v44, v46, v95
	ds_write_b16_d16_hi v91, v16 offset:33856
	v_mul_f32_e32 v44, 0x3fb8aa3b, v44
	v_cvt_pk_bf16_f32 v16, v41, v41
	v_exp_f32_e32 v52, v44
	ds_write_b16_d16_hi v90, v16 offset:33888
	v_cvt_pk_bf16_f32 v16, v40, v40
	ds_write_b16_d16_hi v90, v16 offset:34160
	v_cvt_pk_bf16_f32 v16, v53, v53
	ds_write_b16_d16_hi v90, v16 offset:34432
	v_cvt_pk_bf16_f32 v16, v52, v52
	v_sub_f32_e32 v44, v50, v95
	ds_write_b16_d16_hi v91, v16 offset:33888
	v_mul_f32_e32 v44, 0x3fb8aa3b, v44
	v_cvt_pk_bf16_f32 v16, v39, v39
	v_exp_f32_e32 v50, v44
	ds_write_b16_d16_hi v90, v16 offset:33920
	v_cvt_pk_bf16_f32 v16, v38, v38
	ds_write_b16_d16_hi v90, v16 offset:34192
	v_cvt_pk_bf16_f32 v16, v51, v51
	ds_write_b16_d16_hi v90, v16 offset:34464
	v_cvt_pk_bf16_f32 v16, v50, v50
	v_sub_f32_e32 v44, v103, v95
	ds_write_b16_d16_hi v91, v16 offset:33920
	v_mul_f32_e32 v44, 0x3fb8aa3b, v44
	v_cvt_pk_bf16_f32 v16, v37, v37
	v_exp_f32_e32 v48, v44
	ds_write_b16_d16_hi v90, v16 offset:33952
	v_cvt_pk_bf16_f32 v16, v36, v36
	ds_write_b16_d16_hi v90, v16 offset:34224
	v_cvt_pk_bf16_f32 v16, v49, v49
	ds_write_b16_d16_hi v90, v16 offset:34496
	v_cvt_pk_bf16_f32 v16, v48, v48
	v_add_f32_e32 v31, 0, v108
	v_add_f32_e32 v30, 0, v94
	v_sub_f32_e32 v28, v28, v95
	v_sub_f32_e32 v26, v26, v95
	ds_write_b16_d16_hi v91, v16 offset:33952
	v_add_f32_e32 v31, v109, v31
	v_mul_f32_e32 v29, 0x3fb8aa3b, v29
	v_add_f32_e32 v30, v105, v30
	v_mul_f32_e32 v28, 0x3fb8aa3b, v28
	v_mul_f32_e32 v26, 0x3fb8aa3b, v26
	v_cvt_pk_bf16_f32 v16, v35, v35
	v_exp_f32_e32 v46, v28
	v_exp_f32_e32 v44, v26
	v_exp_f32_e32 v26, v29
	v_pk_add_f32 v[28:29], v[54:55], v[30:31]
	ds_write_b16_d16_hi v90, v16 offset:33984
	v_pk_add_f32 v[28:29], v[52:53], v[28:29]
	v_cvt_pk_bf16_f32 v16, v34, v34
	v_pk_add_f32 v[28:29], v[50:51], v[28:29]
	ds_write_b16_d16_hi v90, v16 offset:34256
	v_pk_add_f32 v[28:29], v[48:49], v[28:29]
	v_cvt_pk_bf16_f32 v16, v47, v47
	v_pk_add_f32 v[28:29], v[46:47], v[28:29]
	ds_write_b16_d16_hi v90, v16 offset:34528
	v_pk_add_f32 v[28:29], v[44:45], v[28:29]
	v_cvt_pk_bf16_f32 v16, v46, v46
	ds_write_b16_d16_hi v91, v16 offset:33984
	v_mov_b32_dpp v31, v29 quad_perm:[1,0,3,2] row_mask:0xf bank_mask:0xf bound_ctrl:1
	v_mov_b32_dpp v30, v28 quad_perm:[1,0,3,2] row_mask:0xf bank_mask:0xf bound_ctrl:1
	v_pk_add_f32 v[28:29], v[28:29], v[30:31]
	v_cvt_pk_bf16_f32 v16, v33, v33
	v_mul_f32_e32 v27, 0x3fb8aa3b, v27
	v_mov_b32_dpp v31, v29 quad_perm:[2,3,0,1] row_mask:0xf bank_mask:0xf bound_ctrl:1
	v_mov_b32_dpp v30, v28 quad_perm:[2,3,0,1] row_mask:0xf bank_mask:0xf bound_ctrl:1
	ds_write_b16_d16_hi v90, v16 offset:34016
	v_exp_f32_e32 v27, v27
	v_pk_add_f32 v[28:29], v[28:29], v[30:31]
	v_cvt_pk_bf16_f32 v16, v32, v32
	ds_write_b16_d16_hi v90, v16 offset:34288
	v_mov_b32_dpp v31, v29 row_half_mirror row_mask:0xf bank_mask:0xf bound_ctrl:1
	v_mov_b32_dpp v30, v28 row_half_mirror row_mask:0xf bank_mask:0xf bound_ctrl:1
	v_pk_add_f32 v[28:29], v[28:29], v[30:31]
	v_cvt_pk_bf16_f32 v16, v45, v45
	ds_write_b16_d16_hi v90, v16 offset:34560
	v_mov_b32_dpp v31, v29 row_mirror row_mask:0xf bank_mask:0xf bound_ctrl:1
	v_mov_b32_dpp v30, v28 row_mirror row_mask:0xf bank_mask:0xf bound_ctrl:1
	v_pk_add_f32 v[28:29], v[28:29], v[30:31]
	v_mov_b32_e32 v102, v27
	v_mov_b32_e32 v103, v26
	v_cvt_pk_bf16_f32 v16, v44, v44
	v_pk_fma_f32 v[60:61], v[60:61], v[26:27], v[28:29]
	v_pk_mul_f32 v[30:31], v[10:11], v[102:103]
	v_pk_mul_f32 v[28:29], v[8:9], v[106:107]
	v_pk_mul_f32 v[26:27], v[14:15], v[102:103]
	v_pk_mul_f32 v[14:15], v[18:19], v[102:103]
	v_pk_mul_f32 v[10:11], v[22:23], v[102:103]
	v_pk_mul_f32 v[8:9], v[20:21], v[106:107]
	ds_write_b16_d16_hi v91, v16 offset:34016
	s_waitcnt lgkmcnt(0)
	s_barrier
	ds_read_b128 v[16:19], v58 offset:33792
	ds_read_b128 v[20:23], v92 offset:16384
	s_waitcnt lgkmcnt(0)
	v_mfma_f32_16x16x32_bf16 v[20:23], v[16:19], v[20:23], v[28:31]
	s_nop 2
	ds_read_b128 v[28:31], v93 offset:16384
	v_mov_b32_e32 v94, v95
	v_mov_b32_e32 v95, v96
	s_waitcnt lgkmcnt(0)
	v_mfma_f32_16x16x32_bf16 v[24:27], v[16:19], v[28:31], v[24:27]
	ds_read_b128 v[28:31], v93 offset:20736
	v_mov_b32_e32 v96, v97
	v_mov_b32_e32 v97, v98
	s_waitcnt lgkmcnt(0)
	v_mfma_f32_16x16x32_bf16 v[12:15], v[16:19], v[28:31], v[12:15]
	ds_read_b128 v[28:31], v93 offset:25088
	s_waitcnt lgkmcnt(0)
	v_mfma_f32_16x16x32_bf16 v[8:11], v[16:19], v[28:31], v[8:11]
	ds_read_b128 v[16:19], v58 offset:33856
	ds_read_b128 v[28:31], v92 offset:16448
	s_waitcnt lgkmcnt(0)
	v_mfma_f32_16x16x32_bf16 v[20:23], v[16:19], v[28:31], v[20:23]
	ds_read_b128 v[28:31], v93 offset:16448
	s_waitcnt lgkmcnt(0)
	v_mfma_f32_16x16x32_bf16 v[24:27], v[16:19], v[28:31], v[24:27]
	ds_read_b128 v[28:31], v93 offset:20800
	s_waitcnt lgkmcnt(0)
	v_mfma_f32_16x16x32_bf16 v[12:15], v[16:19], v[28:31], v[12:15]
	ds_read_b128 v[28:31], v93 offset:25152
	s_waitcnt lgkmcnt(0)
	v_mfma_f32_16x16x32_bf16 v[8:11], v[16:19], v[28:31], v[8:11]
	ds_read_b128 v[16:19], v58 offset:33920
	ds_read_b128 v[28:31], v92 offset:16512
	s_waitcnt lgkmcnt(0)
	v_mfma_f32_16x16x32_bf16 v[20:23], v[16:19], v[28:31], v[20:23]
	ds_read_b128 v[28:31], v93 offset:16512
	s_waitcnt lgkmcnt(0)
	v_mfma_f32_16x16x32_bf16 v[24:27], v[16:19], v[28:31], v[24:27]
	ds_read_b128 v[28:31], v93 offset:20864
	s_waitcnt lgkmcnt(0)
	v_mfma_f32_16x16x32_bf16 v[28:31], v[16:19], v[28:31], v[12:15]
	s_nop 2
	ds_read_b128 v[12:15], v93 offset:25216
	s_waitcnt lgkmcnt(0)
	v_mfma_f32_16x16x32_bf16 v[32:35], v[16:19], v[12:15], v[8:11]
	ds_read_b128 v[36:39], v58 offset:33984
	s_nop 1
	ds_read_b128 v[8:11], v92 offset:16576
	ds_read_b128 v[12:15], v93 offset:16576
	ds_read_b128 v[16:19], v93 offset:20928
	s_waitcnt lgkmcnt(2)
	v_mfma_f32_16x16x32_bf16 v[8:11], v[36:39], v[8:11], v[20:23]
	s_nop 2
	ds_read_b128 v[20:23], v93 offset:25280
	s_waitcnt lgkmcnt(2)
	v_mfma_f32_16x16x32_bf16 v[12:15], v[36:39], v[12:15], v[24:27]
	s_waitcnt lgkmcnt(1)
	v_mfma_f32_16x16x32_bf16 v[16:19], v[36:39], v[16:19], v[28:31]
	s_waitcnt lgkmcnt(0)
	v_mfma_f32_16x16x32_bf16 v[20:23], v[36:39], v[20:23], v[32:35]
	s_cbranch_scc0 .LBB0_721

.LBB0_657:
	v_mad_i64_i32 v[28:29], s[70:71], s70, v56, 0
	v_lshlrev_b64 v[28:29], 2, v[28:29]
	v_lshl_add_u64 v[26:27], v[26:27], 0, v[28:29]
	v_lshl_add_u64 v[38:39], v[26:27], 0, v[116:117]
	s_waitcnt lgkmcnt(0)
	s_barrier
	v_lshl_add_u64 v[36:37], v[24:25], 0, v[28:29]
	global_load_dwordx4 v[24:27], v[38:39], off offset:48
	global_load_dwordx4 v[28:31], v[38:39], off offset:32
	global_load_dwordx4 v[32:35], v[38:39], off offset:16
	global_load_dwordx4 v[40:43], v[38:39], off
	v_lshl_add_u64 v[36:37], v[36:37], 0, v[116:117]
	v_subrev_u32_e32 v98, s3, v98
	s_movk_i32 s70, 0x7c
	v_mul_lo_u32 v119, v98, s70
	v_lshl_add_u32 v118, v59, 2, v119
	s_waitcnt vmcnt(0)
	v_cvt_pk_bf16_f32 v42, v42, v42
	v_cvt_pk_bf16_f32 v40, v40, v40
	v_cvt_pk_bf16_f32 v43, v43, v43
	v_cvt_pk_bf16_f32 v41, v41, v41
	v_and_b32_e32 v43, 0xffff0000, v43
	v_and_b32_e32 v44, 0xffff0000, v41
	v_or_b32_sdwa v41, v43, v42 dst_sel:DWORD dst_unused:UNUSED_PAD src0_sel:DWORD src1_sel:WORD_1
	v_cvt_pk_bf16_f32 v32, v32, v32
	v_cvt_pk_bf16_f32 v33, v33, v33
	v_cvt_pk_bf16_f32 v34, v34, v34
	v_and_b32_e32 v33, 0xffff0000, v33
	v_cvt_pk_bf16_f32 v35, v35, v35
	v_or_b32_sdwa v42, v33, v32 dst_sel:DWORD dst_unused:UNUSED_PAD src0_sel:DWORD src1_sel:WORD_1
	v_cvt_pk_bf16_f32 v30, v30, v30
	v_cvt_pk_bf16_f32 v28, v28, v28
	v_cvt_pk_bf16_f32 v31, v31, v31
	v_cvt_pk_bf16_f32 v29, v29, v29
	v_and_b32_e32 v31, 0xffff0000, v31
	v_and_b32_e32 v32, 0xffff0000, v29
	v_or_b32_sdwa v29, v31, v30 dst_sel:DWORD dst_unused:UNUSED_PAD src0_sel:DWORD src1_sel:WORD_1
	v_cvt_pk_bf16_f32 v24, v24, v24
	v_cvt_pk_bf16_f32 v26, v26, v26
	v_cvt_pk_bf16_f32 v27, v27, v27
	v_cvt_pk_bf16_f32 v25, v25, v25
	v_and_b32_e32 v35, 0xffff0000, v35
	v_and_b32_e32 v27, 0xffff0000, v27
	v_and_b32_e32 v25, 0xffff0000, v25
	v_or_b32_sdwa v40, v44, v40 dst_sel:DWORD dst_unused:UNUSED_PAD src0_sel:DWORD src1_sel:WORD_1
	v_or_b32_sdwa v43, v35, v34 dst_sel:DWORD dst_unused:UNUSED_PAD src0_sel:DWORD src1_sel:WORD_1
	v_or_b32_sdwa v28, v32, v28 dst_sel:DWORD dst_unused:UNUSED_PAD src0_sel:DWORD src1_sel:WORD_1
	v_or_b32_sdwa v31, v27, v26 dst_sel:DWORD dst_unused:UNUSED_PAD src0_sel:DWORD src1_sel:WORD_1
	v_or_b32_sdwa v30, v25, v24 dst_sel:DWORD dst_unused:UNUSED_PAD src0_sel:DWORD src1_sel:WORD_1
	ds_write_b128 v83, v[40:43]
	ds_write_b128 v84, v[28:31]
	global_load_dwordx4 v[24:27], v[38:39], off offset:112
	global_load_dwordx4 v[28:31], v[38:39], off offset:96
	global_load_dwordx4 v[32:35], v[38:39], off offset:80
	s_nop 0
	global_load_dwordx4 v[38:41], v[38:39], off offset:64
	s_waitcnt vmcnt(0)
	v_cvt_pk_bf16_f32 v40, v40, v40
	v_cvt_pk_bf16_f32 v38, v38, v38
	v_cvt_pk_bf16_f32 v41, v41, v41
	v_cvt_pk_bf16_f32 v39, v39, v39
	v_and_b32_e32 v41, 0xffff0000, v41
	v_and_b32_e32 v42, 0xffff0000, v39
	v_or_b32_sdwa v39, v41, v40 dst_sel:DWORD dst_unused:UNUSED_PAD src0_sel:DWORD src1_sel:WORD_1
	v_cvt_pk_bf16_f32 v32, v32, v32
	v_cvt_pk_bf16_f32 v33, v33, v33
	v_cvt_pk_bf16_f32 v34, v34, v34
	v_and_b32_e32 v33, 0xffff0000, v33
	v_cvt_pk_bf16_f32 v35, v35, v35
	v_or_b32_sdwa v40, v33, v32 dst_sel:DWORD dst_unused:UNUSED_PAD src0_sel:DWORD src1_sel:WORD_1
	v_cvt_pk_bf16_f32 v30, v30, v30
	v_cvt_pk_bf16_f32 v28, v28, v28
	v_cvt_pk_bf16_f32 v31, v31, v31
	v_cvt_pk_bf16_f32 v29, v29, v29
	v_and_b32_e32 v31, 0xffff0000, v31
	v_and_b32_e32 v32, 0xffff0000, v29
	v_or_b32_sdwa v29, v31, v30 dst_sel:DWORD dst_unused:UNUSED_PAD src0_sel:DWORD src1_sel:WORD_1
	v_cvt_pk_bf16_f32 v24, v24, v24
	v_cvt_pk_bf16_f32 v26, v26, v26
	v_cvt_pk_bf16_f32 v27, v27, v27
	v_cvt_pk_bf16_f32 v25, v25, v25
	v_and_b32_e32 v35, 0xffff0000, v35
	v_and_b32_e32 v27, 0xffff0000, v27
	v_and_b32_e32 v25, 0xffff0000, v25
	v_or_b32_sdwa v38, v42, v38 dst_sel:DWORD dst_unused:UNUSED_PAD src0_sel:DWORD src1_sel:WORD_1
	v_or_b32_sdwa v41, v35, v34 dst_sel:DWORD dst_unused:UNUSED_PAD src0_sel:DWORD src1_sel:WORD_1
	v_or_b32_sdwa v28, v32, v28 dst_sel:DWORD dst_unused:UNUSED_PAD src0_sel:DWORD src1_sel:WORD_1
	v_or_b32_sdwa v31, v27, v26 dst_sel:DWORD dst_unused:UNUSED_PAD src0_sel:DWORD src1_sel:WORD_1
	v_or_b32_sdwa v30, v25, v24 dst_sel:DWORD dst_unused:UNUSED_PAD src0_sel:DWORD src1_sel:WORD_1
	ds_write_b128 v85, v[38:41]
	ds_write_b128 v86, v[28:31]
	global_load_dwordx4 v[24:27], v[36:37], off offset:48
	global_load_dwordx4 v[28:31], v[36:37], off offset:32
	global_load_dwordx4 v[32:35], v[36:37], off offset:16
	global_load_dwordx4 v[38:41], v[36:37], off
	s_waitcnt vmcnt(0)
	v_cvt_pk_bf16_f32 v38, v38, v38
	ds_write_b16_d16_hi v87, v38 offset:16384
	v_cvt_pk_bf16_f32 v38, v39, v39
	ds_write_b16_d16_hi v87, v38 offset:20736
	v_cvt_pk_bf16_f32 v38, v40, v40
	ds_write_b16_d16_hi v87, v38 offset:25088
	v_cvt_pk_bf16_f32 v38, v41, v41
	ds_write_b16_d16_hi v87, v38 offset:29440
	v_cvt_pk_bf16_f32 v32, v32, v32
	ds_write_b16_d16_hi v87, v32 offset:16656
	v_cvt_pk_bf16_f32 v32, v33, v33
	ds_write_b16_d16_hi v87, v32 offset:21008
	v_cvt_pk_bf16_f32 v32, v34, v34
	ds_write_b16_d16_hi v87, v32 offset:25360
	v_cvt_pk_bf16_f32 v32, v35, v35
	ds_write_b16_d16_hi v87, v32 offset:29712
	v_cvt_pk_bf16_f32 v28, v28, v28
	ds_write_b16_d16_hi v87, v28 offset:16928
	v_cvt_pk_bf16_f32 v28, v29, v29
	ds_write_b16_d16_hi v87, v28 offset:21280
	v_cvt_pk_bf16_f32 v28, v30, v30
	ds_write_b16_d16_hi v87, v28 offset:25632
	v_cvt_pk_bf16_f32 v28, v31, v31
	ds_write_b16_d16_hi v87, v28 offset:29984
	v_cvt_pk_bf16_f32 v24, v24, v24
	ds_write_b16_d16_hi v87, v24 offset:17200
	v_cvt_pk_bf16_f32 v24, v25, v25
	ds_write_b16_d16_hi v87, v24 offset:21552
	v_cvt_pk_bf16_f32 v24, v26, v26
	ds_write_b16_d16_hi v87, v24 offset:25904
	v_cvt_pk_bf16_f32 v24, v27, v27
	ds_write_b16_d16_hi v87, v24 offset:30256
	global_load_dwordx4 v[24:27], v[36:37], off offset:112
	global_load_dwordx4 v[28:31], v[36:37], off offset:96
	global_load_dwordx4 v[32:35], v[36:37], off offset:80
	s_nop 0
	global_load_dwordx4 v[36:39], v[36:37], off offset:64
	s_waitcnt vmcnt(0)
	v_cvt_pk_bf16_f32 v36, v36, v36
	ds_write_b16_d16_hi v87, v36 offset:17472
	v_cvt_pk_bf16_f32 v36, v37, v37
	ds_write_b16_d16_hi v87, v36 offset:21824
	v_cvt_pk_bf16_f32 v36, v38, v38
	ds_write_b16_d16_hi v87, v36 offset:26176
	v_cvt_pk_bf16_f32 v36, v39, v39
	ds_write_b16_d16_hi v87, v36 offset:30528
	v_cvt_pk_bf16_f32 v32, v32, v32
	ds_write_b16_d16_hi v87, v32 offset:17744
	v_cvt_pk_bf16_f32 v32, v33, v33
	ds_write_b16_d16_hi v87, v32 offset:22096
	v_cvt_pk_bf16_f32 v32, v34, v34
	ds_write_b16_d16_hi v87, v32 offset:26448
	v_cvt_pk_bf16_f32 v32, v35, v35
	ds_write_b16_d16_hi v87, v32 offset:30800
	v_cvt_pk_bf16_f32 v28, v28, v28
	ds_write_b16_d16_hi v87, v28 offset:18016
	v_cvt_pk_bf16_f32 v28, v29, v29
	ds_write_b16_d16_hi v87, v28 offset:22368
	v_cvt_pk_bf16_f32 v28, v30, v30
	ds_write_b16_d16_hi v87, v28 offset:26720
	v_cvt_pk_bf16_f32 v28, v31, v31
	ds_write_b16_d16_hi v87, v28 offset:31072
	v_cvt_pk_bf16_f32 v24, v24, v24
	ds_write_b16_d16_hi v87, v24 offset:18288
	v_cvt_pk_bf16_f32 v24, v25, v25
	ds_write_b16_d16_hi v87, v24 offset:22640
	v_cvt_pk_bf16_f32 v24, v26, v26
	ds_write_b16_d16_hi v87, v24 offset:26992
	v_cvt_pk_bf16_f32 v24, v27, v27
	ds_write_b16_d16_hi v87, v24 offset:31344
	s_waitcnt lgkmcnt(0)
	s_barrier
	ds_read_b128 v[24:27], v88
	ds_read_b128 v[28:31], v89
	s_waitcnt lgkmcnt(1)
	v_mfma_f32_16x16x32_bf16 v[24:27], v[0:3], v[24:27], 0
	ds_read_b128 v[100:103], v89 offset:14336
	s_waitcnt lgkmcnt(1)
	v_mfma_f32_16x16x32_bf16 v[52:55], v[4:7], v[28:31], v[24:27]
	ds_read_b128 v[28:31], v89 offset:2048
	s_nop 3
	ds_read_b128 v[24:27], v88 offset:2048
	s_waitcnt lgkmcnt(0)
	v_mfma_f32_16x16x32_bf16 v[24:27], v[0:3], v[24:27], 0
	v_mfma_f32_16x16x32_bf16 v[48:51], v[4:7], v[28:31], v[24:27]
	ds_read_b128 v[28:31], v89 offset:4096
	s_nop 5
	ds_read_b128 v[24:27], v88 offset:4096
	s_waitcnt lgkmcnt(0)
	v_mfma_f32_16x16x32_bf16 v[24:27], v[0:3], v[24:27], 0
	v_mfma_f32_16x16x32_bf16 v[44:47], v[4:7], v[28:31], v[24:27]
	ds_read_b128 v[28:31], v89 offset:6144
	s_nop 5
	ds_read_b128 v[24:27], v88 offset:6144
	s_waitcnt lgkmcnt(0)
	v_mfma_f32_16x16x32_bf16 v[24:27], v[0:3], v[24:27], 0
	v_mfma_f32_16x16x32_bf16 v[40:43], v[4:7], v[28:31], v[24:27]
	ds_read_b128 v[28:31], v89 offset:8192
	s_nop 5
	ds_read_b128 v[24:27], v88 offset:8192
	s_waitcnt lgkmcnt(0)
	v_mfma_f32_16x16x32_bf16 v[24:27], v[0:3], v[24:27], 0
	v_mfma_f32_16x16x32_bf16 v[36:39], v[4:7], v[28:31], v[24:27]
	ds_read_b128 v[28:31], v89 offset:10240
	s_nop 5
	ds_read_b128 v[24:27], v88 offset:10240
	s_waitcnt lgkmcnt(0)
	v_mfma_f32_16x16x32_bf16 v[24:27], v[0:3], v[24:27], 0
	v_mfma_f32_16x16x32_bf16 v[32:35], v[4:7], v[28:31], v[24:27]
	ds_read_b128 v[28:31], v89 offset:12288
	s_nop 5
	ds_read_b128 v[24:27], v88 offset:12288
	s_waitcnt lgkmcnt(0)
	v_mfma_f32_16x16x32_bf16 v[24:27], v[0:3], v[24:27], 0
	v_mfma_f32_16x16x32_bf16 v[28:31], v[4:7], v[28:31], v[24:27]
	s_nop 6
	ds_read_b128 v[24:27], v88 offset:14336
	s_waitcnt lgkmcnt(0)
	v_mfma_f32_16x16x32_bf16 v[24:27], v[0:3], v[24:27], 0
	v_mfma_f32_16x16x32_bf16 v[24:27], v[4:7], v[100:103], v[24:27]
	v_mul_f32_e32 v100, 0x3e000000, v52
	v_cndmask_b32_e64 v52, 0, 1, vcc
	v_cmp_ne_u32_e64 s[70:71], 1, v52
	s_andn2_b64 vcc, exec, vcc
	s_cbranch_vccz .LBB0_689
	v_mul_f32_e32 v99, 0x3e000000, v53
	s_and_b64 vcc, exec, s[70:71]
	v_lshl_add_u32 v102, v66, 2, v119
	s_cbranch_vccz .LBB0_690

.LBB0_721:
	v_div_scale_f32 v1, s[20:21], v63, v63, 1.0
	v_rcp_f32_e32 v2, v1
	v_or_b32_e32 v0, v64, v65
	v_mov_b32_e32 v6, v8
	s_nop 0
	v_mov_b32_e32 v7, v16
	v_fma_f32 v3, -v1, v2, 1.0
	v_fmac_f32_e32 v2, v3, v2
	v_div_scale_f32 v3, vcc, 1.0, v63, 1.0
	v_mul_f32_e32 v4, v3, v2
	v_fma_f32 v5, -v1, v4, v3
	v_fmac_f32_e32 v4, v5, v2
	v_fma_f32 v1, -v1, v4, v3
	v_div_fmas_f32 v1, v1, v2, v4
	v_div_fixup_f32 v2, v1, v63, 1.0
	v_ashrrev_i32_e32 v1, 31, v0
	v_pk_mul_f32 v[6:7], v[2:3], v[6:7] op_sel_hi:[0,1]
	v_mov_b32_e32 v24, v12
	v_mov_b32_e32 v25, v20
	v_lshlrev_b64 v[4:5], 11, v[0:1]
	v_pk_mul_f32 v[2:3], v[2:3], v[24:25] op_sel_hi:[0,1]
	v_cvt_pk_bf16_f32 v1, v7, v7
	s_lshl_b32 s36, s2, 1
	v_cvt_pk_bf16_f32 v6, v6, v6
	v_cvt_pk_bf16_f32 v3, v3, v3
	v_div_scale_f32 v7, s[2:3], v62, v62, 1.0
	v_cvt_pk_bf16_f32 v2, v2, v2
	v_rcp_f32_e32 v8, v7
	v_lshl_add_u64 v[4:5], s[80:81], 0, v[4:5]
	v_and_b32_e32 v3, 0xffff0000, v3
	v_lshl_add_u64 v[4:5], v[4:5], 0, s[36:37]
	v_lshlrev_b32_e32 v116, 3, v57
	v_and_b32_e32 v2, 0xffff0000, v2
	v_or_b32_sdwa v3, v3, v1 dst_sel:DWORD dst_unused:UNUSED_PAD src0_sel:DWORD src1_sel:WORD_1
	v_fma_f32 v1, -v7, v8, 1.0
	v_lshl_add_u64 v[4:5], v[4:5], 0, v[116:117]
	v_or_b32_sdwa v2, v2, v6 dst_sel:DWORD dst_unused:UNUSED_PAD src0_sel:DWORD src1_sel:WORD_1
	v_fmac_f32_e32 v8, v1, v8
	v_div_scale_f32 v1, vcc, 1.0, v62, 1.0
	global_store_dwordx2 v[4:5], v[2:3], off
	v_mul_f32_e32 v2, v1, v8
	v_fma_f32 v3, -v7, v2, v1
	v_fmac_f32_e32 v2, v3, v8
	v_fma_f32 v1, -v7, v2, v1
	v_div_fmas_f32 v1, v1, v8, v2
	v_div_fixup_f32 v2, v1, v62, 1.0
	v_mov_b32_e32 v16, v9
	v_pk_mul_f32 v[6:7], v[2:3], v[16:17] op_sel_hi:[0,1]
	v_mov_b32_e32 v20, v13
	v_pk_mul_f32 v[2:3], v[2:3], v[20:21] op_sel_hi:[0,1]
	v_cvt_pk_bf16_f32 v1, v7, v7
	v_cvt_pk_bf16_f32 v6, v6, v6
	v_cvt_pk_bf16_f32 v3, v3, v3
	v_div_scale_f32 v7, s[2:3], v61, v61, 1.0
	v_or_b32_e32 v4, 1, v0
	v_cvt_pk_bf16_f32 v2, v2, v2
	v_rcp_f32_e32 v8, v7
	v_ashrrev_i32_e32 v5, 31, v4
	v_lshlrev_b64 v[4:5], 11, v[4:5]
	v_lshl_add_u64 v[4:5], s[80:81], 0, v[4:5]
	v_and_b32_e32 v3, 0xffff0000, v3
	v_lshl_add_u64 v[4:5], v[4:5], 0, s[36:37]
	v_and_b32_e32 v2, 0xffff0000, v2
	v_or_b32_sdwa v3, v3, v1 dst_sel:DWORD dst_unused:UNUSED_PAD src0_sel:DWORD src1_sel:WORD_1
	v_fma_f32 v1, -v7, v8, 1.0
	v_lshl_add_u64 v[4:5], v[4:5], 0, v[116:117]
	v_or_b32_sdwa v2, v2, v6 dst_sel:DWORD dst_unused:UNUSED_PAD src0_sel:DWORD src1_sel:WORD_1
	v_fmac_f32_e32 v8, v1, v8
	v_div_scale_f32 v1, vcc, 1.0, v61, 1.0
	global_store_dwordx2 v[4:5], v[2:3], off
	v_mul_f32_e32 v2, v1, v8
	v_fma_f32 v3, -v7, v2, v1
	v_fmac_f32_e32 v2, v3, v8
	v_fma_f32 v1, -v7, v2, v1
	v_div_fmas_f32 v1, v1, v8, v2
	v_div_fixup_f32 v2, v1, v61, 1.0
	v_mov_b32_e32 v6, v10
	v_mov_b32_e32 v7, v18
	v_pk_mul_f32 v[6:7], v[2:3], v[6:7] op_sel_hi:[0,1]
	v_mov_b32_e32 v8, v14
	v_mov_b32_e32 v9, v22
	v_pk_mul_f32 v[2:3], v[2:3], v[8:9] op_sel_hi:[0,1]
	v_cvt_pk_bf16_f32 v1, v7, v7
	v_cvt_pk_bf16_f32 v6, v6, v6
	v_cvt_pk_bf16_f32 v3, v3, v3
	v_div_scale_f32 v7, s[2:3], v60, v60, 1.0
	v_or_b32_e32 v4, 2, v0
	v_cvt_pk_bf16_f32 v2, v2, v2
	v_rcp_f32_e32 v8, v7
	v_ashrrev_i32_e32 v5, 31, v4
	v_lshlrev_b64 v[4:5], 11, v[4:5]
	v_lshl_add_u64 v[4:5], s[80:81], 0, v[4:5]
	v_and_b32_e32 v3, 0xffff0000, v3
	v_lshl_add_u64 v[4:5], v[4:5], 0, s[36:37]
	v_and_b32_e32 v2, 0xffff0000, v2
	v_or_b32_sdwa v3, v3, v1 dst_sel:DWORD dst_unused:UNUSED_PAD src0_sel:DWORD src1_sel:WORD_1
	v_fma_f32 v1, -v7, v8, 1.0
	v_lshl_add_u64 v[4:5], v[4:5], 0, v[116:117]
	v_or_b32_sdwa v2, v2, v6 dst_sel:DWORD dst_unused:UNUSED_PAD src0_sel:DWORD src1_sel:WORD_1
	v_fmac_f32_e32 v8, v1, v8
	v_div_scale_f32 v1, vcc, 1.0, v60, 1.0
	global_store_dwordx2 v[4:5], v[2:3], off
	v_mul_f32_e32 v2, v1, v8
	v_fma_f32 v3, -v7, v2, v1
	v_fmac_f32_e32 v2, v3, v8
	v_fma_f32 v1, -v7, v2, v1
	v_div_fmas_f32 v1, v1, v8, v2
	v_div_fixup_f32 v2, v1, v60, 1.0
	v_mov_b32_e32 v18, v11
	v_or_b32_e32 v0, 3, v0
	v_pk_mul_f32 v[4:5], v[2:3], v[18:19] op_sel_hi:[0,1]
	v_mov_b32_e32 v22, v15
	v_ashrrev_i32_e32 v1, 31, v0
	v_pk_mul_f32 v[2:3], v[2:3], v[22:23] op_sel_hi:[0,1]
	v_lshlrev_b64 v[0:1], 11, v[0:1]
	v_cvt_pk_bf16_f32 v4, v4, v4
	v_cvt_pk_bf16_f32 v5, v5, v5
	v_and_b32_sdwa v6, v3, v129 dst_sel:DWORD dst_unused:UNUSED_PAD src0_sel:WORD_1 src1_sel:DWORD
	v_and_b32_sdwa v7, v2, v129 dst_sel:DWORD dst_unused:UNUSED_PAD src0_sel:WORD_1 src1_sel:DWORD
	v_lshl_add_u64 v[0:1], s[80:81], 0, v[0:1]
	v_cvt_pk_bf16_f32 v3, v3, v3
	v_cvt_pk_bf16_f32 v2, v2, v2
	v_lshl_add_u64 v[0:1], v[0:1], 0, s[36:37]
	v_and_b32_e32 v3, 0xffff0000, v3
	v_and_b32_e32 v2, 0xffff0000, v2
	v_readlane_b32 s68, v162, 32
	v_lshl_add_u64 v[0:1], v[0:1], 0, v[116:117]
	v_or_b32_sdwa v3, v3, v5 dst_sel:DWORD dst_unused:UNUSED_PAD src0_sel:DWORD src1_sel:WORD_1
	v_or_b32_sdwa v2, v2, v4 dst_sel:DWORD dst_unused:UNUSED_PAD src0_sel:DWORD src1_sel:WORD_1
	v_readlane_b32 s69, v162, 33
	v_readlane_b32 s70, v162, 34
	v_readlane_b32 s71, v162, 35
	global_store_dwordx2 v[0:1], v[2:3], off

.LBB0_805:
	s_mov_b32 s66, 0x1000
	s_mov_b32 s67, 0
	v_mov_b32_e32 v232, v40
	v_mov_b32_e32 v233, v41
	v_mov_b32_e32 v216, 0
	v_mov_b32_e32 v217, 0
	v_mov_b32_e32 v218, 0
	v_mov_b32_e32 v219, 0
	v_mov_b32_e32 v220, 0
	v_mov_b32_e32 v221, 0
	v_mov_b32_e32 v222, 0
	v_mov_b32_e32 v223, 0
	v_mov_b32_e32 v224, 0
	v_mov_b32_e32 v225, 0
	v_mov_b32_e32 v226, 0
	v_mov_b32_e32 v227, 0
	v_mov_b32_e32 v228, 0
	v_mov_b32_e32 v229, 0
	v_mov_b32_e32 v230, 0
	v_mov_b32_e32 v231, 0
	global_load_dwordx4 v[168:171], v[232:233], off offset:-2048
	global_load_dwordx4 v[172:175], v[232:233], off offset:-1024
	global_load_dwordx4 v[176:179], v[232:233], off offset:0
	global_load_dwordx4 v[180:183], v[232:233], off offset:1024
	v_lshl_add_u64 v[232:233], v[232:233], 0, s[66:67]
	global_load_dwordx4 v[184:187], v[232:233], off offset:-2048
	global_load_dwordx4 v[188:191], v[232:233], off offset:-1024
	global_load_dwordx4 v[192:195], v[232:233], off offset:0
	global_load_dwordx4 v[196:199], v[232:233], off offset:1024
	v_lshl_add_u64 v[232:233], v[232:233], 0, s[66:67]
	global_load_dwordx4 v[200:203], v[232:233], off offset:-2048
	global_load_dwordx4 v[204:207], v[232:233], off offset:-1024
	global_load_dwordx4 v[208:211], v[232:233], off offset:0
	s_waitcnt vmcnt(10)
	v_readlane_b32 s50, v11, 0
	v_readlane_b32 s52, v54, 0
	v_readlane_b32 s54, v55, 0
	v_readlane_b32 s56, v56, 0
	v_pk_fma_f32 v[216:217], v[168:169], s[50:51], v[216:217] op_sel_hi:[1,0,1]
	v_pk_fma_f32 v[218:219], v[170:171], s[50:51], v[218:219] op_sel_hi:[1,0,1]
	v_pk_fma_f32 v[220:221], v[168:169], s[52:53], v[220:221] op_sel_hi:[1,0,1]
	v_pk_fma_f32 v[222:223], v[170:171], s[52:53], v[222:223] op_sel_hi:[1,0,1]
	v_pk_fma_f32 v[224:225], v[168:169], s[54:55], v[224:225] op_sel_hi:[1,0,1]
	v_pk_fma_f32 v[226:227], v[170:171], s[54:55], v[226:227] op_sel_hi:[1,0,1]
	v_pk_fma_f32 v[228:229], v[168:169], s[56:57], v[228:229] op_sel_hi:[1,0,1]
	v_pk_fma_f32 v[230:231], v[170:171], s[56:57], v[230:231] op_sel_hi:[1,0,1]
	global_load_dwordx4 v[212:215], v[232:233], off offset:1024
	v_lshl_add_u64 v[232:233], v[232:233], 0, s[66:67]
	s_waitcnt vmcnt(10)
	v_readlane_b32 s50, v11, 1
	v_readlane_b32 s52, v54, 1
	v_readlane_b32 s54, v55, 1
	v_readlane_b32 s56, v56, 1
	v_pk_fma_f32 v[216:217], v[172:173], s[50:51], v[216:217] op_sel_hi:[1,0,1]
	v_pk_fma_f32 v[218:219], v[174:175], s[50:51], v[218:219] op_sel_hi:[1,0,1]
	v_pk_fma_f32 v[220:221], v[172:173], s[52:53], v[220:221] op_sel_hi:[1,0,1]
	v_pk_fma_f32 v[222:223], v[174:175], s[52:53], v[222:223] op_sel_hi:[1,0,1]
	v_pk_fma_f32 v[224:225], v[172:173], s[54:55], v[224:225] op_sel_hi:[1,0,1]
	v_pk_fma_f32 v[226:227], v[174:175], s[54:55], v[226:227] op_sel_hi:[1,0,1]
	v_pk_fma_f32 v[228:229], v[172:173], s[56:57], v[228:229] op_sel_hi:[1,0,1]
	v_pk_fma_f32 v[230:231], v[174:175], s[56:57], v[230:231] op_sel_hi:[1,0,1]
	global_load_dwordx4 v[168:171], v[232:233], off offset:-2048
	s_waitcnt vmcnt(10)
	v_readlane_b32 s50, v11, 2
	v_readlane_b32 s52, v54, 2
	v_readlane_b32 s54, v55, 2
	v_readlane_b32 s56, v56, 2
	v_pk_fma_f32 v[216:217], v[176:177], s[50:51], v[216:217] op_sel_hi:[1,0,1]
	v_pk_fma_f32 v[218:219], v[178:179], s[50:51], v[218:219] op_sel_hi:[1,0,1]
	v_pk_fma_f32 v[220:221], v[176:177], s[52:53], v[220:221] op_sel_hi:[1,0,1]
	v_pk_fma_f32 v[222:223], v[178:179], s[52:53], v[222:223] op_sel_hi:[1,0,1]
	v_pk_fma_f32 v[224:225], v[176:177], s[54:55], v[224:225] op_sel_hi:[1,0,1]
	v_pk_fma_f32 v[226:227], v[178:179], s[54:55], v[226:227] op_sel_hi:[1,0,1]
	v_pk_fma_f32 v[228:229], v[176:177], s[56:57], v[228:229] op_sel_hi:[1,0,1]
	v_pk_fma_f32 v[230:231], v[178:179], s[56:57], v[230:231] op_sel_hi:[1,0,1]
	global_load_dwordx4 v[172:175], v[232:233], off offset:-1024
	s_waitcnt vmcnt(10)
	v_readlane_b32 s50, v11, 3
	v_readlane_b32 s52, v54, 3
	v_readlane_b32 s54, v55, 3
	v_readlane_b32 s56, v56, 3
	v_pk_fma_f32 v[216:217], v[180:181], s[50:51], v[216:217] op_sel_hi:[1,0,1]
	v_pk_fma_f32 v[218:219], v[182:183], s[50:51], v[218:219] op_sel_hi:[1,0,1]
	v_pk_fma_f32 v[220:221], v[180:181], s[52:53], v[220:221] op_sel_hi:[1,0,1]
	v_pk_fma_f32 v[222:223], v[182:183], s[52:53], v[222:223] op_sel_hi:[1,0,1]
	v_pk_fma_f32 v[224:225], v[180:181], s[54:55], v[224:225] op_sel_hi:[1,0,1]
	v_pk_fma_f32 v[226:227], v[182:183], s[54:55], v[226:227] op_sel_hi:[1,0,1]
	v_pk_fma_f32 v[228:229], v[180:181], s[56:57], v[228:229] op_sel_hi:[1,0,1]
	v_pk_fma_f32 v[230:231], v[182:183], s[56:57], v[230:231] op_sel_hi:[1,0,1]
	global_load_dwordx4 v[176:179], v[232:233], off offset:0
	s_waitcnt vmcnt(10)
	v_readlane_b32 s50, v11, 4
	v_readlane_b32 s52, v54, 4
	v_readlane_b32 s54, v55, 4
	v_readlane_b32 s56, v56, 4
	v_pk_fma_f32 v[216:217], v[184:185], s[50:51], v[216:217] op_sel_hi:[1,0,1]
	v_pk_fma_f32 v[218:219], v[186:187], s[50:51], v[218:219] op_sel_hi:[1,0,1]
	v_pk_fma_f32 v[220:221], v[184:185], s[52:53], v[220:221] op_sel_hi:[1,0,1]
	v_pk_fma_f32 v[222:223], v[186:187], s[52:53], v[222:223] op_sel_hi:[1,0,1]
	v_pk_fma_f32 v[224:225], v[184:185], s[54:55], v[224:225] op_sel_hi:[1,0,1]
	v_pk_fma_f32 v[226:227], v[186:187], s[54:55], v[226:227] op_sel_hi:[1,0,1]
	v_pk_fma_f32 v[228:229], v[184:185], s[56:57], v[228:229] op_sel_hi:[1,0,1]
	v_pk_fma_f32 v[230:231], v[186:187], s[56:57], v[230:231] op_sel_hi:[1,0,1]
	global_load_dwordx4 v[180:183], v[232:233], off offset:1024
	v_lshl_add_u64 v[232:233], v[232:233], 0, s[66:67]
	s_waitcnt vmcnt(10)
	v_readlane_b32 s50, v11, 5
	v_readlane_b32 s52, v54, 5
	v_readlane_b32 s54, v55, 5
	v_readlane_b32 s56, v56, 5
	v_pk_fma_f32 v[216:217], v[188:189], s[50:51], v[216:217] op_sel_hi:[1,0,1]
	v_pk_fma_f32 v[218:219], v[190:191], s[50:51], v[218:219] op_sel_hi:[1,0,1]
	v_pk_fma_f32 v[220:221], v[188:189], s[52:53], v[220:221] op_sel_hi:[1,0,1]
	v_pk_fma_f32 v[222:223], v[190:191], s[52:53], v[222:223] op_sel_hi:[1,0,1]
	v_pk_fma_f32 v[224:225], v[188:189], s[54:55], v[224:225] op_sel_hi:[1,0,1]
	v_pk_fma_f32 v[226:227], v[190:191], s[54:55], v[226:227] op_sel_hi:[1,0,1]
	v_pk_fma_f32 v[228:229], v[188:189], s[56:57], v[228:229] op_sel_hi:[1,0,1]
	v_pk_fma_f32 v[230:231], v[190:191], s[56:57], v[230:231] op_sel_hi:[1,0,1]
	global_load_dwordx4 v[184:187], v[232:233], off offset:-2048
	s_waitcnt vmcnt(10)
	v_readlane_b32 s50, v11, 6
	v_readlane_b32 s52, v54, 6
	v_readlane_b32 s54, v55, 6
	v_readlane_b32 s56, v56, 6
	v_pk_fma_f32 v[216:217], v[192:193], s[50:51], v[216:217] op_sel_hi:[1,0,1]
	v_pk_fma_f32 v[218:219], v[194:195], s[50:51], v[218:219] op_sel_hi:[1,0,1]
	v_pk_fma_f32 v[220:221], v[192:193], s[52:53], v[220:221] op_sel_hi:[1,0,1]
	v_pk_fma_f32 v[222:223], v[194:195], s[52:53], v[222:223] op_sel_hi:[1,0,1]
	v_pk_fma_f32 v[224:225], v[192:193], s[54:55], v[224:225] op_sel_hi:[1,0,1]
	v_pk_fma_f32 v[226:227], v[194:195], s[54:55], v[226:227] op_sel_hi:[1,0,1]
	v_pk_fma_f32 v[228:229], v[192:193], s[56:57], v[228:229] op_sel_hi:[1,0,1]
	v_pk_fma_f32 v[230:231], v[194:195], s[56:57], v[230:231] op_sel_hi:[1,0,1]
	global_load_dwordx4 v[188:191], v[232:233], off offset:-1024
	s_waitcnt vmcnt(10)
	v_readlane_b32 s50, v11, 7
	v_readlane_b32 s52, v54, 7
	v_readlane_b32 s54, v55, 7
	v_readlane_b32 s56, v56, 7
	v_pk_fma_f32 v[216:217], v[196:197], s[50:51], v[216:217] op_sel_hi:[1,0,1]
	v_pk_fma_f32 v[218:219], v[198:199], s[50:51], v[218:219] op_sel_hi:[1,0,1]
	v_pk_fma_f32 v[220:221], v[196:197], s[52:53], v[220:221] op_sel_hi:[1,0,1]
	v_pk_fma_f32 v[222:223], v[198:199], s[52:53], v[222:223] op_sel_hi:[1,0,1]
	v_pk_fma_f32 v[224:225], v[196:197], s[54:55], v[224:225] op_sel_hi:[1,0,1]
	v_pk_fma_f32 v[226:227], v[198:199], s[54:55], v[226:227] op_sel_hi:[1,0,1]
	v_pk_fma_f32 v[228:229], v[196:197], s[56:57], v[228:229] op_sel_hi:[1,0,1]
	v_pk_fma_f32 v[230:231], v[198:199], s[56:57], v[230:231] op_sel_hi:[1,0,1]
	global_load_dwordx4 v[192:195], v[232:233], off offset:0
	s_waitcnt vmcnt(10)
	v_readlane_b32 s50, v11, 8
	v_readlane_b32 s52, v54, 8
	v_readlane_b32 s54, v55, 8
	v_readlane_b32 s56, v56, 8
	v_pk_fma_f32 v[216:217], v[200:201], s[50:51], v[216:217] op_sel_hi:[1,0,1]
	v_pk_fma_f32 v[218:219], v[202:203], s[50:51], v[218:219] op_sel_hi:[1,0,1]
	v_pk_fma_f32 v[220:221], v[200:201], s[52:53], v[220:221] op_sel_hi:[1,0,1]
	v_pk_fma_f32 v[222:223], v[202:203], s[52:53], v[222:223] op_sel_hi:[1,0,1]
	v_pk_fma_f32 v[224:225], v[200:201], s[54:55], v[224:225] op_sel_hi:[1,0,1]
	v_pk_fma_f32 v[226:227], v[202:203], s[54:55], v[226:227] op_sel_hi:[1,0,1]
	v_pk_fma_f32 v[228:229], v[200:201], s[56:57], v[228:229] op_sel_hi:[1,0,1]
	v_pk_fma_f32 v[230:231], v[202:203], s[56:57], v[230:231] op_sel_hi:[1,0,1]
	global_load_dwordx4 v[196:199], v[232:233], off offset:1024
	v_lshl_add_u64 v[232:233], v[232:233], 0, s[66:67]
	s_waitcnt vmcnt(10)
	v_readlane_b32 s50, v11, 9
	v_readlane_b32 s52, v54, 9
	v_readlane_b32 s54, v55, 9
	v_readlane_b32 s56, v56, 9
	v_pk_fma_f32 v[216:217], v[204:205], s[50:51], v[216:217] op_sel_hi:[1,0,1]
	v_pk_fma_f32 v[218:219], v[206:207], s[50:51], v[218:219] op_sel_hi:[1,0,1]
	v_pk_fma_f32 v[220:221], v[204:205], s[52:53], v[220:221] op_sel_hi:[1,0,1]
	v_pk_fma_f32 v[222:223], v[206:207], s[52:53], v[222:223] op_sel_hi:[1,0,1]
	v_pk_fma_f32 v[224:225], v[204:205], s[54:55], v[224:225] op_sel_hi:[1,0,1]
	v_pk_fma_f32 v[226:227], v[206:207], s[54:55], v[226:227] op_sel_hi:[1,0,1]
	v_pk_fma_f32 v[228:229], v[204:205], s[56:57], v[228:229] op_sel_hi:[1,0,1]
	v_pk_fma_f32 v[230:231], v[206:207], s[56:57], v[230:231] op_sel_hi:[1,0,1]
	global_load_dwordx4 v[200:203], v[232:233], off offset:-2048
	s_waitcnt vmcnt(10)
	v_readlane_b32 s50, v11, 10
	v_readlane_b32 s52, v54, 10
	v_readlane_b32 s54, v55, 10
	v_readlane_b32 s56, v56, 10
	v_pk_fma_f32 v[216:217], v[208:209], s[50:51], v[216:217] op_sel_hi:[1,0,1]
	v_pk_fma_f32 v[218:219], v[210:211], s[50:51], v[218:219] op_sel_hi:[1,0,1]
	v_pk_fma_f32 v[220:221], v[208:209], s[52:53], v[220:221] op_sel_hi:[1,0,1]
	v_pk_fma_f32 v[222:223], v[210:211], s[52:53], v[222:223] op_sel_hi:[1,0,1]
	v_pk_fma_f32 v[224:225], v[208:209], s[54:55], v[224:225] op_sel_hi:[1,0,1]
	v_pk_fma_f32 v[226:227], v[210:211], s[54:55], v[226:227] op_sel_hi:[1,0,1]
	v_pk_fma_f32 v[228:229], v[208:209], s[56:57], v[228:229] op_sel_hi:[1,0,1]
	v_pk_fma_f32 v[230:231], v[210:211], s[56:57], v[230:231] op_sel_hi:[1,0,1]
	global_load_dwordx4 v[204:207], v[232:233], off offset:-1024
	s_waitcnt vmcnt(10)
	v_readlane_b32 s50, v11, 11
	v_readlane_b32 s52, v54, 11
	v_readlane_b32 s54, v55, 11
	v_readlane_b32 s56, v56, 11
	v_pk_fma_f32 v[216:217], v[212:213], s[50:51], v[216:217] op_sel_hi:[1,0,1]
	v_pk_fma_f32 v[218:219], v[214:215], s[50:51], v[218:219] op_sel_hi:[1,0,1]
	v_pk_fma_f32 v[220:221], v[212:213], s[52:53], v[220:221] op_sel_hi:[1,0,1]
	v_pk_fma_f32 v[222:223], v[214:215], s[52:53], v[222:223] op_sel_hi:[1,0,1]
	v_pk_fma_f32 v[224:225], v[212:213], s[54:55], v[224:225] op_sel_hi:[1,0,1]
	v_pk_fma_f32 v[226:227], v[214:215], s[54:55], v[226:227] op_sel_hi:[1,0,1]
	v_pk_fma_f32 v[228:229], v[212:213], s[56:57], v[228:229] op_sel_hi:[1,0,1]
	v_pk_fma_f32 v[230:231], v[214:215], s[56:57], v[230:231] op_sel_hi:[1,0,1]
	global_load_dwordx4 v[208:211], v[232:233], off offset:0
	s_waitcnt vmcnt(10)
	v_readlane_b32 s50, v11, 12
	v_readlane_b32 s52, v54, 12
	v_readlane_b32 s54, v55, 12
	v_readlane_b32 s56, v56, 12
	v_pk_fma_f32 v[216:217], v[168:169], s[50:51], v[216:217] op_sel_hi:[1,0,1]
	v_pk_fma_f32 v[218:219], v[170:171], s[50:51], v[218:219] op_sel_hi:[1,0,1]
	v_pk_fma_f32 v[220:221], v[168:169], s[52:53], v[220:221] op_sel_hi:[1,0,1]
	v_pk_fma_f32 v[222:223], v[170:171], s[52:53], v[222:223] op_sel_hi:[1,0,1]
	v_pk_fma_f32 v[224:225], v[168:169], s[54:55], v[224:225] op_sel_hi:[1,0,1]
	v_pk_fma_f32 v[226:227], v[170:171], s[54:55], v[226:227] op_sel_hi:[1,0,1]
	v_pk_fma_f32 v[228:229], v[168:169], s[56:57], v[228:229] op_sel_hi:[1,0,1]
	v_pk_fma_f32 v[230:231], v[170:171], s[56:57], v[230:231] op_sel_hi:[1,0,1]
	global_load_dwordx4 v[212:215], v[232:233], off offset:1024
	v_lshl_add_u64 v[232:233], v[232:233], 0, s[66:67]
	s_waitcnt vmcnt(10)
	v_readlane_b32 s50, v11, 13
	v_readlane_b32 s52, v54, 13
	v_readlane_b32 s54, v55, 13
	v_readlane_b32 s56, v56, 13
	v_pk_fma_f32 v[216:217], v[172:173], s[50:51], v[216:217] op_sel_hi:[1,0,1]
	v_pk_fma_f32 v[218:219], v[174:175], s[50:51], v[218:219] op_sel_hi:[1,0,1]
	v_pk_fma_f32 v[220:221], v[172:173], s[52:53], v[220:221] op_sel_hi:[1,0,1]
	v_pk_fma_f32 v[222:223], v[174:175], s[52:53], v[222:223] op_sel_hi:[1,0,1]
	v_pk_fma_f32 v[224:225], v[172:173], s[54:55], v[224:225] op_sel_hi:[1,0,1]
	v_pk_fma_f32 v[226:227], v[174:175], s[54:55], v[226:227] op_sel_hi:[1,0,1]
	v_pk_fma_f32 v[228:229], v[172:173], s[56:57], v[228:229] op_sel_hi:[1,0,1]
	v_pk_fma_f32 v[230:231], v[174:175], s[56:57], v[230:231] op_sel_hi:[1,0,1]
	global_load_dwordx4 v[168:171], v[232:233], off offset:-2048
	s_waitcnt vmcnt(10)
	v_readlane_b32 s50, v11, 14
	v_readlane_b32 s52, v54, 14
	v_readlane_b32 s54, v55, 14
	v_readlane_b32 s56, v56, 14
	v_pk_fma_f32 v[216:217], v[176:177], s[50:51], v[216:217] op_sel_hi:[1,0,1]
	v_pk_fma_f32 v[218:219], v[178:179], s[50:51], v[218:219] op_sel_hi:[1,0,1]
	v_pk_fma_f32 v[220:221], v[176:177], s[52:53], v[220:221] op_sel_hi:[1,0,1]
	v_pk_fma_f32 v[222:223], v[178:179], s[52:53], v[222:223] op_sel_hi:[1,0,1]
	v_pk_fma_f32 v[224:225], v[176:177], s[54:55], v[224:225] op_sel_hi:[1,0,1]
	v_pk_fma_f32 v[226:227], v[178:179], s[54:55], v[226:227] op_sel_hi:[1,0,1]
	v_pk_fma_f32 v[228:229], v[176:177], s[56:57], v[228:229] op_sel_hi:[1,0,1]
	v_pk_fma_f32 v[230:231], v[178:179], s[56:57], v[230:231] op_sel_hi:[1,0,1]
	global_load_dwordx4 v[172:175], v[232:233], off offset:-1024
	s_waitcnt vmcnt(10)
	v_readlane_b32 s50, v11, 15
	v_readlane_b32 s52, v54, 15
	v_readlane_b32 s54, v55, 15
	v_readlane_b32 s56, v56, 15
	v_pk_fma_f32 v[216:217], v[180:181], s[50:51], v[216:217] op_sel_hi:[1,0,1]
	v_pk_fma_f32 v[218:219], v[182:183], s[50:51], v[218:219] op_sel_hi:[1,0,1]
	v_pk_fma_f32 v[220:221], v[180:181], s[52:53], v[220:221] op_sel_hi:[1,0,1]
	v_pk_fma_f32 v[222:223], v[182:183], s[52:53], v[222:223] op_sel_hi:[1,0,1]
	v_pk_fma_f32 v[224:225], v[180:181], s[54:55], v[224:225] op_sel_hi:[1,0,1]
	v_pk_fma_f32 v[226:227], v[182:183], s[54:55], v[226:227] op_sel_hi:[1,0,1]
	v_pk_fma_f32 v[228:229], v[180:181], s[56:57], v[228:229] op_sel_hi:[1,0,1]
	v_pk_fma_f32 v[230:231], v[182:183], s[56:57], v[230:231] op_sel_hi:[1,0,1]
	global_load_dwordx4 v[176:179], v[232:233], off offset:0
	s_waitcnt vmcnt(10)
	v_readlane_b32 s50, v11, 16
	v_readlane_b32 s52, v54, 16
	v_readlane_b32 s54, v55, 16
	v_readlane_b32 s56, v56, 16
	v_pk_fma_f32 v[216:217], v[184:185], s[50:51], v[216:217] op_sel_hi:[1,0,1]
	v_pk_fma_f32 v[218:219], v[186:187], s[50:51], v[218:219] op_sel_hi:[1,0,1]
	v_pk_fma_f32 v[220:221], v[184:185], s[52:53], v[220:221] op_sel_hi:[1,0,1]
	v_pk_fma_f32 v[222:223], v[186:187], s[52:53], v[222:223] op_sel_hi:[1,0,1]
	v_pk_fma_f32 v[224:225], v[184:185], s[54:55], v[224:225] op_sel_hi:[1,0,1]
	v_pk_fma_f32 v[226:227], v[186:187], s[54:55], v[226:227] op_sel_hi:[1,0,1]
	v_pk_fma_f32 v[228:229], v[184:185], s[56:57], v[228:229] op_sel_hi:[1,0,1]
	v_pk_fma_f32 v[230:231], v[186:187], s[56:57], v[230:231] op_sel_hi:[1,0,1]
	global_load_dwordx4 v[180:183], v[232:233], off offset:1024
	v_lshl_add_u64 v[232:233], v[232:233], 0, s[66:67]
	s_waitcnt vmcnt(10)
	v_readlane_b32 s50, v11, 17
	v_readlane_b32 s52, v54, 17
	v_readlane_b32 s54, v55, 17
	v_readlane_b32 s56, v56, 17
	v_pk_fma_f32 v[216:217], v[188:189], s[50:51], v[216:217] op_sel_hi:[1,0,1]
	v_pk_fma_f32 v[218:219], v[190:191], s[50:51], v[218:219] op_sel_hi:[1,0,1]
	v_pk_fma_f32 v[220:221], v[188:189], s[52:53], v[220:221] op_sel_hi:[1,0,1]
	v_pk_fma_f32 v[222:223], v[190:191], s[52:53], v[222:223] op_sel_hi:[1,0,1]
	v_pk_fma_f32 v[224:225], v[188:189], s[54:55], v[224:225] op_sel_hi:[1,0,1]
	v_pk_fma_f32 v[226:227], v[190:191], s[54:55], v[226:227] op_sel_hi:[1,0,1]
	v_pk_fma_f32 v[228:229], v[188:189], s[56:57], v[228:229] op_sel_hi:[1,0,1]
	v_pk_fma_f32 v[230:231], v[190:191], s[56:57], v[230:231] op_sel_hi:[1,0,1]
	global_load_dwordx4 v[184:187], v[232:233], off offset:-2048
	s_waitcnt vmcnt(10)
	v_readlane_b32 s50, v11, 18
	v_readlane_b32 s52, v54, 18
	v_readlane_b32 s54, v55, 18
	v_readlane_b32 s56, v56, 18
	v_pk_fma_f32 v[216:217], v[192:193], s[50:51], v[216:217] op_sel_hi:[1,0,1]
	v_pk_fma_f32 v[218:219], v[194:195], s[50:51], v[218:219] op_sel_hi:[1,0,1]
	v_pk_fma_f32 v[220:221], v[192:193], s[52:53], v[220:221] op_sel_hi:[1,0,1]
	v_pk_fma_f32 v[222:223], v[194:195], s[52:53], v[222:223] op_sel_hi:[1,0,1]
	v_pk_fma_f32 v[224:225], v[192:193], s[54:55], v[224:225] op_sel_hi:[1,0,1]
	v_pk_fma_f32 v[226:227], v[194:195], s[54:55], v[226:227] op_sel_hi:[1,0,1]
	v_pk_fma_f32 v[228:229], v[192:193], s[56:57], v[228:229] op_sel_hi:[1,0,1]
	v_pk_fma_f32 v[230:231], v[194:195], s[56:57], v[230:231] op_sel_hi:[1,0,1]
	global_load_dwordx4 v[188:191], v[232:233], off offset:-1024
	s_waitcnt vmcnt(10)
	v_readlane_b32 s50, v11, 19
	v_readlane_b32 s52, v54, 19
	v_readlane_b32 s54, v55, 19
	v_readlane_b32 s56, v56, 19
	v_pk_fma_f32 v[216:217], v[196:197], s[50:51], v[216:217] op_sel_hi:[1,0,1]
	v_pk_fma_f32 v[218:219], v[198:199], s[50:51], v[218:219] op_sel_hi:[1,0,1]
	v_pk_fma_f32 v[220:221], v[196:197], s[52:53], v[220:221] op_sel_hi:[1,0,1]
	v_pk_fma_f32 v[222:223], v[198:199], s[52:53], v[222:223] op_sel_hi:[1,0,1]
	v_pk_fma_f32 v[224:225], v[196:197], s[54:55], v[224:225] op_sel_hi:[1,0,1]
	v_pk_fma_f32 v[226:227], v[198:199], s[54:55], v[226:227] op_sel_hi:[1,0,1]
	v_pk_fma_f32 v[228:229], v[196:197], s[56:57], v[228:229] op_sel_hi:[1,0,1]
	v_pk_fma_f32 v[230:231], v[198:199], s[56:57], v[230:231] op_sel_hi:[1,0,1]
	global_load_dwordx4 v[192:195], v[232:233], off offset:0
	s_waitcnt vmcnt(10)
	v_readlane_b32 s50, v11, 20
	v_readlane_b32 s52, v54, 20
	v_readlane_b32 s54, v55, 20
	v_readlane_b32 s56, v56, 20
	v_pk_fma_f32 v[216:217], v[200:201], s[50:51], v[216:217] op_sel_hi:[1,0,1]
	v_pk_fma_f32 v[218:219], v[202:203], s[50:51], v[218:219] op_sel_hi:[1,0,1]
	v_pk_fma_f32 v[220:221], v[200:201], s[52:53], v[220:221] op_sel_hi:[1,0,1]
	v_pk_fma_f32 v[222:223], v[202:203], s[52:53], v[222:223] op_sel_hi:[1,0,1]
	v_pk_fma_f32 v[224:225], v[200:201], s[54:55], v[224:225] op_sel_hi:[1,0,1]
	v_pk_fma_f32 v[226:227], v[202:203], s[54:55], v[226:227] op_sel_hi:[1,0,1]
	v_pk_fma_f32 v[228:229], v[200:201], s[56:57], v[228:229] op_sel_hi:[1,0,1]
	v_pk_fma_f32 v[230:231], v[202:203], s[56:57], v[230:231] op_sel_hi:[1,0,1]
	global_load_dwordx4 v[196:199], v[232:233], off offset:1024
	v_lshl_add_u64 v[232:233], v[232:233], 0, s[66:67]
	s_waitcnt vmcnt(10)
	v_readlane_b32 s50, v11, 21
	v_readlane_b32 s52, v54, 21
	v_readlane_b32 s54, v55, 21
	v_readlane_b32 s56, v56, 21
	v_pk_fma_f32 v[216:217], v[204:205], s[50:51], v[216:217] op_sel_hi:[1,0,1]
	v_pk_fma_f32 v[218:219], v[206:207], s[50:51], v[218:219] op_sel_hi:[1,0,1]
	v_pk_fma_f32 v[220:221], v[204:205], s[52:53], v[220:221] op_sel_hi:[1,0,1]
	v_pk_fma_f32 v[222:223], v[206:207], s[52:53], v[222:223] op_sel_hi:[1,0,1]
	v_pk_fma_f32 v[224:225], v[204:205], s[54:55], v[224:225] op_sel_hi:[1,0,1]
	v_pk_fma_f32 v[226:227], v[206:207], s[54:55], v[226:227] op_sel_hi:[1,0,1]
	v_pk_fma_f32 v[228:229], v[204:205], s[56:57], v[228:229] op_sel_hi:[1,0,1]
	v_pk_fma_f32 v[230:231], v[206:207], s[56:57], v[230:231] op_sel_hi:[1,0,1]
	global_load_dwordx4 v[200:203], v[232:233], off offset:-2048
	s_waitcnt vmcnt(10)
	v_readlane_b32 s50, v11, 22
	v_readlane_b32 s52, v54, 22
	v_readlane_b32 s54, v55, 22
	v_readlane_b32 s56, v56, 22
	v_pk_fma_f32 v[216:217], v[208:209], s[50:51], v[216:217] op_sel_hi:[1,0,1]
	v_pk_fma_f32 v[218:219], v[210:211], s[50:51], v[218:219] op_sel_hi:[1,0,1]
	v_pk_fma_f32 v[220:221], v[208:209], s[52:53], v[220:221] op_sel_hi:[1,0,1]
	v_pk_fma_f32 v[222:223], v[210:211], s[52:53], v[222:223] op_sel_hi:[1,0,1]
	v_pk_fma_f32 v[224:225], v[208:209], s[54:55], v[224:225] op_sel_hi:[1,0,1]
	v_pk_fma_f32 v[226:227], v[210:211], s[54:55], v[226:227] op_sel_hi:[1,0,1]
	v_pk_fma_f32 v[228:229], v[208:209], s[56:57], v[228:229] op_sel_hi:[1,0,1]
	v_pk_fma_f32 v[230:231], v[210:211], s[56:57], v[230:231] op_sel_hi:[1,0,1]
	global_load_dwordx4 v[204:207], v[232:233], off offset:-1024
	s_waitcnt vmcnt(10)
	v_readlane_b32 s50, v11, 23
	v_readlane_b32 s52, v54, 23
	v_readlane_b32 s54, v55, 23
	v_readlane_b32 s56, v56, 23
	v_pk_fma_f32 v[216:217], v[212:213], s[50:51], v[216:217] op_sel_hi:[1,0,1]
	v_pk_fma_f32 v[218:219], v[214:215], s[50:51], v[218:219] op_sel_hi:[1,0,1]
	v_pk_fma_f32 v[220:221], v[212:213], s[52:53], v[220:221] op_sel_hi:[1,0,1]
	v_pk_fma_f32 v[222:223], v[214:215], s[52:53], v[222:223] op_sel_hi:[1,0,1]
	v_pk_fma_f32 v[224:225], v[212:213], s[54:55], v[224:225] op_sel_hi:[1,0,1]
	v_pk_fma_f32 v[226:227], v[214:215], s[54:55], v[226:227] op_sel_hi:[1,0,1]
	v_pk_fma_f32 v[228:229], v[212:213], s[56:57], v[228:229] op_sel_hi:[1,0,1]
	v_pk_fma_f32 v[230:231], v[214:215], s[56:57], v[230:231] op_sel_hi:[1,0,1]
	global_load_dwordx4 v[208:211], v[232:233], off offset:0
	s_waitcnt vmcnt(10)
	v_readlane_b32 s50, v11, 24
	v_readlane_b32 s52, v54, 24
	v_readlane_b32 s54, v55, 24
	v_readlane_b32 s56, v56, 24
	v_pk_fma_f32 v[216:217], v[168:169], s[50:51], v[216:217] op_sel_hi:[1,0,1]
	v_pk_fma_f32 v[218:219], v[170:171], s[50:51], v[218:219] op_sel_hi:[1,0,1]
	v_pk_fma_f32 v[220:221], v[168:169], s[52:53], v[220:221] op_sel_hi:[1,0,1]
	v_pk_fma_f32 v[222:223], v[170:171], s[52:53], v[222:223] op_sel_hi:[1,0,1]
	v_pk_fma_f32 v[224:225], v[168:169], s[54:55], v[224:225] op_sel_hi:[1,0,1]
	v_pk_fma_f32 v[226:227], v[170:171], s[54:55], v[226:227] op_sel_hi:[1,0,1]
	v_pk_fma_f32 v[228:229], v[168:169], s[56:57], v[228:229] op_sel_hi:[1,0,1]
	v_pk_fma_f32 v[230:231], v[170:171], s[56:57], v[230:231] op_sel_hi:[1,0,1]
	global_load_dwordx4 v[212:215], v[232:233], off offset:1024
	v_lshl_add_u64 v[232:233], v[232:233], 0, s[66:67]
	s_waitcnt vmcnt(10)
	v_readlane_b32 s50, v11, 25
	v_readlane_b32 s52, v54, 25
	v_readlane_b32 s54, v55, 25
	v_readlane_b32 s56, v56, 25
	v_pk_fma_f32 v[216:217], v[172:173], s[50:51], v[216:217] op_sel_hi:[1,0,1]
	v_pk_fma_f32 v[218:219], v[174:175], s[50:51], v[218:219] op_sel_hi:[1,0,1]
	v_pk_fma_f32 v[220:221], v[172:173], s[52:53], v[220:221] op_sel_hi:[1,0,1]
	v_pk_fma_f32 v[222:223], v[174:175], s[52:53], v[222:223] op_sel_hi:[1,0,1]
	v_pk_fma_f32 v[224:225], v[172:173], s[54:55], v[224:225] op_sel_hi:[1,0,1]
	v_pk_fma_f32 v[226:227], v[174:175], s[54:55], v[226:227] op_sel_hi:[1,0,1]
	v_pk_fma_f32 v[228:229], v[172:173], s[56:57], v[228:229] op_sel_hi:[1,0,1]
	v_pk_fma_f32 v[230:231], v[174:175], s[56:57], v[230:231] op_sel_hi:[1,0,1]
	global_load_dwordx4 v[168:171], v[232:233], off offset:-2048
	s_waitcnt vmcnt(10)
	v_readlane_b32 s50, v11, 26
	v_readlane_b32 s52, v54, 26
	v_readlane_b32 s54, v55, 26
	v_readlane_b32 s56, v56, 26
	v_pk_fma_f32 v[216:217], v[176:177], s[50:51], v[216:217] op_sel_hi:[1,0,1]
	v_pk_fma_f32 v[218:219], v[178:179], s[50:51], v[218:219] op_sel_hi:[1,0,1]
	v_pk_fma_f32 v[220:221], v[176:177], s[52:53], v[220:221] op_sel_hi:[1,0,1]
	v_pk_fma_f32 v[222:223], v[178:179], s[52:53], v[222:223] op_sel_hi:[1,0,1]
	v_pk_fma_f32 v[224:225], v[176:177], s[54:55], v[224:225] op_sel_hi:[1,0,1]
	v_pk_fma_f32 v[226:227], v[178:179], s[54:55], v[226:227] op_sel_hi:[1,0,1]
	v_pk_fma_f32 v[228:229], v[176:177], s[56:57], v[228:229] op_sel_hi:[1,0,1]
	v_pk_fma_f32 v[230:231], v[178:179], s[56:57], v[230:231] op_sel_hi:[1,0,1]
	global_load_dwordx4 v[172:175], v[232:233], off offset:-1024
	s_waitcnt vmcnt(10)
	v_readlane_b32 s50, v11, 27
	v_readlane_b32 s52, v54, 27
	v_readlane_b32 s54, v55, 27
	v_readlane_b32 s56, v56, 27
	v_pk_fma_f32 v[216:217], v[180:181], s[50:51], v[216:217] op_sel_hi:[1,0,1]
	v_pk_fma_f32 v[218:219], v[182:183], s[50:51], v[218:219] op_sel_hi:[1,0,1]
	v_pk_fma_f32 v[220:221], v[180:181], s[52:53], v[220:221] op_sel_hi:[1,0,1]
	v_pk_fma_f32 v[222:223], v[182:183], s[52:53], v[222:223] op_sel_hi:[1,0,1]
	v_pk_fma_f32 v[224:225], v[180:181], s[54:55], v[224:225] op_sel_hi:[1,0,1]
	v_pk_fma_f32 v[226:227], v[182:183], s[54:55], v[226:227] op_sel_hi:[1,0,1]
	v_pk_fma_f32 v[228:229], v[180:181], s[56:57], v[228:229] op_sel_hi:[1,0,1]
	v_pk_fma_f32 v[230:231], v[182:183], s[56:57], v[230:231] op_sel_hi:[1,0,1]
	global_load_dwordx4 v[176:179], v[232:233], off offset:0
	s_waitcnt vmcnt(10)
	v_readlane_b32 s50, v11, 28
	v_readlane_b32 s52, v54, 28
	v_readlane_b32 s54, v55, 28
	v_readlane_b32 s56, v56, 28
	v_pk_fma_f32 v[216:217], v[184:185], s[50:51], v[216:217] op_sel_hi:[1,0,1]
	v_pk_fma_f32 v[218:219], v[186:187], s[50:51], v[218:219] op_sel_hi:[1,0,1]
	v_pk_fma_f32 v[220:221], v[184:185], s[52:53], v[220:221] op_sel_hi:[1,0,1]
	v_pk_fma_f32 v[222:223], v[186:187], s[52:53], v[222:223] op_sel_hi:[1,0,1]
	v_pk_fma_f32 v[224:225], v[184:185], s[54:55], v[224:225] op_sel_hi:[1,0,1]
	v_pk_fma_f32 v[226:227], v[186:187], s[54:55], v[226:227] op_sel_hi:[1,0,1]
	v_pk_fma_f32 v[228:229], v[184:185], s[56:57], v[228:229] op_sel_hi:[1,0,1]
	v_pk_fma_f32 v[230:231], v[186:187], s[56:57], v[230:231] op_sel_hi:[1,0,1]
	global_load_dwordx4 v[180:183], v[232:233], off offset:1024
	v_lshl_add_u64 v[232:233], v[232:233], 0, s[66:67]
	s_waitcnt vmcnt(10)
	v_readlane_b32 s50, v11, 29
	v_readlane_b32 s52, v54, 29
	v_readlane_b32 s54, v55, 29
	v_readlane_b32 s56, v56, 29
	v_pk_fma_f32 v[216:217], v[188:189], s[50:51], v[216:217] op_sel_hi:[1,0,1]
	v_pk_fma_f32 v[218:219], v[190:191], s[50:51], v[218:219] op_sel_hi:[1,0,1]
	v_pk_fma_f32 v[220:221], v[188:189], s[52:53], v[220:221] op_sel_hi:[1,0,1]
	v_pk_fma_f32 v[222:223], v[190:191], s[52:53], v[222:223] op_sel_hi:[1,0,1]
	v_pk_fma_f32 v[224:225], v[188:189], s[54:55], v[224:225] op_sel_hi:[1,0,1]
	v_pk_fma_f32 v[226:227], v[190:191], s[54:55], v[226:227] op_sel_hi:[1,0,1]
	v_pk_fma_f32 v[228:229], v[188:189], s[56:57], v[228:229] op_sel_hi:[1,0,1]
	v_pk_fma_f32 v[230:231], v[190:191], s[56:57], v[230:231] op_sel_hi:[1,0,1]
	global_load_dwordx4 v[184:187], v[232:233], off offset:-2048
	s_waitcnt vmcnt(10)
	v_readlane_b32 s50, v11, 30
	v_readlane_b32 s52, v54, 30
	v_readlane_b32 s54, v55, 30
	v_readlane_b32 s56, v56, 30
	v_pk_fma_f32 v[216:217], v[192:193], s[50:51], v[216:217] op_sel_hi:[1,0,1]
	v_pk_fma_f32 v[218:219], v[194:195], s[50:51], v[218:219] op_sel_hi:[1,0,1]
	v_pk_fma_f32 v[220:221], v[192:193], s[52:53], v[220:221] op_sel_hi:[1,0,1]
	v_pk_fma_f32 v[222:223], v[194:195], s[52:53], v[222:223] op_sel_hi:[1,0,1]
	v_pk_fma_f32 v[224:225], v[192:193], s[54:55], v[224:225] op_sel_hi:[1,0,1]
	v_pk_fma_f32 v[226:227], v[194:195], s[54:55], v[226:227] op_sel_hi:[1,0,1]
	v_pk_fma_f32 v[228:229], v[192:193], s[56:57], v[228:229] op_sel_hi:[1,0,1]
	v_pk_fma_f32 v[230:231], v[194:195], s[56:57], v[230:231] op_sel_hi:[1,0,1]
	global_load_dwordx4 v[188:191], v[232:233], off offset:-1024
	s_waitcnt vmcnt(10)
	v_readlane_b32 s50, v11, 31
	v_readlane_b32 s52, v54, 31
	v_readlane_b32 s54, v55, 31
	v_readlane_b32 s56, v56, 31
	v_pk_fma_f32 v[216:217], v[196:197], s[50:51], v[216:217] op_sel_hi:[1,0,1]
	v_pk_fma_f32 v[218:219], v[198:199], s[50:51], v[218:219] op_sel_hi:[1,0,1]
	v_pk_fma_f32 v[220:221], v[196:197], s[52:53], v[220:221] op_sel_hi:[1,0,1]
	v_pk_fma_f32 v[222:223], v[198:199], s[52:53], v[222:223] op_sel_hi:[1,0,1]
	v_pk_fma_f32 v[224:225], v[196:197], s[54:55], v[224:225] op_sel_hi:[1,0,1]
	v_pk_fma_f32 v[226:227], v[198:199], s[54:55], v[226:227] op_sel_hi:[1,0,1]
	v_pk_fma_f32 v[228:229], v[196:197], s[56:57], v[228:229] op_sel_hi:[1,0,1]
	v_pk_fma_f32 v[230:231], v[198:199], s[56:57], v[230:231] op_sel_hi:[1,0,1]
	global_load_dwordx4 v[192:195], v[232:233], off offset:0
	s_waitcnt vmcnt(10)
	v_readlane_b32 s50, v11, 32
	v_readlane_b32 s52, v54, 32
	v_readlane_b32 s54, v55, 32
	v_readlane_b32 s56, v56, 32
	v_pk_fma_f32 v[216:217], v[200:201], s[50:51], v[216:217] op_sel_hi:[1,0,1]
	v_pk_fma_f32 v[218:219], v[202:203], s[50:51], v[218:219] op_sel_hi:[1,0,1]
	v_pk_fma_f32 v[220:221], v[200:201], s[52:53], v[220:221] op_sel_hi:[1,0,1]
	v_pk_fma_f32 v[222:223], v[202:203], s[52:53], v[222:223] op_sel_hi:[1,0,1]
	v_pk_fma_f32 v[224:225], v[200:201], s[54:55], v[224:225] op_sel_hi:[1,0,1]
	v_pk_fma_f32 v[226:227], v[202:203], s[54:55], v[226:227] op_sel_hi:[1,0,1]
	v_pk_fma_f32 v[228:229], v[200:201], s[56:57], v[228:229] op_sel_hi:[1,0,1]
	v_pk_fma_f32 v[230:231], v[202:203], s[56:57], v[230:231] op_sel_hi:[1,0,1]
	global_load_dwordx4 v[196:199], v[232:233], off offset:1024
	v_lshl_add_u64 v[232:233], v[232:233], 0, s[66:67]
	s_waitcnt vmcnt(10)
	v_readlane_b32 s50, v11, 33
	v_readlane_b32 s52, v54, 33
	v_readlane_b32 s54, v55, 33
	v_readlane_b32 s56, v56, 33
	v_pk_fma_f32 v[216:217], v[204:205], s[50:51], v[216:217] op_sel_hi:[1,0,1]
	v_pk_fma_f32 v[218:219], v[206:207], s[50:51], v[218:219] op_sel_hi:[1,0,1]
	v_pk_fma_f32 v[220:221], v[204:205], s[52:53], v[220:221] op_sel_hi:[1,0,1]
	v_pk_fma_f32 v[222:223], v[206:207], s[52:53], v[222:223] op_sel_hi:[1,0,1]
	v_pk_fma_f32 v[224:225], v[204:205], s[54:55], v[224:225] op_sel_hi:[1,0,1]
	v_pk_fma_f32 v[226:227], v[206:207], s[54:55], v[226:227] op_sel_hi:[1,0,1]
	v_pk_fma_f32 v[228:229], v[204:205], s[56:57], v[228:229] op_sel_hi:[1,0,1]
	v_pk_fma_f32 v[230:231], v[206:207], s[56:57], v[230:231] op_sel_hi:[1,0,1]
	global_load_dwordx4 v[200:203], v[232:233], off offset:-2048
	s_waitcnt vmcnt(10)
	v_readlane_b32 s50, v11, 34
	v_readlane_b32 s52, v54, 34
	v_readlane_b32 s54, v55, 34
	v_readlane_b32 s56, v56, 34
	v_pk_fma_f32 v[216:217], v[208:209], s[50:51], v[216:217] op_sel_hi:[1,0,1]
	v_pk_fma_f32 v[218:219], v[210:211], s[50:51], v[218:219] op_sel_hi:[1,0,1]
	v_pk_fma_f32 v[220:221], v[208:209], s[52:53], v[220:221] op_sel_hi:[1,0,1]
	v_pk_fma_f32 v[222:223], v[210:211], s[52:53], v[222:223] op_sel_hi:[1,0,1]
	v_pk_fma_f32 v[224:225], v[208:209], s[54:55], v[224:225] op_sel_hi:[1,0,1]
	v_pk_fma_f32 v[226:227], v[210:211], s[54:55], v[226:227] op_sel_hi:[1,0,1]
	v_pk_fma_f32 v[228:229], v[208:209], s[56:57], v[228:229] op_sel_hi:[1,0,1]
	v_pk_fma_f32 v[230:231], v[210:211], s[56:57], v[230:231] op_sel_hi:[1,0,1]
	global_load_dwordx4 v[204:207], v[232:233], off offset:-1024
	s_waitcnt vmcnt(10)
	v_readlane_b32 s50, v11, 35
	v_readlane_b32 s52, v54, 35
	v_readlane_b32 s54, v55, 35
	v_readlane_b32 s56, v56, 35
	v_pk_fma_f32 v[216:217], v[212:213], s[50:51], v[216:217] op_sel_hi:[1,0,1]
	v_pk_fma_f32 v[218:219], v[214:215], s[50:51], v[218:219] op_sel_hi:[1,0,1]
	v_pk_fma_f32 v[220:221], v[212:213], s[52:53], v[220:221] op_sel_hi:[1,0,1]
	v_pk_fma_f32 v[222:223], v[214:215], s[52:53], v[222:223] op_sel_hi:[1,0,1]
	v_pk_fma_f32 v[224:225], v[212:213], s[54:55], v[224:225] op_sel_hi:[1,0,1]
	v_pk_fma_f32 v[226:227], v[214:215], s[54:55], v[226:227] op_sel_hi:[1,0,1]
	v_pk_fma_f32 v[228:229], v[212:213], s[56:57], v[228:229] op_sel_hi:[1,0,1]
	v_pk_fma_f32 v[230:231], v[214:215], s[56:57], v[230:231] op_sel_hi:[1,0,1]
	global_load_dwordx4 v[208:211], v[232:233], off offset:0
	s_waitcnt vmcnt(10)
	v_readlane_b32 s50, v11, 36
	v_readlane_b32 s52, v54, 36
	v_readlane_b32 s54, v55, 36
	v_readlane_b32 s56, v56, 36
	v_pk_fma_f32 v[216:217], v[168:169], s[50:51], v[216:217] op_sel_hi:[1,0,1]
	v_pk_fma_f32 v[218:219], v[170:171], s[50:51], v[218:219] op_sel_hi:[1,0,1]
	v_pk_fma_f32 v[220:221], v[168:169], s[52:53], v[220:221] op_sel_hi:[1,0,1]
	v_pk_fma_f32 v[222:223], v[170:171], s[52:53], v[222:223] op_sel_hi:[1,0,1]
	v_pk_fma_f32 v[224:225], v[168:169], s[54:55], v[224:225] op_sel_hi:[1,0,1]
	v_pk_fma_f32 v[226:227], v[170:171], s[54:55], v[226:227] op_sel_hi:[1,0,1]
	v_pk_fma_f32 v[228:229], v[168:169], s[56:57], v[228:229] op_sel_hi:[1,0,1]
	v_pk_fma_f32 v[230:231], v[170:171], s[56:57], v[230:231] op_sel_hi:[1,0,1]
	global_load_dwordx4 v[212:215], v[232:233], off offset:1024
	v_lshl_add_u64 v[232:233], v[232:233], 0, s[66:67]
	s_waitcnt vmcnt(10)
	v_readlane_b32 s50, v11, 37
	v_readlane_b32 s52, v54, 37
	v_readlane_b32 s54, v55, 37
	v_readlane_b32 s56, v56, 37
	v_pk_fma_f32 v[216:217], v[172:173], s[50:51], v[216:217] op_sel_hi:[1,0,1]
	v_pk_fma_f32 v[218:219], v[174:175], s[50:51], v[218:219] op_sel_hi:[1,0,1]
	v_pk_fma_f32 v[220:221], v[172:173], s[52:53], v[220:221] op_sel_hi:[1,0,1]
	v_pk_fma_f32 v[222:223], v[174:175], s[52:53], v[222:223] op_sel_hi:[1,0,1]
	v_pk_fma_f32 v[224:225], v[172:173], s[54:55], v[224:225] op_sel_hi:[1,0,1]
	v_pk_fma_f32 v[226:227], v[174:175], s[54:55], v[226:227] op_sel_hi:[1,0,1]
	v_pk_fma_f32 v[228:229], v[172:173], s[56:57], v[228:229] op_sel_hi:[1,0,1]
	v_pk_fma_f32 v[230:231], v[174:175], s[56:57], v[230:231] op_sel_hi:[1,0,1]
	global_load_dwordx4 v[168:171], v[232:233], off offset:-2048
	s_waitcnt vmcnt(10)
	v_readlane_b32 s50, v11, 38
	v_readlane_b32 s52, v54, 38
	v_readlane_b32 s54, v55, 38
	v_readlane_b32 s56, v56, 38
	v_pk_fma_f32 v[216:217], v[176:177], s[50:51], v[216:217] op_sel_hi:[1,0,1]
	v_pk_fma_f32 v[218:219], v[178:179], s[50:51], v[218:219] op_sel_hi:[1,0,1]
	v_pk_fma_f32 v[220:221], v[176:177], s[52:53], v[220:221] op_sel_hi:[1,0,1]
	v_pk_fma_f32 v[222:223], v[178:179], s[52:53], v[222:223] op_sel_hi:[1,0,1]
	v_pk_fma_f32 v[224:225], v[176:177], s[54:55], v[224:225] op_sel_hi:[1,0,1]
	v_pk_fma_f32 v[226:227], v[178:179], s[54:55], v[226:227] op_sel_hi:[1,0,1]
	v_pk_fma_f32 v[228:229], v[176:177], s[56:57], v[228:229] op_sel_hi:[1,0,1]
	v_pk_fma_f32 v[230:231], v[178:179], s[56:57], v[230:231] op_sel_hi:[1,0,1]
	global_load_dwordx4 v[172:175], v[232:233], off offset:-1024
	s_waitcnt vmcnt(10)
	v_readlane_b32 s50, v11, 39
	v_readlane_b32 s52, v54, 39
	v_readlane_b32 s54, v55, 39
	v_readlane_b32 s56, v56, 39
	v_pk_fma_f32 v[216:217], v[180:181], s[50:51], v[216:217] op_sel_hi:[1,0,1]
	v_pk_fma_f32 v[218:219], v[182:183], s[50:51], v[218:219] op_sel_hi:[1,0,1]
	v_pk_fma_f32 v[220:221], v[180:181], s[52:53], v[220:221] op_sel_hi:[1,0,1]
	v_pk_fma_f32 v[222:223], v[182:183], s[52:53], v[222:223] op_sel_hi:[1,0,1]
	v_pk_fma_f32 v[224:225], v[180:181], s[54:55], v[224:225] op_sel_hi:[1,0,1]
	v_pk_fma_f32 v[226:227], v[182:183], s[54:55], v[226:227] op_sel_hi:[1,0,1]
	v_pk_fma_f32 v[228:229], v[180:181], s[56:57], v[228:229] op_sel_hi:[1,0,1]
	v_pk_fma_f32 v[230:231], v[182:183], s[56:57], v[230:231] op_sel_hi:[1,0,1]
	global_load_dwordx4 v[176:179], v[232:233], off offset:0
	s_waitcnt vmcnt(10)
	v_readlane_b32 s50, v11, 40
	v_readlane_b32 s52, v54, 40
	v_readlane_b32 s54, v55, 40
	v_readlane_b32 s56, v56, 40
	v_pk_fma_f32 v[216:217], v[184:185], s[50:51], v[216:217] op_sel_hi:[1,0,1]
	v_pk_fma_f32 v[218:219], v[186:187], s[50:51], v[218:219] op_sel_hi:[1,0,1]
	v_pk_fma_f32 v[220:221], v[184:185], s[52:53], v[220:221] op_sel_hi:[1,0,1]
	v_pk_fma_f32 v[222:223], v[186:187], s[52:53], v[222:223] op_sel_hi:[1,0,1]
	v_pk_fma_f32 v[224:225], v[184:185], s[54:55], v[224:225] op_sel_hi:[1,0,1]
	v_pk_fma_f32 v[226:227], v[186:187], s[54:55], v[226:227] op_sel_hi:[1,0,1]
	v_pk_fma_f32 v[228:229], v[184:185], s[56:57], v[228:229] op_sel_hi:[1,0,1]
	v_pk_fma_f32 v[230:231], v[186:187], s[56:57], v[230:231] op_sel_hi:[1,0,1]
	global_load_dwordx4 v[180:183], v[232:233], off offset:1024
	v_lshl_add_u64 v[232:233], v[232:233], 0, s[66:67]
	s_waitcnt vmcnt(10)
	v_readlane_b32 s50, v11, 41
	v_readlane_b32 s52, v54, 41
	v_readlane_b32 s54, v55, 41
	v_readlane_b32 s56, v56, 41
	v_pk_fma_f32 v[216:217], v[188:189], s[50:51], v[216:217] op_sel_hi:[1,0,1]
	v_pk_fma_f32 v[218:219], v[190:191], s[50:51], v[218:219] op_sel_hi:[1,0,1]
	v_pk_fma_f32 v[220:221], v[188:189], s[52:53], v[220:221] op_sel_hi:[1,0,1]
	v_pk_fma_f32 v[222:223], v[190:191], s[52:53], v[222:223] op_sel_hi:[1,0,1]
	v_pk_fma_f32 v[224:225], v[188:189], s[54:55], v[224:225] op_sel_hi:[1,0,1]
	v_pk_fma_f32 v[226:227], v[190:191], s[54:55], v[226:227] op_sel_hi:[1,0,1]
	v_pk_fma_f32 v[228:229], v[188:189], s[56:57], v[228:229] op_sel_hi:[1,0,1]
	v_pk_fma_f32 v[230:231], v[190:191], s[56:57], v[230:231] op_sel_hi:[1,0,1]
	global_load_dwordx4 v[184:187], v[232:233], off offset:-2048
	s_waitcnt vmcnt(10)
	v_readlane_b32 s50, v11, 42
	v_readlane_b32 s52, v54, 42
	v_readlane_b32 s54, v55, 42
	v_readlane_b32 s56, v56, 42
	v_pk_fma_f32 v[216:217], v[192:193], s[50:51], v[216:217] op_sel_hi:[1,0,1]
	v_pk_fma_f32 v[218:219], v[194:195], s[50:51], v[218:219] op_sel_hi:[1,0,1]
	v_pk_fma_f32 v[220:221], v[192:193], s[52:53], v[220:221] op_sel_hi:[1,0,1]
	v_pk_fma_f32 v[222:223], v[194:195], s[52:53], v[222:223] op_sel_hi:[1,0,1]
	v_pk_fma_f32 v[224:225], v[192:193], s[54:55], v[224:225] op_sel_hi:[1,0,1]
	v_pk_fma_f32 v[226:227], v[194:195], s[54:55], v[226:227] op_sel_hi:[1,0,1]
	v_pk_fma_f32 v[228:229], v[192:193], s[56:57], v[228:229] op_sel_hi:[1,0,1]
	v_pk_fma_f32 v[230:231], v[194:195], s[56:57], v[230:231] op_sel_hi:[1,0,1]
	global_load_dwordx4 v[188:191], v[232:233], off offset:-1024
	s_waitcnt vmcnt(10)
	v_readlane_b32 s50, v11, 43
	v_readlane_b32 s52, v54, 43
	v_readlane_b32 s54, v55, 43
	v_readlane_b32 s56, v56, 43
	v_pk_fma_f32 v[216:217], v[196:197], s[50:51], v[216:217] op_sel_hi:[1,0,1]
	v_pk_fma_f32 v[218:219], v[198:199], s[50:51], v[218:219] op_sel_hi:[1,0,1]
	v_pk_fma_f32 v[220:221], v[196:197], s[52:53], v[220:221] op_sel_hi:[1,0,1]
	v_pk_fma_f32 v[222:223], v[198:199], s[52:53], v[222:223] op_sel_hi:[1,0,1]
	v_pk_fma_f32 v[224:225], v[196:197], s[54:55], v[224:225] op_sel_hi:[1,0,1]
	v_pk_fma_f32 v[226:227], v[198:199], s[54:55], v[226:227] op_sel_hi:[1,0,1]
	v_pk_fma_f32 v[228:229], v[196:197], s[56:57], v[228:229] op_sel_hi:[1,0,1]
	v_pk_fma_f32 v[230:231], v[198:199], s[56:57], v[230:231] op_sel_hi:[1,0,1]
	global_load_dwordx4 v[192:195], v[232:233], off offset:0
	s_waitcnt vmcnt(10)
	v_readlane_b32 s50, v11, 44
	v_readlane_b32 s52, v54, 44
	v_readlane_b32 s54, v55, 44
	v_readlane_b32 s56, v56, 44
	v_pk_fma_f32 v[216:217], v[200:201], s[50:51], v[216:217] op_sel_hi:[1,0,1]
	v_pk_fma_f32 v[218:219], v[202:203], s[50:51], v[218:219] op_sel_hi:[1,0,1]
	v_pk_fma_f32 v[220:221], v[200:201], s[52:53], v[220:221] op_sel_hi:[1,0,1]
	v_pk_fma_f32 v[222:223], v[202:203], s[52:53], v[222:223] op_sel_hi:[1,0,1]
	v_pk_fma_f32 v[224:225], v[200:201], s[54:55], v[224:225] op_sel_hi:[1,0,1]
	v_pk_fma_f32 v[226:227], v[202:203], s[54:55], v[226:227] op_sel_hi:[1,0,1]
	v_pk_fma_f32 v[228:229], v[200:201], s[56:57], v[228:229] op_sel_hi:[1,0,1]
	v_pk_fma_f32 v[230:231], v[202:203], s[56:57], v[230:231] op_sel_hi:[1,0,1]
	global_load_dwordx4 v[196:199], v[232:233], off offset:1024
	v_lshl_add_u64 v[232:233], v[232:233], 0, s[66:67]
	s_waitcnt vmcnt(10)
	v_readlane_b32 s50, v11, 45
	v_readlane_b32 s52, v54, 45
	v_readlane_b32 s54, v55, 45
	v_readlane_b32 s56, v56, 45
	v_pk_fma_f32 v[216:217], v[204:205], s[50:51], v[216:217] op_sel_hi:[1,0,1]
	v_pk_fma_f32 v[218:219], v[206:207], s[50:51], v[218:219] op_sel_hi:[1,0,1]
	v_pk_fma_f32 v[220:221], v[204:205], s[52:53], v[220:221] op_sel_hi:[1,0,1]
	v_pk_fma_f32 v[222:223], v[206:207], s[52:53], v[222:223] op_sel_hi:[1,0,1]
	v_pk_fma_f32 v[224:225], v[204:205], s[54:55], v[224:225] op_sel_hi:[1,0,1]
	v_pk_fma_f32 v[226:227], v[206:207], s[54:55], v[226:227] op_sel_hi:[1,0,1]
	v_pk_fma_f32 v[228:229], v[204:205], s[56:57], v[228:229] op_sel_hi:[1,0,1]
	v_pk_fma_f32 v[230:231], v[206:207], s[56:57], v[230:231] op_sel_hi:[1,0,1]
	global_load_dwordx4 v[200:203], v[232:233], off offset:-2048
	s_waitcnt vmcnt(10)
	v_readlane_b32 s50, v11, 46
	v_readlane_b32 s52, v54, 46
	v_readlane_b32 s54, v55, 46
	v_readlane_b32 s56, v56, 46
	v_pk_fma_f32 v[216:217], v[208:209], s[50:51], v[216:217] op_sel_hi:[1,0,1]
	v_pk_fma_f32 v[218:219], v[210:211], s[50:51], v[218:219] op_sel_hi:[1,0,1]
	v_pk_fma_f32 v[220:221], v[208:209], s[52:53], v[220:221] op_sel_hi:[1,0,1]
	v_pk_fma_f32 v[222:223], v[210:211], s[52:53], v[222:223] op_sel_hi:[1,0,1]
	v_pk_fma_f32 v[224:225], v[208:209], s[54:55], v[224:225] op_sel_hi:[1,0,1]
	v_pk_fma_f32 v[226:227], v[210:211], s[54:55], v[226:227] op_sel_hi:[1,0,1]
	v_pk_fma_f32 v[228:229], v[208:209], s[56:57], v[228:229] op_sel_hi:[1,0,1]
	v_pk_fma_f32 v[230:231], v[210:211], s[56:57], v[230:231] op_sel_hi:[1,0,1]
	global_load_dwordx4 v[204:207], v[232:233], off offset:-1024
	s_waitcnt vmcnt(10)
	v_readlane_b32 s50, v11, 47
	v_readlane_b32 s52, v54, 47
	v_readlane_b32 s54, v55, 47
	v_readlane_b32 s56, v56, 47
	v_pk_fma_f32 v[216:217], v[212:213], s[50:51], v[216:217] op_sel_hi:[1,0,1]
	v_pk_fma_f32 v[218:219], v[214:215], s[50:51], v[218:219] op_sel_hi:[1,0,1]
	v_pk_fma_f32 v[220:221], v[212:213], s[52:53], v[220:221] op_sel_hi:[1,0,1]
	v_pk_fma_f32 v[222:223], v[214:215], s[52:53], v[222:223] op_sel_hi:[1,0,1]
	v_pk_fma_f32 v[224:225], v[212:213], s[54:55], v[224:225] op_sel_hi:[1,0,1]
	v_pk_fma_f32 v[226:227], v[214:215], s[54:55], v[226:227] op_sel_hi:[1,0,1]
	v_pk_fma_f32 v[228:229], v[212:213], s[56:57], v[228:229] op_sel_hi:[1,0,1]
	v_pk_fma_f32 v[230:231], v[214:215], s[56:57], v[230:231] op_sel_hi:[1,0,1]
	global_load_dwordx4 v[208:211], v[232:233], off offset:0
	s_waitcnt vmcnt(10)
	v_readlane_b32 s50, v11, 48
	v_readlane_b32 s52, v54, 48
	v_readlane_b32 s54, v55, 48
	v_readlane_b32 s56, v56, 48
	v_pk_fma_f32 v[216:217], v[168:169], s[50:51], v[216:217] op_sel_hi:[1,0,1]
	v_pk_fma_f32 v[218:219], v[170:171], s[50:51], v[218:219] op_sel_hi:[1,0,1]
	v_pk_fma_f32 v[220:221], v[168:169], s[52:53], v[220:221] op_sel_hi:[1,0,1]
	v_pk_fma_f32 v[222:223], v[170:171], s[52:53], v[222:223] op_sel_hi:[1,0,1]
	v_pk_fma_f32 v[224:225], v[168:169], s[54:55], v[224:225] op_sel_hi:[1,0,1]
	v_pk_fma_f32 v[226:227], v[170:171], s[54:55], v[226:227] op_sel_hi:[1,0,1]
	v_pk_fma_f32 v[228:229], v[168:169], s[56:57], v[228:229] op_sel_hi:[1,0,1]
	v_pk_fma_f32 v[230:231], v[170:171], s[56:57], v[230:231] op_sel_hi:[1,0,1]
	global_load_dwordx4 v[212:215], v[232:233], off offset:1024
	v_lshl_add_u64 v[232:233], v[232:233], 0, s[66:67]
	s_waitcnt vmcnt(10)
	v_readlane_b32 s50, v11, 49
	v_readlane_b32 s52, v54, 49
	v_readlane_b32 s54, v55, 49
	v_readlane_b32 s56, v56, 49
	v_pk_fma_f32 v[216:217], v[172:173], s[50:51], v[216:217] op_sel_hi:[1,0,1]
	v_pk_fma_f32 v[218:219], v[174:175], s[50:51], v[218:219] op_sel_hi:[1,0,1]
	v_pk_fma_f32 v[220:221], v[172:173], s[52:53], v[220:221] op_sel_hi:[1,0,1]
	v_pk_fma_f32 v[222:223], v[174:175], s[52:53], v[222:223] op_sel_hi:[1,0,1]
	v_pk_fma_f32 v[224:225], v[172:173], s[54:55], v[224:225] op_sel_hi:[1,0,1]
	v_pk_fma_f32 v[226:227], v[174:175], s[54:55], v[226:227] op_sel_hi:[1,0,1]
	v_pk_fma_f32 v[228:229], v[172:173], s[56:57], v[228:229] op_sel_hi:[1,0,1]
	v_pk_fma_f32 v[230:231], v[174:175], s[56:57], v[230:231] op_sel_hi:[1,0,1]
	global_load_dwordx4 v[168:171], v[232:233], off offset:-2048
	s_waitcnt vmcnt(10)
	v_readlane_b32 s50, v11, 50
	v_readlane_b32 s52, v54, 50
	v_readlane_b32 s54, v55, 50
	v_readlane_b32 s56, v56, 50
	v_pk_fma_f32 v[216:217], v[176:177], s[50:51], v[216:217] op_sel_hi:[1,0,1]
	v_pk_fma_f32 v[218:219], v[178:179], s[50:51], v[218:219] op_sel_hi:[1,0,1]
	v_pk_fma_f32 v[220:221], v[176:177], s[52:53], v[220:221] op_sel_hi:[1,0,1]
	v_pk_fma_f32 v[222:223], v[178:179], s[52:53], v[222:223] op_sel_hi:[1,0,1]
	v_pk_fma_f32 v[224:225], v[176:177], s[54:55], v[224:225] op_sel_hi:[1,0,1]
	v_pk_fma_f32 v[226:227], v[178:179], s[54:55], v[226:227] op_sel_hi:[1,0,1]
	v_pk_fma_f32 v[228:229], v[176:177], s[56:57], v[228:229] op_sel_hi:[1,0,1]
	v_pk_fma_f32 v[230:231], v[178:179], s[56:57], v[230:231] op_sel_hi:[1,0,1]
	global_load_dwordx4 v[172:175], v[232:233], off offset:-1024
	s_waitcnt vmcnt(10)
	v_readlane_b32 s50, v11, 51
	v_readlane_b32 s52, v54, 51
	v_readlane_b32 s54, v55, 51
	v_readlane_b32 s56, v56, 51
	v_pk_fma_f32 v[216:217], v[180:181], s[50:51], v[216:217] op_sel_hi:[1,0,1]
	v_pk_fma_f32 v[218:219], v[182:183], s[50:51], v[218:219] op_sel_hi:[1,0,1]
	v_pk_fma_f32 v[220:221], v[180:181], s[52:53], v[220:221] op_sel_hi:[1,0,1]
	v_pk_fma_f32 v[222:223], v[182:183], s[52:53], v[222:223] op_sel_hi:[1,0,1]
	v_pk_fma_f32 v[224:225], v[180:181], s[54:55], v[224:225] op_sel_hi:[1,0,1]
	v_pk_fma_f32 v[226:227], v[182:183], s[54:55], v[226:227] op_sel_hi:[1,0,1]
	v_pk_fma_f32 v[228:229], v[180:181], s[56:57], v[228:229] op_sel_hi:[1,0,1]
	v_pk_fma_f32 v[230:231], v[182:183], s[56:57], v[230:231] op_sel_hi:[1,0,1]
	global_load_dwordx4 v[176:179], v[232:233], off offset:0
	s_waitcnt vmcnt(10)
	v_readlane_b32 s50, v11, 52
	v_readlane_b32 s52, v54, 52
	v_readlane_b32 s54, v55, 52
	v_readlane_b32 s56, v56, 52
	v_pk_fma_f32 v[216:217], v[184:185], s[50:51], v[216:217] op_sel_hi:[1,0,1]
	v_pk_fma_f32 v[218:219], v[186:187], s[50:51], v[218:219] op_sel_hi:[1,0,1]
	v_pk_fma_f32 v[220:221], v[184:185], s[52:53], v[220:221] op_sel_hi:[1,0,1]
	v_pk_fma_f32 v[222:223], v[186:187], s[52:53], v[222:223] op_sel_hi:[1,0,1]
	v_pk_fma_f32 v[224:225], v[184:185], s[54:55], v[224:225] op_sel_hi:[1,0,1]
	v_pk_fma_f32 v[226:227], v[186:187], s[54:55], v[226:227] op_sel_hi:[1,0,1]
	v_pk_fma_f32 v[228:229], v[184:185], s[56:57], v[228:229] op_sel_hi:[1,0,1]
	v_pk_fma_f32 v[230:231], v[186:187], s[56:57], v[230:231] op_sel_hi:[1,0,1]
	global_load_dwordx4 v[180:183], v[232:233], off offset:1024
	s_waitcnt vmcnt(10)
	v_readlane_b32 s50, v11, 53
	v_readlane_b32 s52, v54, 53
	v_readlane_b32 s54, v55, 53
	v_readlane_b32 s56, v56, 53
	v_pk_fma_f32 v[216:217], v[188:189], s[50:51], v[216:217] op_sel_hi:[1,0,1]
	v_pk_fma_f32 v[218:219], v[190:191], s[50:51], v[218:219] op_sel_hi:[1,0,1]
	v_pk_fma_f32 v[220:221], v[188:189], s[52:53], v[220:221] op_sel_hi:[1,0,1]
	v_pk_fma_f32 v[222:223], v[190:191], s[52:53], v[222:223] op_sel_hi:[1,0,1]
	v_pk_fma_f32 v[224:225], v[188:189], s[54:55], v[224:225] op_sel_hi:[1,0,1]
	v_pk_fma_f32 v[226:227], v[190:191], s[54:55], v[226:227] op_sel_hi:[1,0,1]
	v_pk_fma_f32 v[228:229], v[188:189], s[56:57], v[228:229] op_sel_hi:[1,0,1]
	v_pk_fma_f32 v[230:231], v[190:191], s[56:57], v[230:231] op_sel_hi:[1,0,1]
	s_waitcnt vmcnt(9)
	v_readlane_b32 s50, v11, 54
	v_readlane_b32 s52, v54, 54
	v_readlane_b32 s54, v55, 54
	v_readlane_b32 s56, v56, 54
	v_pk_fma_f32 v[216:217], v[192:193], s[50:51], v[216:217] op_sel_hi:[1,0,1]
	v_pk_fma_f32 v[218:219], v[194:195], s[50:51], v[218:219] op_sel_hi:[1,0,1]
	v_pk_fma_f32 v[220:221], v[192:193], s[52:53], v[220:221] op_sel_hi:[1,0,1]
	v_pk_fma_f32 v[222:223], v[194:195], s[52:53], v[222:223] op_sel_hi:[1,0,1]
	v_pk_fma_f32 v[224:225], v[192:193], s[54:55], v[224:225] op_sel_hi:[1,0,1]
	v_pk_fma_f32 v[226:227], v[194:195], s[54:55], v[226:227] op_sel_hi:[1,0,1]
	v_pk_fma_f32 v[228:229], v[192:193], s[56:57], v[228:229] op_sel_hi:[1,0,1]
	v_pk_fma_f32 v[230:231], v[194:195], s[56:57], v[230:231] op_sel_hi:[1,0,1]
	s_waitcnt vmcnt(8)
	v_readlane_b32 s50, v11, 55
	v_readlane_b32 s52, v54, 55
	v_readlane_b32 s54, v55, 55
	v_readlane_b32 s56, v56, 55
	v_pk_fma_f32 v[216:217], v[196:197], s[50:51], v[216:217] op_sel_hi:[1,0,1]
	v_pk_fma_f32 v[218:219], v[198:199], s[50:51], v[218:219] op_sel_hi:[1,0,1]
	v_pk_fma_f32 v[220:221], v[196:197], s[52:53], v[220:221] op_sel_hi:[1,0,1]
	v_pk_fma_f32 v[222:223], v[198:199], s[52:53], v[222:223] op_sel_hi:[1,0,1]
	v_pk_fma_f32 v[224:225], v[196:197], s[54:55], v[224:225] op_sel_hi:[1,0,1]
	v_pk_fma_f32 v[226:227], v[198:199], s[54:55], v[226:227] op_sel_hi:[1,0,1]
	v_pk_fma_f32 v[228:229], v[196:197], s[56:57], v[228:229] op_sel_hi:[1,0,1]
	v_pk_fma_f32 v[230:231], v[198:199], s[56:57], v[230:231] op_sel_hi:[1,0,1]
	s_waitcnt vmcnt(7)
	v_readlane_b32 s50, v11, 56
	v_readlane_b32 s52, v54, 56
	v_readlane_b32 s54, v55, 56
	v_readlane_b32 s56, v56, 56
	v_pk_fma_f32 v[216:217], v[200:201], s[50:51], v[216:217] op_sel_hi:[1,0,1]
	v_pk_fma_f32 v[218:219], v[202:203], s[50:51], v[218:219] op_sel_hi:[1,0,1]
	v_pk_fma_f32 v[220:221], v[200:201], s[52:53], v[220:221] op_sel_hi:[1,0,1]
	v_pk_fma_f32 v[222:223], v[202:203], s[52:53], v[222:223] op_sel_hi:[1,0,1]
	v_pk_fma_f32 v[224:225], v[200:201], s[54:55], v[224:225] op_sel_hi:[1,0,1]
	v_pk_fma_f32 v[226:227], v[202:203], s[54:55], v[226:227] op_sel_hi:[1,0,1]
	v_pk_fma_f32 v[228:229], v[200:201], s[56:57], v[228:229] op_sel_hi:[1,0,1]
	v_pk_fma_f32 v[230:231], v[202:203], s[56:57], v[230:231] op_sel_hi:[1,0,1]
	s_waitcnt vmcnt(6)
	v_readlane_b32 s50, v11, 57
	v_readlane_b32 s52, v54, 57
	v_readlane_b32 s54, v55, 57
	v_readlane_b32 s56, v56, 57
	v_pk_fma_f32 v[216:217], v[204:205], s[50:51], v[216:217] op_sel_hi:[1,0,1]
	v_pk_fma_f32 v[218:219], v[206:207], s[50:51], v[218:219] op_sel_hi:[1,0,1]
	v_pk_fma_f32 v[220:221], v[204:205], s[52:53], v[220:221] op_sel_hi:[1,0,1]
	v_pk_fma_f32 v[222:223], v[206:207], s[52:53], v[222:223] op_sel_hi:[1,0,1]
	v_pk_fma_f32 v[224:225], v[204:205], s[54:55], v[224:225] op_sel_hi:[1,0,1]
	v_pk_fma_f32 v[226:227], v[206:207], s[54:55], v[226:227] op_sel_hi:[1,0,1]
	v_pk_fma_f32 v[228:229], v[204:205], s[56:57], v[228:229] op_sel_hi:[1,0,1]
	v_pk_fma_f32 v[230:231], v[206:207], s[56:57], v[230:231] op_sel_hi:[1,0,1]
	s_waitcnt vmcnt(5)
	v_readlane_b32 s50, v11, 58
	v_readlane_b32 s52, v54, 58
	v_readlane_b32 s54, v55, 58
	v_readlane_b32 s56, v56, 58
	v_pk_fma_f32 v[216:217], v[208:209], s[50:51], v[216:217] op_sel_hi:[1,0,1]
	v_pk_fma_f32 v[218:219], v[210:211], s[50:51], v[218:219] op_sel_hi:[1,0,1]
	v_pk_fma_f32 v[220:221], v[208:209], s[52:53], v[220:221] op_sel_hi:[1,0,1]
	v_pk_fma_f32 v[222:223], v[210:211], s[52:53], v[222:223] op_sel_hi:[1,0,1]
	v_pk_fma_f32 v[224:225], v[208:209], s[54:55], v[224:225] op_sel_hi:[1,0,1]
	v_pk_fma_f32 v[226:227], v[210:211], s[54:55], v[226:227] op_sel_hi:[1,0,1]
	v_pk_fma_f32 v[228:229], v[208:209], s[56:57], v[228:229] op_sel_hi:[1,0,1]
	v_pk_fma_f32 v[230:231], v[210:211], s[56:57], v[230:231] op_sel_hi:[1,0,1]
	s_waitcnt vmcnt(4)
	v_readlane_b32 s50, v11, 59
	v_readlane_b32 s52, v54, 59
	v_readlane_b32 s54, v55, 59
	v_readlane_b32 s56, v56, 59
	v_pk_fma_f32 v[216:217], v[212:213], s[50:51], v[216:217] op_sel_hi:[1,0,1]
	v_pk_fma_f32 v[218:219], v[214:215], s[50:51], v[218:219] op_sel_hi:[1,0,1]
	v_pk_fma_f32 v[220:221], v[212:213], s[52:53], v[220:221] op_sel_hi:[1,0,1]
	v_pk_fma_f32 v[222:223], v[214:215], s[52:53], v[222:223] op_sel_hi:[1,0,1]
	v_pk_fma_f32 v[224:225], v[212:213], s[54:55], v[224:225] op_sel_hi:[1,0,1]
	v_pk_fma_f32 v[226:227], v[214:215], s[54:55], v[226:227] op_sel_hi:[1,0,1]
	v_pk_fma_f32 v[228:229], v[212:213], s[56:57], v[228:229] op_sel_hi:[1,0,1]
	v_pk_fma_f32 v[230:231], v[214:215], s[56:57], v[230:231] op_sel_hi:[1,0,1]
	s_waitcnt vmcnt(3)
	v_readlane_b32 s50, v11, 60
	v_readlane_b32 s52, v54, 60
	v_readlane_b32 s54, v55, 60
	v_readlane_b32 s56, v56, 60
	v_pk_fma_f32 v[216:217], v[168:169], s[50:51], v[216:217] op_sel_hi:[1,0,1]
	v_pk_fma_f32 v[218:219], v[170:171], s[50:51], v[218:219] op_sel_hi:[1,0,1]
	v_pk_fma_f32 v[220:221], v[168:169], s[52:53], v[220:221] op_sel_hi:[1,0,1]
	v_pk_fma_f32 v[222:223], v[170:171], s[52:53], v[222:223] op_sel_hi:[1,0,1]
	v_pk_fma_f32 v[224:225], v[168:169], s[54:55], v[224:225] op_sel_hi:[1,0,1]
	v_pk_fma_f32 v[226:227], v[170:171], s[54:55], v[226:227] op_sel_hi:[1,0,1]
	v_pk_fma_f32 v[228:229], v[168:169], s[56:57], v[228:229] op_sel_hi:[1,0,1]
	v_pk_fma_f32 v[230:231], v[170:171], s[56:57], v[230:231] op_sel_hi:[1,0,1]
	s_waitcnt vmcnt(2)
	v_readlane_b32 s50, v11, 61
	v_readlane_b32 s52, v54, 61
	v_readlane_b32 s54, v55, 61
	v_readlane_b32 s56, v56, 61
	v_pk_fma_f32 v[216:217], v[172:173], s[50:51], v[216:217] op_sel_hi:[1,0,1]
	v_pk_fma_f32 v[218:219], v[174:175], s[50:51], v[218:219] op_sel_hi:[1,0,1]
	v_pk_fma_f32 v[220:221], v[172:173], s[52:53], v[220:221] op_sel_hi:[1,0,1]
	v_pk_fma_f32 v[222:223], v[174:175], s[52:53], v[222:223] op_sel_hi:[1,0,1]
	v_pk_fma_f32 v[224:225], v[172:173], s[54:55], v[224:225] op_sel_hi:[1,0,1]
	v_pk_fma_f32 v[226:227], v[174:175], s[54:55], v[226:227] op_sel_hi:[1,0,1]
	v_pk_fma_f32 v[228:229], v[172:173], s[56:57], v[228:229] op_sel_hi:[1,0,1]
	v_pk_fma_f32 v[230:231], v[174:175], s[56:57], v[230:231] op_sel_hi:[1,0,1]
	s_waitcnt vmcnt(1)
	v_readlane_b32 s50, v11, 62
	v_readlane_b32 s52, v54, 62
	v_readlane_b32 s54, v55, 62
	v_readlane_b32 s56, v56, 62
	v_pk_fma_f32 v[216:217], v[176:177], s[50:51], v[216:217] op_sel_hi:[1,0,1]
	v_pk_fma_f32 v[218:219], v[178:179], s[50:51], v[218:219] op_sel_hi:[1,0,1]
	v_pk_fma_f32 v[220:221], v[176:177], s[52:53], v[220:221] op_sel_hi:[1,0,1]
	v_pk_fma_f32 v[222:223], v[178:179], s[52:53], v[222:223] op_sel_hi:[1,0,1]
	v_pk_fma_f32 v[224:225], v[176:177], s[54:55], v[224:225] op_sel_hi:[1,0,1]
	v_pk_fma_f32 v[226:227], v[178:179], s[54:55], v[226:227] op_sel_hi:[1,0,1]
	v_pk_fma_f32 v[228:229], v[176:177], s[56:57], v[228:229] op_sel_hi:[1,0,1]
	v_pk_fma_f32 v[230:231], v[178:179], s[56:57], v[230:231] op_sel_hi:[1,0,1]
	s_waitcnt vmcnt(0)
	v_readlane_b32 s50, v11, 63
	v_readlane_b32 s52, v54, 63
	v_readlane_b32 s54, v55, 63
	v_readlane_b32 s56, v56, 63
	v_pk_fma_f32 v[216:217], v[180:181], s[50:51], v[216:217] op_sel_hi:[1,0,1]
	v_pk_fma_f32 v[218:219], v[182:183], s[50:51], v[218:219] op_sel_hi:[1,0,1]
	v_pk_fma_f32 v[220:221], v[180:181], s[52:53], v[220:221] op_sel_hi:[1,0,1]
	v_pk_fma_f32 v[222:223], v[182:183], s[52:53], v[222:223] op_sel_hi:[1,0,1]
	v_pk_fma_f32 v[224:225], v[180:181], s[54:55], v[224:225] op_sel_hi:[1,0,1]
	v_pk_fma_f32 v[226:227], v[182:183], s[54:55], v[226:227] op_sel_hi:[1,0,1]
	v_pk_fma_f32 v[228:229], v[180:181], s[56:57], v[228:229] op_sel_hi:[1,0,1]
	v_pk_fma_f32 v[230:231], v[182:183], s[56:57], v[230:231] op_sel_hi:[1,0,1]
	v_mov_b32_e32 v52, v216
	v_mov_b32_e32 v53, v218
	v_mov_b32_e32 v50, v217
	v_mov_b32_e32 v51, v219
	v_mov_b32_e32 v46, v220
	v_mov_b32_e32 v47, v222
	v_mov_b32_e32 v44, v221
	v_mov_b32_e32 v45, v223
	v_mov_b32_e32 v36, v224
	v_mov_b32_e32 v37, v226
	v_mov_b32_e32 v34, v225
	v_mov_b32_e32 v35, v227
	v_mov_b32_e32 v28, v228
	v_mov_b32_e32 v29, v230
	v_mov_b32_e32 v26, v229
	v_mov_b32_e32 v27, v231
	v_lshlrev_b64 v[40:41], 10, v[12:13]
	v_lshl_add_u64 v[40:41], v[16:17], 0, v[40:41]
	global_load_dwordx4 v[54:57], v[40:41], off
	v_add_co_u32_e32 v40, vcc, 0xa00000, v40
	v_readlane_b32 s4, v162, 8
	s_nop 0
	v_addc_co_u32_e32 v41, vcc, 0, v41, vcc
	global_load_dwordx4 v[58:61], v[40:41], off
	s_waitcnt vmcnt(1)
	v_mov_b32_e32 v62, v54
	v_mov_b32_e32 v63, v56
	v_mov_b32_e32 v56, v55
	s_waitcnt vmcnt(0)
	v_mov_b32_e32 v64, v58
	v_mov_b32_e32 v65, v60
	v_mov_b32_e32 v60, v59
	v_pk_add_f32 v[62:63], v[62:63], v[64:65]
	v_pk_add_f32 v[64:65], v[56:57], v[60:61]
	s_nop 0
	v_pk_add_f32 v[54:55], v[62:63], v[64:65]
	s_nop 0
	v_add_f32_e32 v11, v54, v55
	s_nop 1
	v_add_f32_dpp v11, v11, v11 quad_perm:[1,0,3,2] row_mask:0xf bank_mask:0xf bound_ctrl:1
	s_nop 1
	v_add_f32_dpp v11, v11, v11 quad_perm:[2,3,0,1] row_mask:0xf bank_mask:0xf bound_ctrl:1
	s_nop 1
	v_add_f32_dpp v11, v11, v11 row_half_mirror row_mask:0xf bank_mask:0xf bound_ctrl:1
	s_nop 1
	v_add_f32_dpp v11, v11, v11 row_mirror row_mask:0xf bank_mask:0xf bound_ctrl:1
	v_mul_f32_e32 v66, 0x3c800000, v11
	v_mov_b32_e32 v11, v117
	v_lshl_add_u64 v[48:49], v[48:49], 0, v[10:11]
	v_add_co_u32_e32 v48, vcc, s96, v48
	v_pk_add_f32 v[64:65], v[64:65], v[66:67] op_sel_hi:[1,0] neg_lo:[0,1] neg_hi:[0,1]
	s_nop 0
	v_addc_co_u32_e32 v49, vcc, 0, v49, vcc
	global_load_dwordx4 v[54:57], v[48:49], off
	global_load_dwordx4 v[58:61], v[48:49], off offset:1024
	v_pk_add_f32 v[62:63], v[62:63], v[66:67] op_sel_hi:[1,0] neg_lo:[0,1] neg_hi:[0,1]
	v_lshl_add_u64 v[42:43], v[42:43], 0, v[10:11]
	v_lshl_add_u64 v[32:33], v[32:33], 0, v[10:11]
	v_lshl_add_u64 v[24:25], v[24:25], 0, v[10:11]
	s_waitcnt vmcnt(1)
	v_mov_b32_e32 v68, v55
	s_waitcnt vmcnt(0)
	v_mov_b32_e32 v70, v59
	v_mov_b32_e32 v55, v57
	v_mov_b32_e32 v59, v61
	v_mov_b32_e32 v69, v56
	v_mov_b32_e32 v71, v60
	v_pk_mul_f32 v[54:55], v[54:55], v[58:59]
	v_pk_mul_f32 v[68:69], v[68:69], v[70:71]
	v_pk_mul_f32 v[54:55], v[0:1], v[54:55]
	s_nop 0
	v_pk_fma_f32 v[54:55], v[14:15], v[68:69], v[54:55]
	s_nop 0
	v_add_f32_e32 v54, v54, v55
	s_nop 1
	v_add_f32_dpp v54, v54, v54 quad_perm:[1,0,3,2] row_mask:0xf bank_mask:0xf bound_ctrl:1
	s_nop 1
	v_add_f32_dpp v54, v54, v54 quad_perm:[2,3,0,1] row_mask:0xf bank_mask:0xf bound_ctrl:1
	s_nop 1
	v_add_f32_dpp v54, v54, v54 row_half_mirror row_mask:0xf bank_mask:0xf bound_ctrl:1
	s_nop 1
	v_add_f32_dpp v58, v54, v54 row_mirror row_mask:0xf bank_mask:0xf bound_ctrl:1
	v_lshlrev_b64 v[54:55], 11, v[12:13]
	v_lshl_add_u64 v[60:61], v[2:3], 0, v[54:55]
	v_pk_mul_f32 v[54:55], v[64:65], v[64:65]
	v_add_u32_e32 v12, s4, v12
	v_pk_fma_f32 v[54:55], v[62:63], v[62:63], v[54:55]
	s_nop 0
	v_add_f32_e32 v13, v54, v55
	s_nop 1
	v_add_f32_dpp v13, v13, v13 quad_perm:[1,0,3,2] row_mask:0xf bank_mask:0xf bound_ctrl:1
	s_nop 1
	v_add_f32_dpp v13, v13, v13 quad_perm:[2,3,0,1] row_mask:0xf bank_mask:0xf bound_ctrl:1
	s_nop 1
	v_add_f32_dpp v13, v13, v13 row_half_mirror row_mask:0xf bank_mask:0xf bound_ctrl:1
	s_nop 1
	v_add_f32_dpp v13, v13, v13 row_mirror row_mask:0xf bank_mask:0xf bound_ctrl:1
	v_fmamk_f32 v13, v13, 0x3c800000, v132
	v_cmp_gt_f32_e32 vcc, s5, v13
	v_mul_f32_e32 v54, 0x4b800000, v13
	s_nop 0
	v_cndmask_b32_e32 v13, v13, v54, vcc
	v_rsq_f32_e32 v13, v13
	s_nop 0
	v_mul_f32_e32 v54, 0x45800000, v13
	v_cndmask_b32_e32 v66, v13, v54, vcc
	global_load_dwordx4 v[54:57], v[48:49], off offset:2048
	v_pk_mul_f32 v[48:49], v[62:63], v[66:67] op_sel_hi:[1,0]
	v_add_co_u32_e32 v42, vcc, s96, v42
	v_pk_fma_f32 v[48:49], v[8:9], v[48:49], v[4:5]
	s_nop 0
	v_addc_co_u32_e32 v43, vcc, 0, v43, vcc
	s_waitcnt vmcnt(0)
	v_mov_b32_e32 v62, v54
	v_mov_b32_e32 v63, v56
	v_pk_fma_f32 v[48:49], v[62:63], v[58:59], v[48:49] op_sel_hi:[1,0,1]
	v_mov_b32_e32 v56, v55
	v_pk_mul_f32 v[48:49], v[52:53], v[48:49]
	v_pk_mul_f32 v[52:53], v[64:65], v[66:67] op_sel_hi:[1,0]
	v_pk_fma_f32 v[52:53], v[20:21], v[52:53], v[18:19]
	v_cvt_pk_bf16_f32 v13, v49, v49
	v_pk_fma_f32 v[52:53], v[56:57], v[58:59], v[52:53] op_sel_hi:[1,0,1]
	s_nop 0
	v_pk_mul_f32 v[50:51], v[50:51], v[52:53]
	v_cvt_pk_bf16_f32 v48, v48, v48
	v_cvt_pk_bf16_f32 v49, v51, v51
	v_cvt_pk_bf16_f32 v50, v50, v50
	v_and_b32_e32 v49, 0xffff0000, v49
	v_and_b32_e32 v50, 0xffff0000, v50
	v_or_b32_sdwa v49, v49, v13 dst_sel:DWORD dst_unused:UNUSED_PAD src0_sel:DWORD src1_sel:WORD_1
	v_or_b32_sdwa v48, v50, v48 dst_sel:DWORD dst_unused:UNUSED_PAD src0_sel:DWORD src1_sel:WORD_1
	global_store_dwordx2 v[60:61], v[48:49], off offset:1536
	v_lshlrev_b64 v[48:49], 10, v[38:39]
	v_lshl_add_u64 v[48:49], v[16:17], 0, v[48:49]
	global_load_dwordx4 v[50:53], v[48:49], off
	global_load_dwordx4 v[54:57], v[40:41], off offset:1024
	v_lshlrev_b64 v[38:39], 11, v[38:39]
	v_lshl_add_u64 v[38:39], v[2:3], 0, v[38:39]
	s_waitcnt vmcnt(1)
	v_mov_b32_e32 v48, v50
	v_mov_b32_e32 v49, v52
	s_waitcnt vmcnt(0)
	v_mov_b32_e32 v58, v54
	v_mov_b32_e32 v59, v56
	v_mov_b32_e32 v52, v51
	v_mov_b32_e32 v56, v55
	v_pk_add_f32 v[48:49], v[48:49], v[58:59]
	v_pk_add_f32 v[50:51], v[52:53], v[56:57]
	global_load_dwordx4 v[54:57], v[42:43], off
	global_load_dwordx4 v[58:61], v[42:43], off offset:1024
	v_pk_add_f32 v[52:53], v[48:49], v[50:51]
	s_waitcnt vmcnt(1)
	v_mov_b32_e32 v62, v55
	v_add_f32_e32 v13, v52, v53
	s_waitcnt vmcnt(0)
	v_mov_b32_e32 v64, v59
	v_mov_b32_e32 v55, v57
	v_add_f32_dpp v13, v13, v13 quad_perm:[1,0,3,2] row_mask:0xf bank_mask:0xf bound_ctrl:1
	v_mov_b32_e32 v59, v61
	v_mov_b32_e32 v63, v56
	v_add_f32_dpp v13, v13, v13 quad_perm:[2,3,0,1] row_mask:0xf bank_mask:0xf bound_ctrl:1
	v_mov_b32_e32 v65, v60
	v_pk_mul_f32 v[54:55], v[54:55], v[58:59]
	v_add_f32_dpp v13, v13, v13 row_half_mirror row_mask:0xf bank_mask:0xf bound_ctrl:1
	v_pk_mul_f32 v[62:63], v[62:63], v[64:65]
	v_pk_mul_f32 v[54:55], v[0:1], v[54:55]
	v_add_f32_dpp v13, v13, v13 row_mirror row_mask:0xf bank_mask:0xf bound_ctrl:1
	v_pk_fma_f32 v[54:55], v[14:15], v[62:63], v[54:55]
	v_mul_f32_e32 v52, 0x3c800000, v13
	v_add_f32_e32 v13, v54, v55
	v_pk_add_f32 v[56:57], v[48:49], v[52:53] op_sel_hi:[1,0] neg_lo:[0,1] neg_hi:[0,1]
	v_pk_add_f32 v[52:53], v[50:51], v[52:53] op_sel_hi:[1,0] neg_lo:[0,1] neg_hi:[0,1]
	v_add_f32_dpp v13, v13, v13 quad_perm:[1,0,3,2] row_mask:0xf bank_mask:0xf bound_ctrl:1
	v_pk_mul_f32 v[48:49], v[52:53], v[52:53]
	s_nop 0
	v_add_f32_dpp v13, v13, v13 quad_perm:[2,3,0,1] row_mask:0xf bank_mask:0xf bound_ctrl:1
	v_pk_fma_f32 v[48:49], v[56:57], v[56:57], v[48:49]
	s_nop 0
	v_add_f32_dpp v13, v13, v13 row_half_mirror row_mask:0xf bank_mask:0xf bound_ctrl:1
	s_nop 1
	v_add_f32_dpp v54, v13, v13 row_mirror row_mask:0xf bank_mask:0xf bound_ctrl:1
	v_add_f32_e32 v13, v48, v49
	s_nop 1
	v_add_f32_dpp v13, v13, v13 quad_perm:[1,0,3,2] row_mask:0xf bank_mask:0xf bound_ctrl:1
	s_nop 1
	v_add_f32_dpp v13, v13, v13 quad_perm:[2,3,0,1] row_mask:0xf bank_mask:0xf bound_ctrl:1
	s_nop 1
	v_add_f32_dpp v13, v13, v13 row_half_mirror row_mask:0xf bank_mask:0xf bound_ctrl:1
	s_nop 1
	v_add_f32_dpp v13, v13, v13 row_mirror row_mask:0xf bank_mask:0xf bound_ctrl:1
	v_fmamk_f32 v13, v13, 0x3c800000, v132
	v_cmp_gt_f32_e32 vcc, s5, v13
	v_mul_f32_e32 v48, 0x4b800000, v13
	s_nop 0
	v_cndmask_b32_e32 v13, v13, v48, vcc
	v_rsq_f32_e32 v13, v13
	s_nop 0
	v_mul_f32_e32 v48, 0x45800000, v13
	v_cndmask_b32_e32 v58, v13, v48, vcc
	global_load_dwordx4 v[48:51], v[42:43], off offset:2048
	v_pk_mul_f32 v[42:43], v[56:57], v[58:59] op_sel_hi:[1,0]
	v_add_co_u32_e32 v32, vcc, s96, v32
	v_pk_fma_f32 v[42:43], v[8:9], v[42:43], v[4:5]
	s_nop 0
	v_addc_co_u32_e32 v33, vcc, 0, v33, vcc
	s_waitcnt vmcnt(0)
	v_mov_b32_e32 v56, v48
	v_mov_b32_e32 v57, v50
	v_pk_fma_f32 v[42:43], v[56:57], v[54:55], v[42:43] op_sel_hi:[1,0,1]
	v_mov_b32_e32 v50, v49
	v_pk_mul_f32 v[42:43], v[46:47], v[42:43]
	v_pk_mul_f32 v[46:47], v[52:53], v[58:59] op_sel_hi:[1,0]
	v_pk_fma_f32 v[46:47], v[20:21], v[46:47], v[18:19]
	v_cvt_pk_bf16_f32 v13, v43, v43
	v_pk_fma_f32 v[46:47], v[50:51], v[54:55], v[46:47] op_sel_hi:[1,0,1]
	s_nop 0
	v_pk_mul_f32 v[44:45], v[44:45], v[46:47]
	v_cvt_pk_bf16_f32 v42, v42, v42
	v_cvt_pk_bf16_f32 v43, v45, v45
	v_cvt_pk_bf16_f32 v44, v44, v44
	v_and_b32_e32 v43, 0xffff0000, v43
	v_and_b32_e32 v44, 0xffff0000, v44
	v_or_b32_sdwa v43, v43, v13 dst_sel:DWORD dst_unused:UNUSED_PAD src0_sel:DWORD src1_sel:WORD_1
	v_or_b32_sdwa v42, v44, v42 dst_sel:DWORD dst_unused:UNUSED_PAD src0_sel:DWORD src1_sel:WORD_1
	global_store_dwordx2 v[38:39], v[42:43], off offset:1536
	v_lshlrev_b64 v[38:39], 10, v[30:31]
	v_lshl_add_u64 v[38:39], v[16:17], 0, v[38:39]
	global_load_dwordx4 v[42:45], v[38:39], off
	global_load_dwordx4 v[46:49], v[40:41], off offset:2048
	v_lshlrev_b64 v[30:31], 11, v[30:31]
	s_waitcnt vmcnt(1)
	v_mov_b32_e32 v38, v42
	v_mov_b32_e32 v39, v44
	s_waitcnt vmcnt(0)
	v_mov_b32_e32 v50, v46
	v_mov_b32_e32 v51, v48
	v_mov_b32_e32 v44, v43
	v_mov_b32_e32 v48, v47
	v_pk_add_f32 v[38:39], v[38:39], v[50:51]
	v_pk_add_f32 v[42:43], v[44:45], v[48:49]
	global_load_dwordx4 v[46:49], v[32:33], off
	global_load_dwordx4 v[50:53], v[32:33], off offset:1024
	v_pk_add_f32 v[44:45], v[38:39], v[42:43]
	s_waitcnt vmcnt(1)
	v_mov_b32_e32 v54, v47
	v_add_f32_e32 v13, v44, v45
	s_waitcnt vmcnt(0)
	v_mov_b32_e32 v56, v51
	v_mov_b32_e32 v47, v49
	v_add_f32_dpp v13, v13, v13 quad_perm:[1,0,3,2] row_mask:0xf bank_mask:0xf bound_ctrl:1
	v_mov_b32_e32 v51, v53
	v_mov_b32_e32 v55, v48
	v_add_f32_dpp v13, v13, v13 quad_perm:[2,3,0,1] row_mask:0xf bank_mask:0xf bound_ctrl:1
	v_mov_b32_e32 v57, v52
	v_pk_mul_f32 v[46:47], v[46:47], v[50:51]
	v_add_f32_dpp v13, v13, v13 row_half_mirror row_mask:0xf bank_mask:0xf bound_ctrl:1
	v_pk_mul_f32 v[54:55], v[54:55], v[56:57]
	v_pk_mul_f32 v[46:47], v[0:1], v[46:47]
	v_add_f32_dpp v13, v13, v13 row_mirror row_mask:0xf bank_mask:0xf bound_ctrl:1
	v_pk_fma_f32 v[46:47], v[14:15], v[54:55], v[46:47]
	v_mul_f32_e32 v44, 0x3c800000, v13
	v_add_f32_e32 v13, v46, v47
	v_pk_add_f32 v[42:43], v[42:43], v[44:45] op_sel_hi:[1,0] neg_lo:[0,1] neg_hi:[0,1]
	v_lshl_add_u64 v[48:49], v[2:3], 0, v[30:31]
	v_add_f32_dpp v13, v13, v13 quad_perm:[1,0,3,2] row_mask:0xf bank_mask:0xf bound_ctrl:1
	v_pk_add_f32 v[38:39], v[38:39], v[44:45] op_sel_hi:[1,0] neg_lo:[0,1] neg_hi:[0,1]
	v_pk_mul_f32 v[30:31], v[42:43], v[42:43]
	v_add_f32_dpp v13, v13, v13 quad_perm:[2,3,0,1] row_mask:0xf bank_mask:0xf bound_ctrl:1
	v_pk_fma_f32 v[30:31], v[38:39], v[38:39], v[30:31]
	s_nop 0
	v_add_f32_dpp v13, v13, v13 row_half_mirror row_mask:0xf bank_mask:0xf bound_ctrl:1
	s_nop 1
	v_add_f32_dpp v46, v13, v13 row_mirror row_mask:0xf bank_mask:0xf bound_ctrl:1
	v_add_f32_e32 v13, v30, v31
	s_nop 1
	v_add_f32_dpp v13, v13, v13 quad_perm:[1,0,3,2] row_mask:0xf bank_mask:0xf bound_ctrl:1
	s_nop 1
	v_add_f32_dpp v13, v13, v13 quad_perm:[2,3,0,1] row_mask:0xf bank_mask:0xf bound_ctrl:1
	s_nop 1
	v_add_f32_dpp v13, v13, v13 row_half_mirror row_mask:0xf bank_mask:0xf bound_ctrl:1
	s_nop 1
	v_add_f32_dpp v13, v13, v13 row_mirror row_mask:0xf bank_mask:0xf bound_ctrl:1
	v_fmamk_f32 v13, v13, 0x3c800000, v132
	v_cmp_gt_f32_e32 vcc, s5, v13
	v_mul_f32_e32 v30, 0x4b800000, v13
	s_nop 0
	v_cndmask_b32_e32 v13, v13, v30, vcc
	v_rsq_f32_e32 v13, v13
	s_nop 0
	v_mul_f32_e32 v30, 0x45800000, v13
	v_cndmask_b32_e32 v44, v13, v30, vcc
	global_load_dwordx4 v[30:33], v[32:33], off offset:2048
	v_pk_mul_f32 v[38:39], v[38:39], v[44:45] op_sel_hi:[1,0]
	v_add_co_u32_e32 v24, vcc, s96, v24
	v_pk_fma_f32 v[38:39], v[8:9], v[38:39], v[4:5]
	s_nop 0
	v_addc_co_u32_e32 v25, vcc, 0, v25, vcc
	s_waitcnt vmcnt(0)
	v_mov_b32_e32 v50, v30
	v_mov_b32_e32 v51, v32
	v_pk_fma_f32 v[38:39], v[50:51], v[46:47], v[38:39] op_sel_hi:[1,0,1]
	v_mov_b32_e32 v32, v31
	v_pk_mul_f32 v[36:37], v[36:37], v[38:39]
	v_pk_mul_f32 v[38:39], v[42:43], v[44:45] op_sel_hi:[1,0]
	v_pk_fma_f32 v[38:39], v[20:21], v[38:39], v[18:19]
	v_cvt_pk_bf16_f32 v13, v37, v37
	v_pk_fma_f32 v[30:31], v[32:33], v[46:47], v[38:39] op_sel_hi:[1,0,1]
	v_pk_mul_f32 v[30:31], v[34:35], v[30:31]
	v_cvt_pk_bf16_f32 v32, v36, v36
	v_cvt_pk_bf16_f32 v31, v31, v31
	v_cvt_pk_bf16_f32 v30, v30, v30
	v_and_b32_e32 v31, 0xffff0000, v31
	v_and_b32_e32 v30, 0xffff0000, v30
	v_or_b32_sdwa v31, v31, v13 dst_sel:DWORD dst_unused:UNUSED_PAD src0_sel:DWORD src1_sel:WORD_1
	v_or_b32_sdwa v30, v30, v32 dst_sel:DWORD dst_unused:UNUSED_PAD src0_sel:DWORD src1_sel:WORD_1
	global_store_dwordx2 v[48:49], v[30:31], off offset:1536
	v_lshlrev_b64 v[30:31], 10, v[22:23]
	v_lshl_add_u64 v[30:31], v[16:17], 0, v[30:31]
	global_load_dwordx4 v[32:35], v[30:31], off
	global_load_dwordx4 v[36:39], v[40:41], off offset:3072
	v_lshlrev_b64 v[22:23], 11, v[22:23]
	s_waitcnt vmcnt(1)
	v_mov_b32_e32 v30, v32
	v_mov_b32_e32 v31, v34
	s_waitcnt vmcnt(0)
	v_mov_b32_e32 v40, v36
	v_mov_b32_e32 v41, v38
	v_mov_b32_e32 v34, v33
	v_mov_b32_e32 v38, v37
	v_pk_add_f32 v[30:31], v[30:31], v[40:41]
	v_pk_add_f32 v[32:33], v[34:35], v[38:39]
	global_load_dwordx4 v[36:39], v[24:25], off
	global_load_dwordx4 v[40:43], v[24:25], off offset:1024
	v_pk_add_f32 v[34:35], v[30:31], v[32:33]
	s_waitcnt vmcnt(1)
	v_mov_b32_e32 v44, v37
	v_add_f32_e32 v13, v34, v35
	s_waitcnt vmcnt(0)
	v_mov_b32_e32 v46, v41
	v_mov_b32_e32 v37, v39
	v_add_f32_dpp v13, v13, v13 quad_perm:[1,0,3,2] row_mask:0xf bank_mask:0xf bound_ctrl:1
	v_mov_b32_e32 v41, v43
	v_mov_b32_e32 v45, v38
	v_add_f32_dpp v13, v13, v13 quad_perm:[2,3,0,1] row_mask:0xf bank_mask:0xf bound_ctrl:1
	v_mov_b32_e32 v47, v42
	v_pk_mul_f32 v[36:37], v[36:37], v[40:41]
	v_add_f32_dpp v13, v13, v13 row_half_mirror row_mask:0xf bank_mask:0xf bound_ctrl:1
	v_pk_mul_f32 v[44:45], v[44:45], v[46:47]
	v_pk_mul_f32 v[36:37], v[0:1], v[36:37]
	v_add_f32_dpp v13, v13, v13 row_mirror row_mask:0xf bank_mask:0xf bound_ctrl:1
	v_pk_fma_f32 v[36:37], v[14:15], v[44:45], v[36:37]
	v_mul_f32_e32 v34, 0x3c800000, v13
	v_add_f32_e32 v11, v36, v37
	v_pk_add_f32 v[32:33], v[32:33], v[34:35] op_sel_hi:[1,0] neg_lo:[0,1] neg_hi:[0,1]
	v_lshl_add_u64 v[38:39], v[2:3], 0, v[22:23]
	v_add_f32_dpp v11, v11, v11 quad_perm:[1,0,3,2] row_mask:0xf bank_mask:0xf bound_ctrl:1
	v_pk_add_f32 v[30:31], v[30:31], v[34:35] op_sel_hi:[1,0] neg_lo:[0,1] neg_hi:[0,1]
	v_pk_mul_f32 v[22:23], v[32:33], v[32:33]
	v_add_f32_dpp v11, v11, v11 quad_perm:[2,3,0,1] row_mask:0xf bank_mask:0xf bound_ctrl:1
	v_pk_fma_f32 v[22:23], v[30:31], v[30:31], v[22:23]
	s_nop 0
	v_add_f32_dpp v11, v11, v11 row_half_mirror row_mask:0xf bank_mask:0xf bound_ctrl:1
	s_nop 1
	v_add_f32_dpp v36, v11, v11 row_mirror row_mask:0xf bank_mask:0xf bound_ctrl:1
	v_add_f32_e32 v11, v22, v23
	global_load_dwordx4 v[22:25], v[24:25], off offset:2048
	s_waitcnt vmcnt(0)
	v_mov_b32_e32 v40, v22
	v_add_f32_dpp v11, v11, v11 quad_perm:[1,0,3,2] row_mask:0xf bank_mask:0xf bound_ctrl:1
	v_mov_b32_e32 v41, v24
	v_mov_b32_e32 v24, v23
	v_add_f32_dpp v11, v11, v11 quad_perm:[2,3,0,1] row_mask:0xf bank_mask:0xf bound_ctrl:1
	s_nop 1
	v_add_f32_dpp v11, v11, v11 row_half_mirror row_mask:0xf bank_mask:0xf bound_ctrl:1
	s_nop 1
	v_add_f32_dpp v11, v11, v11 row_mirror row_mask:0xf bank_mask:0xf bound_ctrl:1
	v_fmamk_f32 v11, v11, 0x3c800000, v132
	v_cmp_gt_f32_e32 vcc, s5, v11
	v_mul_f32_e32 v13, 0x4b800000, v11
	s_nop 0
	v_cndmask_b32_e32 v11, v11, v13, vcc
	v_rsq_f32_e32 v11, v11
	s_nop 0
	v_mul_f32_e32 v13, 0x45800000, v11
	v_cndmask_b32_e32 v34, v11, v13, vcc
	v_pk_mul_f32 v[30:31], v[30:31], v[34:35] op_sel_hi:[1,0]
	v_cmp_lt_i32_e32 vcc, s6, v12
	v_pk_fma_f32 v[30:31], v[8:9], v[30:31], v[4:5]
	s_or_b64 s[20:21], vcc, s[20:21]
	v_pk_fma_f32 v[30:31], v[40:41], v[36:37], v[30:31] op_sel_hi:[1,0,1]
	s_nop 0
	v_pk_mul_f32 v[28:29], v[28:29], v[30:31]
	v_pk_mul_f32 v[30:31], v[32:33], v[34:35] op_sel_hi:[1,0]
	v_pk_fma_f32 v[30:31], v[20:21], v[30:31], v[18:19]
	v_pk_fma_f32 v[22:23], v[24:25], v[36:37], v[30:31] op_sel_hi:[1,0,1]
	v_cvt_pk_bf16_f32 v13, v28, v28
	v_pk_mul_f32 v[22:23], v[26:27], v[22:23]
	v_cvt_pk_bf16_f32 v11, v29, v29
	v_and_b32_sdwa v24, v23, v129 dst_sel:DWORD dst_unused:UNUSED_PAD src0_sel:WORD_1 src1_sel:DWORD
	v_and_b32_sdwa v25, v22, v129 dst_sel:DWORD dst_unused:UNUSED_PAD src0_sel:WORD_1 src1_sel:DWORD
	v_cvt_pk_bf16_f32 v23, v23, v23
	v_cvt_pk_bf16_f32 v22, v22, v22
	v_and_b32_e32 v23, 0xffff0000, v23
	v_and_b32_e32 v22, 0xffff0000, v22
	v_or_b32_sdwa v23, v23, v11 dst_sel:DWORD dst_unused:UNUSED_PAD src0_sel:DWORD src1_sel:WORD_1
	v_or_b32_sdwa v22, v22, v13 dst_sel:DWORD dst_unused:UNUSED_PAD src0_sel:DWORD src1_sel:WORD_1
	global_store_dwordx2 v[38:39], v[22:23], off offset:1536
	s_andn2_b64 exec, exec, s[20:21]
	s_cbranch_execnz .LBB0_804
